# bf16 pair packing via v_cvt_pk_bf16_f32 instead of the integer RNE trick where intermediates are single-use (449 sites)
# speedup vs baseline: 1.0179x; 1.0146x over previous
.LBB0_740:
	ds_write_b32 v49, v0 offset:16380
	s_waitcnt lgkmcnt(0)
	ds_read_b32 v0, v51
	ds_read_b32 v13, v51 offset:260
	v_lshl_add_u64 v[14:15], s[4:5], 1, v[4:5]
	s_waitcnt lgkmcnt(0)
	v_cvt_pk_bf16_f32 v18, v0, v13
	ds_read_b32 v0, v51 offset:520
	ds_read_b32 v13, v51 offset:780
	s_waitcnt lgkmcnt(1)
	s_waitcnt lgkmcnt(0)
	v_cvt_pk_bf16_f32 v19, v0, v13
	ds_read_b32 v0, v51 offset:1040
	ds_read_b32 v13, v51 offset:1300
	s_waitcnt lgkmcnt(1)
	s_waitcnt lgkmcnt(0)
	v_cvt_pk_bf16_f32 v20, v0, v13
	ds_read_b32 v0, v51 offset:1560
	ds_read_b32 v13, v51 offset:1820
	s_waitcnt lgkmcnt(1)
	s_waitcnt lgkmcnt(0)
	v_add_u32_e32 v16, s8, v50
	v_ashrrev_i32_e32 v17, 31, v16
	v_lshlrev_b64 v[22:23], 12, v[16:17]
	v_cvt_pk_bf16_f32 v21, v0, v13
	v_lshl_add_u64 v[22:23], v[14:15], 0, v[22:23]
	flat_store_dwordx4 v[22:23], v[18:21]
	ds_read_b32 v0, v51 offset:32
	ds_read_b32 v13, v51 offset:292
	v_add_u32_e32 v22, 8, v16
	v_ashrrev_i32_e32 v23, 31, v22
	v_lshlrev_b64 v[22:23], 12, v[22:23]
	s_waitcnt lgkmcnt(0)
	v_cvt_pk_bf16_f32 v18, v0, v13
	ds_read_b32 v0, v51 offset:552
	ds_read_b32 v13, v51 offset:812
	v_lshl_add_u64 v[22:23], v[14:15], 0, v[22:23]
	s_waitcnt lgkmcnt(0)
	v_cvt_pk_bf16_f32 v19, v0, v13
	ds_read_b32 v0, v51 offset:1072
	ds_read_b32 v13, v51 offset:1332
	s_waitcnt lgkmcnt(0)
	v_cvt_pk_bf16_f32 v20, v0, v13
	ds_read_b32 v0, v51 offset:1592
	ds_read_b32 v13, v51 offset:1852
	s_waitcnt lgkmcnt(0)
	v_cvt_pk_bf16_f32 v21, v0, v13
	flat_store_dwordx4 v[22:23], v[18:21]
	ds_read_b32 v0, v51 offset:64
	ds_read_b32 v13, v51 offset:324
	v_add_u32_e32 v22, 16, v16
	v_ashrrev_i32_e32 v23, 31, v22
	v_lshlrev_b64 v[22:23], 12, v[22:23]
	s_waitcnt lgkmcnt(0)
	v_cvt_pk_bf16_f32 v18, v0, v13
	ds_read_b32 v0, v51 offset:584
	ds_read_b32 v13, v51 offset:844
	v_lshl_add_u64 v[22:23], v[14:15], 0, v[22:23]
	s_waitcnt lgkmcnt(0)
	v_cvt_pk_bf16_f32 v19, v0, v13
	ds_read_b32 v0, v51 offset:1104
	ds_read_b32 v13, v51 offset:1364
	s_waitcnt lgkmcnt(0)
	v_cvt_pk_bf16_f32 v20, v0, v13
	ds_read_b32 v0, v51 offset:1624
	ds_read_b32 v13, v51 offset:1884
	s_waitcnt lgkmcnt(0)
	v_cvt_pk_bf16_f32 v21, v0, v13
	flat_store_dwordx4 v[22:23], v[18:21]
	ds_read_b32 v0, v51 offset:96
	ds_read_b32 v13, v51 offset:356
	v_add_u32_e32 v22, 24, v16
	v_ashrrev_i32_e32 v23, 31, v22
	v_lshlrev_b64 v[22:23], 12, v[22:23]
	s_waitcnt lgkmcnt(0)
	v_cvt_pk_bf16_f32 v18, v0, v13
	ds_read_b32 v0, v51 offset:616
	ds_read_b32 v13, v51 offset:876
	v_lshl_add_u64 v[22:23], v[14:15], 0, v[22:23]
	s_waitcnt lgkmcnt(0)
	v_cvt_pk_bf16_f32 v19, v0, v13
	ds_read_b32 v0, v51 offset:1136
	ds_read_b32 v13, v51 offset:1396
	s_waitcnt lgkmcnt(0)
	v_cvt_pk_bf16_f32 v20, v0, v13
	ds_read_b32 v0, v51 offset:1656
	ds_read_b32 v13, v51 offset:1916
	s_waitcnt lgkmcnt(0)
	v_cvt_pk_bf16_f32 v21, v0, v13
	flat_store_dwordx4 v[22:23], v[18:21]
	ds_read_b32 v0, v51 offset:128
	ds_read_b32 v13, v51 offset:388
	v_add_u32_e32 v22, 32, v16
	v_ashrrev_i32_e32 v23, 31, v22
	v_lshlrev_b64 v[22:23], 12, v[22:23]
	s_waitcnt lgkmcnt(0)
	v_cvt_pk_bf16_f32 v18, v0, v13
	ds_read_b32 v0, v51 offset:648
	ds_read_b32 v13, v51 offset:908
	v_lshl_add_u64 v[22:23], v[14:15], 0, v[22:23]
	s_waitcnt lgkmcnt(0)
	v_cvt_pk_bf16_f32 v19, v0, v13
	ds_read_b32 v0, v51 offset:1168
	ds_read_b32 v13, v51 offset:1428
	s_waitcnt lgkmcnt(0)
	v_cvt_pk_bf16_f32 v20, v0, v13
	ds_read_b32 v0, v51 offset:1688
	ds_read_b32 v13, v51 offset:1948
	s_waitcnt lgkmcnt(0)
	v_cvt_pk_bf16_f32 v21, v0, v13
	flat_store_dwordx4 v[22:23], v[18:21]
	ds_read_b32 v0, v51 offset:160
	ds_read_b32 v13, v51 offset:420
	v_add_u32_e32 v22, 40, v16
	v_ashrrev_i32_e32 v23, 31, v22
	v_lshlrev_b64 v[22:23], 12, v[22:23]
	s_waitcnt lgkmcnt(0)
	v_cvt_pk_bf16_f32 v18, v0, v13
	ds_read_b32 v0, v51 offset:680
	ds_read_b32 v13, v51 offset:940
	v_lshl_add_u64 v[22:23], v[14:15], 0, v[22:23]
	s_waitcnt lgkmcnt(0)
	v_cvt_pk_bf16_f32 v19, v0, v13
	ds_read_b32 v0, v51 offset:1200
	ds_read_b32 v13, v51 offset:1460
	s_waitcnt lgkmcnt(0)
	v_cvt_pk_bf16_f32 v20, v0, v13
	ds_read_b32 v0, v51 offset:1720
	ds_read_b32 v13, v51 offset:1980
	s_waitcnt lgkmcnt(0)
	v_cvt_pk_bf16_f32 v21, v0, v13
	flat_store_dwordx4 v[22:23], v[18:21]
	ds_read_b32 v0, v51 offset:192
	ds_read_b32 v13, v51 offset:452
	v_add_u32_e32 v22, 48, v16
	v_ashrrev_i32_e32 v23, 31, v22
	v_lshlrev_b64 v[22:23], 12, v[22:23]
	s_waitcnt lgkmcnt(0)
	v_cvt_pk_bf16_f32 v18, v0, v13
	ds_read_b32 v0, v51 offset:712
	ds_read_b32 v13, v51 offset:972
	v_lshl_add_u64 v[22:23], v[14:15], 0, v[22:23]
	v_add_u32_e32 v16, 56, v16
	s_waitcnt lgkmcnt(0)
	v_cvt_pk_bf16_f32 v19, v0, v13
	ds_read_b32 v0, v51 offset:1232
	ds_read_b32 v13, v51 offset:1492
	s_waitcnt lgkmcnt(0)
	v_cvt_pk_bf16_f32 v20, v0, v13
	ds_read_b32 v0, v51 offset:1752
	ds_read_b32 v13, v51 offset:2012
	s_waitcnt lgkmcnt(0)
	v_cvt_pk_bf16_f32 v21, v0, v13
	flat_store_dwordx4 v[22:23], v[18:21]
	ds_read_b32 v0, v51 offset:224
	ds_read_b32 v13, v51 offset:484
	s_waitcnt lgkmcnt(0)
	v_cvt_pk_bf16_f32 v18, v0, v13
	ds_read_b32 v0, v51 offset:744
	ds_read_b32 v13, v51 offset:1004
	s_waitcnt lgkmcnt(0)
	v_cvt_pk_bf16_f32 v19, v0, v13
	ds_read_b32 v0, v51 offset:1264
	ds_read_b32 v13, v51 offset:1524
	s_waitcnt lgkmcnt(0)
	v_cvt_pk_bf16_f32 v20, v0, v13
	ds_read_b32 v0, v51 offset:1784
	ds_read_b32 v13, v51 offset:2044
	s_waitcnt lgkmcnt(0)
	v_ashrrev_i32_e32 v17, 31, v16
	v_lshlrev_b64 v[16:17], 12, v[16:17]
	v_cvt_pk_bf16_f32 v21, v0, v13
	v_lshl_add_u64 v[14:15], v[14:15], 0, v[16:17]
	flat_store_dwordx4 v[14:15], v[18:21]
	s_waitcnt lgkmcnt(0)

.LBB0_742:
	s_cmpk_gt_i32 s63, 0x18ff
	s_mov_b64 s[4:5], -1
	s_cbranch_scc0 .LBB0_808
	s_cmpk_gt_u32 s63, 0x1cff
	s_cbranch_scc0 .LBB0_805
	s_cmpk_gt_u32 s63, 0x20ff
	s_cbranch_scc0 .LBB0_802
	s_cmpk_gt_u32 s63, 0x36ff
	s_cbranch_scc0 .LBB0_751
	s_cmpk_gt_u32 s63, 0x41ff
	s_cbranch_scc0 .LBB0_748
	s_add_i32 s4, s63, 0xbe00
	s_bfe_u32 s5, s4, 0xd0003
	s_and_b32 s4, s64, 0x1c0
	v_or_b32_e32 v0, s4, v48
	v_lshlrev_b32_e32 v0, 2, v0
	v_lshl_add_u64 v[14:15], s[42:43], 0, v[0:1]
	s_lshl_b32 s90, s5, 17
	v_lshl_add_u64 v[14:15], v[14:15], 0, s[90:91]
	v_add_co_u32_e32 v18, vcc, 0x1000, v14
	global_load_dword v0, v[14:15], off
	global_load_dword v13, v[14:15], off offset:2048
	v_addc_co_u32_e32 v19, vcc, 0, v15, vcc
	v_add_co_u32_e32 v20, vcc, s12, v14
	global_load_dword v16, v[18:19], off
	global_load_dword v17, v[18:19], off offset:2048
	v_addc_co_u32_e32 v21, vcc, 0, v15, vcc
	global_load_dword v18, v[20:21], off
	global_load_dword v19, v[20:21], off offset:2048
	v_add_co_u32_e32 v20, vcc, 0x3000, v14
	s_movk_i32 s6, 0x6000
	s_nop 0
	v_addc_co_u32_e32 v21, vcc, 0, v15, vcc
	global_load_dword v22, v[20:21], off
	global_load_dword v23, v[20:21], off offset:2048
	v_add_co_u32_e32 v20, vcc, s13, v14
	s_lshl_b32 s90, s5, 7
	s_nop 0
	v_addc_co_u32_e32 v21, vcc, 0, v15, vcc
	global_load_dword v24, v[20:21], off
	global_load_dword v25, v[20:21], off offset:2048
	v_add_co_u32_e32 v20, vcc, 0x5000, v14
	s_nop 1
	v_addc_co_u32_e32 v21, vcc, 0, v15, vcc
	global_load_dword v26, v[20:21], off
	global_load_dword v27, v[20:21], off offset:2048
	v_add_co_u32_e32 v20, vcc, s6, v14
	s_mov_b32 s6, 0x8000
	s_nop 0
	v_addc_co_u32_e32 v21, vcc, 0, v15, vcc
	global_load_dword v28, v[20:21], off
	global_load_dword v29, v[20:21], off offset:2048
	v_add_co_u32_e32 v20, vcc, 0x7000, v14
	s_nop 1
	v_addc_co_u32_e32 v21, vcc, 0, v15, vcc
	global_load_dword v30, v[20:21], off
	global_load_dword v31, v[20:21], off offset:2048
	v_add_co_u32_e32 v20, vcc, s6, v14
	s_mov_b32 s6, 0xa000
	s_nop 0
	v_addc_co_u32_e32 v21, vcc, 0, v15, vcc
	global_load_dword v32, v[20:21], off
	global_load_dword v33, v[20:21], off offset:2048
	v_add_co_u32_e32 v20, vcc, 0x9000, v14
	s_nop 1
	v_addc_co_u32_e32 v21, vcc, 0, v15, vcc
	global_load_dword v34, v[20:21], off
	global_load_dword v35, v[20:21], off offset:2048
	v_add_co_u32_e32 v20, vcc, s6, v14
	s_mov_b32 s6, 0xc000
	s_nop 0
	v_addc_co_u32_e32 v21, vcc, 0, v15, vcc
	global_load_dword v36, v[20:21], off
	global_load_dword v37, v[20:21], off offset:2048
	v_add_co_u32_e32 v20, vcc, 0xb000, v14
	s_nop 1
	v_addc_co_u32_e32 v21, vcc, 0, v15, vcc
	global_load_dword v38, v[20:21], off
	global_load_dword v39, v[20:21], off offset:2048
	v_add_co_u32_e32 v20, vcc, s6, v14
	s_mov_b32 s6, 0xe000
	s_nop 0
	v_addc_co_u32_e32 v21, vcc, 0, v15, vcc
	global_load_dword v40, v[20:21], off
	global_load_dword v41, v[20:21], off offset:2048
	v_add_co_u32_e32 v20, vcc, 0xd000, v14
	s_nop 1
	v_addc_co_u32_e32 v21, vcc, 0, v15, vcc
	global_load_dword v42, v[20:21], off
	global_load_dword v43, v[20:21], off offset:2048
	v_add_co_u32_e32 v20, vcc, s6, v14
	s_mov_b32 s6, 0x10000
	s_nop 0
	v_addc_co_u32_e32 v21, vcc, 0, v15, vcc
	global_load_dword v44, v[20:21], off
	global_load_dword v45, v[20:21], off offset:2048
	v_add_co_u32_e32 v20, vcc, 0xf000, v14
	s_nop 1
	v_addc_co_u32_e32 v21, vcc, 0, v15, vcc
	global_load_dword v46, v[20:21], off
	global_load_dword v47, v[20:21], off offset:2048
	v_add_co_u32_e32 v20, vcc, s6, v14
	s_mov_b32 s6, 0x12000
	s_nop 0
	v_addc_co_u32_e32 v21, vcc, 0, v15, vcc
	global_load_dword v59, v[20:21], off
	global_load_dword v60, v[20:21], off offset:2048
	v_add_co_u32_e32 v20, vcc, 0x11000, v14
	s_nop 1
	v_addc_co_u32_e32 v21, vcc, 0, v15, vcc
	global_load_dword v61, v[20:21], off
	global_load_dword v62, v[20:21], off offset:2048
	v_add_co_u32_e32 v20, vcc, s6, v14
	s_mov_b32 s6, 0x14000
	s_nop 0
	v_addc_co_u32_e32 v21, vcc, 0, v15, vcc
	global_load_dword v63, v[20:21], off
	global_load_dword v64, v[20:21], off offset:2048
	v_add_co_u32_e32 v20, vcc, 0x13000, v14
	s_nop 1
	v_addc_co_u32_e32 v21, vcc, 0, v15, vcc
	global_load_dword v65, v[20:21], off
	global_load_dword v66, v[20:21], off offset:2048
	v_add_co_u32_e32 v20, vcc, s6, v14
	s_mov_b32 s6, 0x1a000
	s_nop 0
	v_addc_co_u32_e32 v21, vcc, 0, v15, vcc
	global_load_dword v67, v[20:21], off
	global_load_dword v68, v[20:21], off offset:2048
	v_add_co_u32_e32 v20, vcc, 0x15000, v14
	s_nop 1
	v_addc_co_u32_e32 v21, vcc, 0, v15, vcc
	global_load_dword v69, v[20:21], off
	global_load_dword v70, v[20:21], off offset:2048
	v_add_co_u32_e32 v20, vcc, s14, v14
	s_nop 1
	v_addc_co_u32_e32 v21, vcc, 0, v15, vcc
	global_load_dword v71, v[20:21], off
	global_load_dword v72, v[20:21], off offset:2048
	v_add_co_u32_e32 v20, vcc, 0x17000, v14
	s_nop 1
	v_addc_co_u32_e32 v21, vcc, 0, v15, vcc
	global_load_dword v73, v[20:21], off
	global_load_dword v74, v[20:21], off offset:2048
	v_add_co_u32_e32 v20, vcc, s9, v14
	s_nop 1
	v_addc_co_u32_e32 v21, vcc, 0, v15, vcc
	global_load_dword v75, v[20:21], off
	global_load_dword v76, v[20:21], off offset:2048
	v_add_co_u32_e32 v20, vcc, 0x19000, v14
	s_nop 1
	v_addc_co_u32_e32 v21, vcc, 0, v15, vcc
	global_load_dword v77, v[20:21], off
	global_load_dword v78, v[20:21], off offset:2048
	v_add_co_u32_e32 v20, vcc, s6, v14
	s_mov_b32 s6, 0x1c000
	s_nop 0
	v_addc_co_u32_e32 v21, vcc, 0, v15, vcc
	global_load_dword v79, v[20:21], off
	global_load_dword v80, v[20:21], off offset:2048
	v_add_co_u32_e32 v20, vcc, 0x1b000, v14
	s_nop 1
	v_addc_co_u32_e32 v21, vcc, 0, v15, vcc
	global_load_dword v81, v[20:21], off
	global_load_dword v82, v[20:21], off offset:2048
	v_add_co_u32_e32 v20, vcc, s6, v14
	s_mov_b32 s6, 0x1e000
	s_nop 0
	v_addc_co_u32_e32 v21, vcc, 0, v15, vcc
	global_load_dword v83, v[20:21], off
	global_load_dword v84, v[20:21], off offset:2048
	v_add_co_u32_e32 v20, vcc, 0x1d000, v14
	s_nop 1
	v_addc_co_u32_e32 v21, vcc, 0, v15, vcc
	global_load_dword v85, v[20:21], off
	global_load_dword v86, v[20:21], off offset:2048
	v_add_co_u32_e32 v20, vcc, s6, v14
	s_nop 1
	v_addc_co_u32_e32 v21, vcc, 0, v15, vcc
	v_add_co_u32_e32 v14, vcc, 0x1f000, v14
	global_load_dword v87, v[20:21], off
	s_nop 0
	global_load_dword v20, v[20:21], off offset:2048
	v_addc_co_u32_e32 v15, vcc, 0, v15, vcc
	global_load_dword v21, v[14:15], off
	s_nop 0
	global_load_dword v14, v[14:15], off offset:2048
	s_waitcnt vmcnt(0)
	ds_write2_b32 v49, v0, v13 offset1:65
	ds_write2_b32 v49, v16, v17 offset0:130 offset1:195
	v_add_u32_e32 v0, 0x400, v49
	ds_write2_b32 v0, v18, v19 offset0:4 offset1:69
	ds_write2_b32 v0, v22, v23 offset0:134 offset1:199
	v_add_u32_e32 v0, 0x800, v49
	ds_write2_b32 v0, v24, v25 offset0:8 offset1:73
	ds_write2_b32 v0, v26, v27 offset0:138 offset1:203
	v_add_u32_e32 v0, 0xc00, v49
	ds_write2_b32 v0, v28, v29 offset0:12 offset1:77
	ds_write2_b32 v0, v30, v31 offset0:142 offset1:207
	v_add_u32_e32 v0, 0x1000, v49
	ds_write2_b32 v0, v32, v33 offset0:16 offset1:81
	ds_write2_b32 v0, v34, v35 offset0:146 offset1:211
	v_add_u32_e32 v0, 0x1400, v49
	ds_write2_b32 v0, v36, v37 offset0:20 offset1:85
	ds_write2_b32 v0, v38, v39 offset0:150 offset1:215
	v_add_u32_e32 v0, 0x1800, v49
	ds_write2_b32 v0, v40, v41 offset0:24 offset1:89
	ds_write2_b32 v0, v42, v43 offset0:154 offset1:219
	v_add_u32_e32 v0, 0x1c00, v49
	ds_write2_b32 v0, v44, v45 offset0:28 offset1:93
	ds_write2_b32 v0, v46, v47 offset0:158 offset1:223
	v_add_u32_e32 v0, 0x2000, v49
	ds_write2_b32 v0, v59, v60 offset0:32 offset1:97
	ds_write2_b32 v0, v61, v62 offset0:162 offset1:227
	v_add_u32_e32 v0, 0x2400, v49
	ds_write2_b32 v0, v63, v64 offset0:36 offset1:101
	ds_write2_b32 v0, v65, v66 offset0:166 offset1:231
	v_add_u32_e32 v0, 0x2800, v49
	ds_write2_b32 v0, v67, v68 offset0:40 offset1:105
	ds_write2_b32 v0, v69, v70 offset0:170 offset1:235
	v_add_u32_e32 v0, 0x2c00, v49
	ds_write2_b32 v0, v71, v72 offset0:44 offset1:109
	ds_write2_b32 v0, v73, v74 offset0:174 offset1:239
	v_add_u32_e32 v0, 0x3000, v49
	ds_write2_b32 v0, v75, v76 offset0:48 offset1:113
	ds_write2_b32 v0, v77, v78 offset0:178 offset1:243
	v_add_u32_e32 v0, 0x3400, v49
	ds_write2_b32 v0, v79, v80 offset0:52 offset1:117
	ds_write2_b32 v0, v81, v82 offset0:182 offset1:247
	v_add_u32_e32 v0, 0x3800, v49
	ds_write2_b32 v0, v83, v84 offset0:56 offset1:121
	ds_write2_b32 v0, v85, v86 offset0:186 offset1:251
	v_add_u32_e32 v0, 0x3c00, v49
	ds_write2_b32 v0, v87, v20 offset0:60 offset1:125
	ds_write2_b32 v0, v21, v14 offset0:190 offset1:255
	s_waitcnt lgkmcnt(0)
	ds_read_b32 v0, v51
	ds_read_b32 v13, v51 offset:260
	v_lshl_add_u64 v[14:15], v[2:3], 0, s[90:91]
	s_waitcnt lgkmcnt(0)
	v_cvt_pk_bf16_f32 v16, v0, v13
	ds_read_b32 v0, v51 offset:520
	ds_read_b32 v13, v51 offset:780
	s_waitcnt lgkmcnt(1)
	s_waitcnt lgkmcnt(0)
	v_cvt_pk_bf16_f32 v17, v0, v13
	ds_read_b32 v0, v51 offset:1040
	ds_read_b32 v13, v51 offset:1300
	s_waitcnt lgkmcnt(1)
	s_waitcnt lgkmcnt(0)
	v_cvt_pk_bf16_f32 v18, v0, v13
	ds_read_b32 v0, v51 offset:1560
	ds_read_b32 v13, v51 offset:1820
	s_waitcnt lgkmcnt(1)
	s_waitcnt lgkmcnt(0)
	v_cvt_pk_bf16_f32 v19, v0, v13
	v_or_b32_e32 v0, s4, v50
	v_lshlrev_b32_e32 v0, 10, v0
	v_lshl_add_u64 v[20:21], v[14:15], 0, v[0:1]
	flat_store_dwordx4 v[20:21], v[16:19]
	ds_read_b32 v0, v51 offset:32
	ds_read_b32 v13, v51 offset:292
	s_waitcnt lgkmcnt(0)
	v_cvt_pk_bf16_f32 v16, v0, v13
	ds_read_b32 v0, v51 offset:552
	ds_read_b32 v13, v51 offset:812
	s_waitcnt lgkmcnt(0)
	v_cvt_pk_bf16_f32 v17, v0, v13
	ds_read_b32 v0, v51 offset:1072
	ds_read_b32 v13, v51 offset:1332
	s_waitcnt lgkmcnt(0)
	v_cvt_pk_bf16_f32 v18, v0, v13
	ds_read_b32 v0, v51 offset:1592
	ds_read_b32 v13, v51 offset:1852
	s_waitcnt lgkmcnt(0)
	v_cvt_pk_bf16_f32 v19, v0, v13
	v_or_b32_e32 v0, s4, v52
	v_lshlrev_b32_e32 v0, 10, v0
	v_lshl_add_u64 v[20:21], v[14:15], 0, v[0:1]
	flat_store_dwordx4 v[20:21], v[16:19]
	ds_read_b32 v0, v51 offset:64
	ds_read_b32 v13, v51 offset:324
	s_waitcnt lgkmcnt(0)
	v_cvt_pk_bf16_f32 v16, v0, v13
	ds_read_b32 v0, v51 offset:584
	ds_read_b32 v13, v51 offset:844
	s_waitcnt lgkmcnt(0)
	v_cvt_pk_bf16_f32 v17, v0, v13
	ds_read_b32 v0, v51 offset:1104
	ds_read_b32 v13, v51 offset:1364
	s_waitcnt lgkmcnt(0)
	v_cvt_pk_bf16_f32 v18, v0, v13
	ds_read_b32 v0, v51 offset:1624
	ds_read_b32 v13, v51 offset:1884
	s_waitcnt lgkmcnt(0)
	v_cvt_pk_bf16_f32 v19, v0, v13
	v_or_b32_e32 v0, s4, v53
	v_lshlrev_b32_e32 v0, 10, v0
	v_lshl_add_u64 v[20:21], v[14:15], 0, v[0:1]
	flat_store_dwordx4 v[20:21], v[16:19]
	ds_read_b32 v0, v51 offset:96
	ds_read_b32 v13, v51 offset:356
	s_waitcnt lgkmcnt(0)
	v_cvt_pk_bf16_f32 v16, v0, v13
	ds_read_b32 v0, v51 offset:616
	ds_read_b32 v13, v51 offset:876
	s_waitcnt lgkmcnt(0)
	v_cvt_pk_bf16_f32 v17, v0, v13
	ds_read_b32 v0, v51 offset:1136
	ds_read_b32 v13, v51 offset:1396
	s_waitcnt lgkmcnt(0)
	v_cvt_pk_bf16_f32 v18, v0, v13
	ds_read_b32 v0, v51 offset:1656
	ds_read_b32 v13, v51 offset:1916
	s_waitcnt lgkmcnt(0)
	v_cvt_pk_bf16_f32 v19, v0, v13
	v_or_b32_e32 v0, s4, v54
	v_lshlrev_b32_e32 v0, 10, v0
	v_lshl_add_u64 v[20:21], v[14:15], 0, v[0:1]
	flat_store_dwordx4 v[20:21], v[16:19]
	ds_read_b32 v0, v51 offset:128
	ds_read_b32 v13, v51 offset:388
	s_waitcnt lgkmcnt(0)
	v_cvt_pk_bf16_f32 v16, v0, v13
	ds_read_b32 v0, v51 offset:648
	ds_read_b32 v13, v51 offset:908
	s_waitcnt lgkmcnt(0)
	v_cvt_pk_bf16_f32 v17, v0, v13
	ds_read_b32 v0, v51 offset:1168
	ds_read_b32 v13, v51 offset:1428
	s_waitcnt lgkmcnt(0)
	v_cvt_pk_bf16_f32 v18, v0, v13
	ds_read_b32 v0, v51 offset:1688
	ds_read_b32 v13, v51 offset:1948
	s_waitcnt lgkmcnt(0)
	v_cvt_pk_bf16_f32 v19, v0, v13
	v_or_b32_e32 v0, s4, v55
	v_lshlrev_b32_e32 v0, 10, v0
	v_lshl_add_u64 v[20:21], v[14:15], 0, v[0:1]
	flat_store_dwordx4 v[20:21], v[16:19]
	ds_read_b32 v0, v51 offset:160
	ds_read_b32 v13, v51 offset:420
	s_waitcnt lgkmcnt(0)
	v_cvt_pk_bf16_f32 v16, v0, v13
	ds_read_b32 v0, v51 offset:680
	ds_read_b32 v13, v51 offset:940
	s_waitcnt lgkmcnt(0)
	v_cvt_pk_bf16_f32 v17, v0, v13
	ds_read_b32 v0, v51 offset:1200
	ds_read_b32 v13, v51 offset:1460
	s_waitcnt lgkmcnt(0)
	v_cvt_pk_bf16_f32 v18, v0, v13
	ds_read_b32 v0, v51 offset:1720
	ds_read_b32 v13, v51 offset:1980
	s_waitcnt lgkmcnt(0)
	v_cvt_pk_bf16_f32 v19, v0, v13
	v_or_b32_e32 v0, s4, v56
	v_lshlrev_b32_e32 v0, 10, v0
	v_lshl_add_u64 v[20:21], v[14:15], 0, v[0:1]
	flat_store_dwordx4 v[20:21], v[16:19]
	ds_read_b32 v0, v51 offset:192
	ds_read_b32 v13, v51 offset:452
	s_waitcnt lgkmcnt(0)
	v_cvt_pk_bf16_f32 v16, v0, v13
	ds_read_b32 v0, v51 offset:712
	ds_read_b32 v13, v51 offset:972
	s_waitcnt lgkmcnt(0)
	v_cvt_pk_bf16_f32 v17, v0, v13
	ds_read_b32 v0, v51 offset:1232
	ds_read_b32 v13, v51 offset:1492
	s_waitcnt lgkmcnt(0)
	v_cvt_pk_bf16_f32 v18, v0, v13
	ds_read_b32 v0, v51 offset:1752
	ds_read_b32 v13, v51 offset:2012
	s_waitcnt lgkmcnt(0)
	v_cvt_pk_bf16_f32 v19, v0, v13
	v_or_b32_e32 v0, s4, v57
	v_lshlrev_b32_e32 v0, 10, v0
	v_lshl_add_u64 v[20:21], v[14:15], 0, v[0:1]
	flat_store_dwordx4 v[20:21], v[16:19]
	ds_read_b32 v0, v51 offset:224
	ds_read_b32 v13, v51 offset:484
	s_waitcnt lgkmcnt(0)
	v_cvt_pk_bf16_f32 v16, v0, v13
	ds_read_b32 v0, v51 offset:744
	ds_read_b32 v13, v51 offset:1004
	s_waitcnt lgkmcnt(0)
	v_cvt_pk_bf16_f32 v17, v0, v13
	ds_read_b32 v0, v51 offset:1264
	ds_read_b32 v13, v51 offset:1524
	s_waitcnt lgkmcnt(0)
	v_cvt_pk_bf16_f32 v18, v0, v13
	ds_read_b32 v0, v51 offset:1784
	ds_read_b32 v13, v51 offset:2044
	s_waitcnt lgkmcnt(0)
	v_cvt_pk_bf16_f32 v19, v0, v13
	v_or_b32_e32 v0, s4, v58
	v_lshlrev_b32_e32 v0, 10, v0
	v_lshl_add_u64 v[14:15], v[14:15], 0, v[0:1]
	flat_store_dwordx4 v[14:15], v[16:19]
	s_waitcnt lgkmcnt(0)
	s_mov_b64 s[4:5], 0
.LBB0_748:
	s_andn2_b64 vcc, exec, s[4:5]
	s_cbranch_vccnz .LBB0_750
	s_add_i32 s4, s63, 0xc900
	s_bfe_u32 s5, s4, 0xb0005
	s_and_b32 s4, s64, 0x7c0
	v_or_b32_e32 v0, s4, v48
	v_lshlrev_b32_e32 v0, 2, v0
	v_lshl_add_u64 v[14:15], s[44:45], 0, v[0:1]
	s_lshl_b32 s90, s5, 19
	v_lshl_add_u64 v[14:15], v[14:15], 0, s[90:91]
	v_add_co_u32_e32 v16, vcc, 0x2000, v14
	global_load_dword v0, v[14:15], off
	s_nop 0
	v_addc_co_u32_e32 v17, vcc, 0, v15, vcc
	global_load_dword v13, v[16:17], off
	v_add_co_u32_e32 v16, vcc, 0x4000, v14
	s_mov_b32 s6, 0x10000
	s_nop 0
	v_addc_co_u32_e32 v17, vcc, 0, v15, vcc
	v_add_co_u32_e32 v18, vcc, 0x6000, v14
	global_load_dword v16, v[16:17], off
	s_nop 0
	v_addc_co_u32_e32 v19, vcc, 0, v15, vcc
	global_load_dword v17, v[18:19], off
	v_add_co_u32_e32 v18, vcc, 0x8000, v14
	s_lshl_b32 s90, s5, 7
	s_nop 0
	v_addc_co_u32_e32 v19, vcc, 0, v15, vcc
	v_add_co_u32_e32 v20, vcc, 0xa000, v14
	global_load_dword v18, v[18:19], off
	s_nop 0
	v_addc_co_u32_e32 v21, vcc, 0, v15, vcc
	global_load_dword v19, v[20:21], off
	v_add_co_u32_e32 v20, vcc, 0xc000, v14
	s_nop 1
	v_addc_co_u32_e32 v21, vcc, 0, v15, vcc
	v_add_co_u32_e32 v22, vcc, 0xe000, v14
	global_load_dword v20, v[20:21], off
	s_nop 0
	v_addc_co_u32_e32 v23, vcc, 0, v15, vcc
	global_load_dword v21, v[22:23], off
	v_add_co_u32_e32 v22, vcc, s6, v14
	s_mov_b32 s6, 0x12000
	s_nop 0
	v_addc_co_u32_e32 v23, vcc, 0, v15, vcc
	v_add_co_u32_e32 v24, vcc, s6, v14
	s_mov_b32 s6, 0x14000
	s_nop 0
	v_addc_co_u32_e32 v25, vcc, 0, v15, vcc
	global_load_dword v22, v[22:23], off
	s_nop 0
	global_load_dword v23, v[24:25], off
	v_add_co_u32_e32 v24, vcc, s6, v14
	s_mov_b32 s6, 0x1a000
	s_nop 0
	v_addc_co_u32_e32 v25, vcc, 0, v15, vcc
	v_add_co_u32_e32 v26, vcc, s14, v14
	global_load_dword v24, v[24:25], off
	s_nop 0
	v_addc_co_u32_e32 v27, vcc, 0, v15, vcc
	global_load_dword v25, v[26:27], off
	v_add_co_u32_e32 v26, vcc, s9, v14
	s_nop 1
	v_addc_co_u32_e32 v27, vcc, 0, v15, vcc
	v_add_co_u32_e32 v28, vcc, s6, v14
	s_mov_b32 s6, 0x1c000
	s_nop 0
	v_addc_co_u32_e32 v29, vcc, 0, v15, vcc
	global_load_dword v26, v[26:27], off
	s_nop 0
	global_load_dword v27, v[28:29], off
	v_add_co_u32_e32 v28, vcc, s6, v14
	s_mov_b32 s6, 0x1e000
	s_nop 0
	v_addc_co_u32_e32 v29, vcc, 0, v15, vcc
	v_add_co_u32_e32 v30, vcc, s6, v14
	s_mov_b32 s6, 0x20000
	s_nop 0
	v_addc_co_u32_e32 v31, vcc, 0, v15, vcc
	global_load_dword v28, v[28:29], off
	s_nop 0
	global_load_dword v29, v[30:31], off
	v_add_co_u32_e32 v30, vcc, s6, v14
	s_mov_b32 s6, 0x22000
	s_nop 0
	v_addc_co_u32_e32 v31, vcc, 0, v15, vcc
	v_add_co_u32_e32 v32, vcc, s6, v14
	s_mov_b32 s6, 0x24000
	s_nop 0
	v_addc_co_u32_e32 v33, vcc, 0, v15, vcc
	global_load_dword v30, v[30:31], off
	s_nop 0
	global_load_dword v31, v[32:33], off
	v_add_co_u32_e32 v32, vcc, s6, v14
	s_mov_b32 s6, 0x26000
	s_nop 0
	v_addc_co_u32_e32 v33, vcc, 0, v15, vcc
	v_add_co_u32_e32 v34, vcc, s6, v14
	s_mov_b32 s6, 0x28000
	s_nop 0
	v_addc_co_u32_e32 v35, vcc, 0, v15, vcc
	global_load_dword v32, v[32:33], off
	s_nop 0
	global_load_dword v33, v[34:35], off
	v_add_co_u32_e32 v34, vcc, s6, v14
	s_mov_b32 s6, 0x2a000
	s_nop 0
	v_addc_co_u32_e32 v35, vcc, 0, v15, vcc
	v_add_co_u32_e32 v36, vcc, s6, v14
	s_mov_b32 s6, 0x2c000
	s_nop 0
	v_addc_co_u32_e32 v37, vcc, 0, v15, vcc
	global_load_dword v34, v[34:35], off
	s_nop 0
	global_load_dword v35, v[36:37], off
	v_add_co_u32_e32 v36, vcc, s6, v14
	s_mov_b32 s6, 0x2e000
	s_nop 0
	v_addc_co_u32_e32 v37, vcc, 0, v15, vcc
	v_add_co_u32_e32 v38, vcc, s6, v14
	s_mov_b32 s6, 0x30000
	s_nop 0
	v_addc_co_u32_e32 v39, vcc, 0, v15, vcc
	global_load_dword v36, v[36:37], off
	s_nop 0
	global_load_dword v37, v[38:39], off
	v_add_co_u32_e32 v38, vcc, s6, v14
	s_mov_b32 s6, 0x32000
	s_nop 0
	v_addc_co_u32_e32 v39, vcc, 0, v15, vcc
	v_add_co_u32_e32 v40, vcc, s6, v14
	s_mov_b32 s6, 0x34000
	s_nop 0
	v_addc_co_u32_e32 v41, vcc, 0, v15, vcc
	global_load_dword v38, v[38:39], off
	s_nop 0
	global_load_dword v39, v[40:41], off
	v_add_co_u32_e32 v40, vcc, s6, v14
	s_mov_b32 s6, 0x36000
	s_nop 0
	v_addc_co_u32_e32 v41, vcc, 0, v15, vcc
	v_add_co_u32_e32 v42, vcc, s6, v14
	s_mov_b32 s6, 0x38000
	s_nop 0
	v_addc_co_u32_e32 v43, vcc, 0, v15, vcc
	global_load_dword v40, v[40:41], off
	s_nop 0
	global_load_dword v41, v[42:43], off
	v_add_co_u32_e32 v42, vcc, s6, v14
	s_mov_b32 s6, 0x3a000
	s_nop 0
	v_addc_co_u32_e32 v43, vcc, 0, v15, vcc
	global_load_dword v44, v[42:43], off
	v_add_co_u32_e32 v42, vcc, s6, v14
	s_mov_b32 s6, 0x3c000
	s_nop 0
	v_addc_co_u32_e32 v43, vcc, 0, v15, vcc
	global_load_dword v45, v[42:43], off
	v_add_co_u32_e32 v42, vcc, s6, v14
	s_mov_b32 s6, 0x3e000
	s_nop 0
	v_addc_co_u32_e32 v43, vcc, 0, v15, vcc
	global_load_dword v46, v[42:43], off
	v_add_co_u32_e32 v42, vcc, s6, v14
	s_mov_b32 s6, 0x40000
	s_nop 0
	v_addc_co_u32_e32 v43, vcc, 0, v15, vcc
	global_load_dword v47, v[42:43], off
	v_add_co_u32_e32 v42, vcc, s6, v14
	s_mov_b32 s6, 0x42000
	s_nop 0
	v_addc_co_u32_e32 v43, vcc, 0, v15, vcc
	global_load_dword v59, v[42:43], off
	v_add_co_u32_e32 v42, vcc, s6, v14
	s_mov_b32 s6, 0x44000
	s_nop 0
	v_addc_co_u32_e32 v43, vcc, 0, v15, vcc
	global_load_dword v60, v[42:43], off
	v_add_co_u32_e32 v42, vcc, s6, v14
	s_mov_b32 s6, 0x46000
	s_nop 0
	v_addc_co_u32_e32 v43, vcc, 0, v15, vcc
	global_load_dword v61, v[42:43], off
	v_add_co_u32_e32 v42, vcc, s6, v14
	s_mov_b32 s6, 0x48000
	s_nop 0
	v_addc_co_u32_e32 v43, vcc, 0, v15, vcc
	global_load_dword v62, v[42:43], off
	v_add_co_u32_e32 v42, vcc, s6, v14
	s_mov_b32 s6, 0x4a000
	s_nop 0
	v_addc_co_u32_e32 v43, vcc, 0, v15, vcc
	global_load_dword v63, v[42:43], off
	v_add_co_u32_e32 v42, vcc, s6, v14
	s_mov_b32 s6, 0x4c000
	s_nop 0
	v_addc_co_u32_e32 v43, vcc, 0, v15, vcc
	global_load_dword v64, v[42:43], off
	v_add_co_u32_e32 v42, vcc, s6, v14
	s_mov_b32 s6, 0x4e000
	s_nop 0
	v_addc_co_u32_e32 v43, vcc, 0, v15, vcc
	global_load_dword v65, v[42:43], off
	v_add_co_u32_e32 v42, vcc, s6, v14
	s_mov_b32 s6, 0x50000
	s_nop 0
	v_addc_co_u32_e32 v43, vcc, 0, v15, vcc
	global_load_dword v66, v[42:43], off
	v_add_co_u32_e32 v42, vcc, s6, v14
	s_mov_b32 s6, 0x52000
	s_nop 0
	v_addc_co_u32_e32 v43, vcc, 0, v15, vcc
	global_load_dword v67, v[42:43], off
	v_add_co_u32_e32 v42, vcc, s6, v14
	s_mov_b32 s6, 0x54000
	s_nop 0
	v_addc_co_u32_e32 v43, vcc, 0, v15, vcc
	global_load_dword v68, v[42:43], off
	v_add_co_u32_e32 v42, vcc, s6, v14
	s_mov_b32 s6, 0x56000
	s_nop 0
	v_addc_co_u32_e32 v43, vcc, 0, v15, vcc
	global_load_dword v69, v[42:43], off
	v_add_co_u32_e32 v42, vcc, s6, v14
	s_mov_b32 s6, 0x58000
	s_nop 0
	v_addc_co_u32_e32 v43, vcc, 0, v15, vcc
	global_load_dword v70, v[42:43], off
	v_add_co_u32_e32 v42, vcc, s6, v14
	s_mov_b32 s6, 0x5a000
	s_nop 0
	v_addc_co_u32_e32 v43, vcc, 0, v15, vcc
	global_load_dword v71, v[42:43], off
	v_add_co_u32_e32 v42, vcc, s6, v14
	s_mov_b32 s6, 0x5c000
	s_nop 0
	v_addc_co_u32_e32 v43, vcc, 0, v15, vcc
	global_load_dword v72, v[42:43], off
	v_add_co_u32_e32 v42, vcc, s6, v14
	s_mov_b32 s6, 0x5e000
	s_nop 0
	v_addc_co_u32_e32 v43, vcc, 0, v15, vcc
	global_load_dword v73, v[42:43], off
	v_add_co_u32_e32 v42, vcc, s6, v14
	s_mov_b32 s6, 0x60000
	s_nop 0
	v_addc_co_u32_e32 v43, vcc, 0, v15, vcc
	global_load_dword v74, v[42:43], off
	v_add_co_u32_e32 v42, vcc, s6, v14
	s_mov_b32 s6, 0x64000
	s_nop 0
	v_addc_co_u32_e32 v43, vcc, 0, v15, vcc
	global_load_dword v75, v[42:43], off
	v_add_co_u32_e32 v42, vcc, s21, v14
	s_nop 1
	v_addc_co_u32_e32 v43, vcc, 0, v15, vcc
	global_load_dword v76, v[42:43], off
	v_add_co_u32_e32 v42, vcc, s6, v14
	s_mov_b32 s6, 0x66000
	s_nop 0
	v_addc_co_u32_e32 v43, vcc, 0, v15, vcc
	global_load_dword v77, v[42:43], off
	v_add_co_u32_e32 v42, vcc, s6, v14
	s_mov_b32 s6, 0x68000
	s_nop 0
	v_addc_co_u32_e32 v43, vcc, 0, v15, vcc
	global_load_dword v78, v[42:43], off
	v_add_co_u32_e32 v42, vcc, s6, v14
	s_mov_b32 s6, 0x6a000
	s_nop 0
	v_addc_co_u32_e32 v43, vcc, 0, v15, vcc
	global_load_dword v79, v[42:43], off
	v_add_co_u32_e32 v42, vcc, s6, v14
	s_mov_b32 s6, 0x6c000
	s_nop 0
	v_addc_co_u32_e32 v43, vcc, 0, v15, vcc
	global_load_dword v80, v[42:43], off
	v_add_co_u32_e32 v42, vcc, s6, v14
	s_mov_b32 s6, 0x70000
	s_nop 0
	v_addc_co_u32_e32 v43, vcc, 0, v15, vcc
	global_load_dword v81, v[42:43], off
	v_add_co_u32_e32 v42, vcc, s16, v14
	s_nop 1
	v_addc_co_u32_e32 v43, vcc, 0, v15, vcc
	global_load_dword v82, v[42:43], off
	v_add_co_u32_e32 v42, vcc, s6, v14
	s_mov_b32 s6, 0x72000
	s_nop 0
	v_addc_co_u32_e32 v43, vcc, 0, v15, vcc
	global_load_dword v83, v[42:43], off
	v_add_co_u32_e32 v42, vcc, s6, v14
	s_mov_b32 s6, 0x74000
	s_nop 0
	v_addc_co_u32_e32 v43, vcc, 0, v15, vcc
	global_load_dword v84, v[42:43], off
	v_add_co_u32_e32 v42, vcc, s6, v14
	s_mov_b32 s6, 0x76000
	s_nop 0
	v_addc_co_u32_e32 v43, vcc, 0, v15, vcc
	global_load_dword v85, v[42:43], off
	v_add_co_u32_e32 v42, vcc, s6, v14
	s_mov_b32 s6, 0x78000
	s_nop 0
	v_addc_co_u32_e32 v43, vcc, 0, v15, vcc
	global_load_dword v86, v[42:43], off
	v_add_co_u32_e32 v42, vcc, s6, v14
	s_mov_b32 s6, 0x7c000
	s_nop 0
	v_addc_co_u32_e32 v43, vcc, 0, v15, vcc
	global_load_dword v87, v[42:43], off
	v_add_co_u32_e32 v42, vcc, s89, v14
	s_nop 1
	v_addc_co_u32_e32 v43, vcc, 0, v15, vcc
	global_load_dword v88, v[42:43], off
	v_add_co_u32_e32 v42, vcc, s6, v14
	s_mov_b32 s6, 0x7e000
	s_nop 0
	v_addc_co_u32_e32 v43, vcc, 0, v15, vcc
	v_add_co_u32_e32 v14, vcc, s6, v14
	global_load_dword v42, v[42:43], off
	s_nop 0
	v_addc_co_u32_e32 v15, vcc, 0, v15, vcc
	global_load_dword v14, v[14:15], off
	s_waitcnt vmcnt(0)
	ds_write2_b32 v49, v0, v13 offset1:65
	ds_write2_b32 v49, v16, v17 offset0:130 offset1:195
	v_add_u32_e32 v0, 0x400, v49
	ds_write2_b32 v0, v18, v19 offset0:4 offset1:69
	ds_write2_b32 v0, v20, v21 offset0:134 offset1:199
	v_add_u32_e32 v0, 0x800, v49
	ds_write2_b32 v0, v22, v23 offset0:8 offset1:73
	ds_write2_b32 v0, v24, v25 offset0:138 offset1:203
	v_add_u32_e32 v0, 0xc00, v49
	ds_write2_b32 v0, v26, v27 offset0:12 offset1:77
	ds_write2_b32 v0, v28, v29 offset0:142 offset1:207
	v_add_u32_e32 v0, 0x1000, v49
	ds_write2_b32 v0, v30, v31 offset0:16 offset1:81
	ds_write2_b32 v0, v32, v33 offset0:146 offset1:211
	v_add_u32_e32 v0, 0x1400, v49
	ds_write2_b32 v0, v34, v35 offset0:20 offset1:85
	ds_write2_b32 v0, v36, v37 offset0:150 offset1:215
	v_add_u32_e32 v0, 0x1800, v49
	ds_write2_b32 v0, v38, v39 offset0:24 offset1:89
	ds_write2_b32 v0, v40, v41 offset0:154 offset1:219
	v_add_u32_e32 v0, 0x1c00, v49
	ds_write2_b32 v0, v44, v45 offset0:28 offset1:93
	ds_write2_b32 v0, v46, v47 offset0:158 offset1:223
	v_add_u32_e32 v0, 0x2000, v49
	ds_write2_b32 v0, v59, v60 offset0:32 offset1:97
	ds_write2_b32 v0, v61, v62 offset0:162 offset1:227
	v_add_u32_e32 v0, 0x2400, v49
	ds_write2_b32 v0, v63, v64 offset0:36 offset1:101
	ds_write2_b32 v0, v65, v66 offset0:166 offset1:231
	v_add_u32_e32 v0, 0x2800, v49
	ds_write2_b32 v0, v67, v68 offset0:40 offset1:105
	ds_write2_b32 v0, v69, v70 offset0:170 offset1:235
	v_add_u32_e32 v0, 0x2c00, v49
	ds_write2_b32 v0, v71, v72 offset0:44 offset1:109
	ds_write2_b32 v0, v73, v74 offset0:174 offset1:239
	v_add_u32_e32 v0, 0x3000, v49
	ds_write2_b32 v0, v75, v76 offset0:48 offset1:113
	ds_write2_b32 v0, v77, v78 offset0:178 offset1:243
	v_add_u32_e32 v0, 0x3400, v49
	ds_write2_b32 v0, v79, v80 offset0:52 offset1:117
	ds_write2_b32 v0, v81, v82 offset0:182 offset1:247
	v_add_u32_e32 v0, 0x3800, v49
	ds_write2_b32 v0, v83, v84 offset0:56 offset1:121
	ds_write2_b32 v0, v85, v86 offset0:186 offset1:251
	v_add_u32_e32 v0, 0x3c00, v49
	ds_write2_b32 v0, v87, v88 offset0:60 offset1:125
	ds_write2_b32 v0, v42, v14 offset0:190 offset1:255
	s_waitcnt lgkmcnt(0)
	ds_read_b32 v0, v51
	ds_read_b32 v13, v51 offset:260
	v_lshl_add_u64 v[14:15], v[6:7], 0, s[90:91]
	s_waitcnt lgkmcnt(0)
	v_cvt_pk_bf16_f32 v16, v0, v13
	ds_read_b32 v0, v51 offset:520
	ds_read_b32 v13, v51 offset:780
	s_waitcnt lgkmcnt(1)
	s_waitcnt lgkmcnt(0)
	v_cvt_pk_bf16_f32 v17, v0, v13
	ds_read_b32 v0, v51 offset:1040
	ds_read_b32 v13, v51 offset:1300
	s_waitcnt lgkmcnt(1)
	s_waitcnt lgkmcnt(0)
	v_cvt_pk_bf16_f32 v18, v0, v13
	ds_read_b32 v0, v51 offset:1560
	ds_read_b32 v13, v51 offset:1820
	s_waitcnt lgkmcnt(1)
	s_waitcnt lgkmcnt(0)
	v_cvt_pk_bf16_f32 v19, v0, v13
	v_or_b32_e32 v0, s4, v50
	v_mul_u32_u24_e32 v0, 0x1600, v0
	v_lshlrev_b32_e32 v0, 1, v0
	v_lshl_add_u64 v[20:21], v[14:15], 0, v[0:1]
	flat_store_dwordx4 v[20:21], v[16:19]
	ds_read_b32 v0, v51 offset:32
	ds_read_b32 v13, v51 offset:292
	s_waitcnt lgkmcnt(0)
	v_cvt_pk_bf16_f32 v16, v0, v13
	ds_read_b32 v0, v51 offset:552
	ds_read_b32 v13, v51 offset:812
	s_waitcnt lgkmcnt(0)
	v_cvt_pk_bf16_f32 v17, v0, v13
	ds_read_b32 v0, v51 offset:1072
	ds_read_b32 v13, v51 offset:1332
	s_waitcnt lgkmcnt(0)
	v_cvt_pk_bf16_f32 v18, v0, v13
	ds_read_b32 v0, v51 offset:1592
	ds_read_b32 v13, v51 offset:1852
	s_waitcnt lgkmcnt(0)
	v_cvt_pk_bf16_f32 v19, v0, v13
	v_or_b32_e32 v0, s4, v52
	v_mul_u32_u24_e32 v0, 0x1600, v0
	v_lshlrev_b32_e32 v0, 1, v0
	v_lshl_add_u64 v[20:21], v[14:15], 0, v[0:1]
	flat_store_dwordx4 v[20:21], v[16:19]
	ds_read_b32 v0, v51 offset:64
	ds_read_b32 v13, v51 offset:324
	s_waitcnt lgkmcnt(0)
	v_cvt_pk_bf16_f32 v16, v0, v13
	ds_read_b32 v0, v51 offset:584
	ds_read_b32 v13, v51 offset:844
	s_waitcnt lgkmcnt(0)
	v_cvt_pk_bf16_f32 v17, v0, v13
	ds_read_b32 v0, v51 offset:1104
	ds_read_b32 v13, v51 offset:1364
	s_waitcnt lgkmcnt(0)
	v_cvt_pk_bf16_f32 v18, v0, v13
	ds_read_b32 v0, v51 offset:1624
	ds_read_b32 v13, v51 offset:1884
	s_waitcnt lgkmcnt(0)
	v_cvt_pk_bf16_f32 v19, v0, v13
	v_or_b32_e32 v0, s4, v53
	v_mul_u32_u24_e32 v0, 0x1600, v0
	v_lshlrev_b32_e32 v0, 1, v0
	v_lshl_add_u64 v[20:21], v[14:15], 0, v[0:1]
	flat_store_dwordx4 v[20:21], v[16:19]
	ds_read_b32 v0, v51 offset:96
	ds_read_b32 v13, v51 offset:356
	s_waitcnt lgkmcnt(0)
	v_cvt_pk_bf16_f32 v16, v0, v13
	ds_read_b32 v0, v51 offset:616
	ds_read_b32 v13, v51 offset:876
	s_waitcnt lgkmcnt(0)
	v_cvt_pk_bf16_f32 v17, v0, v13
	ds_read_b32 v0, v51 offset:1136
	ds_read_b32 v13, v51 offset:1396
	s_waitcnt lgkmcnt(0)
	v_cvt_pk_bf16_f32 v18, v0, v13
	ds_read_b32 v0, v51 offset:1656
	ds_read_b32 v13, v51 offset:1916
	s_waitcnt lgkmcnt(0)
	v_cvt_pk_bf16_f32 v19, v0, v13
	v_or_b32_e32 v0, s4, v54
	v_mul_u32_u24_e32 v0, 0x1600, v0
	v_lshlrev_b32_e32 v0, 1, v0
	v_lshl_add_u64 v[20:21], v[14:15], 0, v[0:1]
	flat_store_dwordx4 v[20:21], v[16:19]
	ds_read_b32 v0, v51 offset:128
	ds_read_b32 v13, v51 offset:388
	s_waitcnt lgkmcnt(0)
	v_cvt_pk_bf16_f32 v16, v0, v13
	ds_read_b32 v0, v51 offset:648
	ds_read_b32 v13, v51 offset:908
	s_waitcnt lgkmcnt(0)
	v_cvt_pk_bf16_f32 v17, v0, v13
	ds_read_b32 v0, v51 offset:1168
	ds_read_b32 v13, v51 offset:1428
	s_waitcnt lgkmcnt(0)
	v_cvt_pk_bf16_f32 v18, v0, v13
	ds_read_b32 v0, v51 offset:1688
	ds_read_b32 v13, v51 offset:1948
	s_waitcnt lgkmcnt(0)
	v_cvt_pk_bf16_f32 v19, v0, v13
	v_or_b32_e32 v0, s4, v55
	v_mul_u32_u24_e32 v0, 0x1600, v0
	v_lshlrev_b32_e32 v0, 1, v0
	v_lshl_add_u64 v[20:21], v[14:15], 0, v[0:1]
	flat_store_dwordx4 v[20:21], v[16:19]
	ds_read_b32 v0, v51 offset:160
	ds_read_b32 v13, v51 offset:420
	s_waitcnt lgkmcnt(0)
	v_cvt_pk_bf16_f32 v16, v0, v13
	ds_read_b32 v0, v51 offset:680
	ds_read_b32 v13, v51 offset:940
	s_waitcnt lgkmcnt(0)
	v_cvt_pk_bf16_f32 v17, v0, v13
	ds_read_b32 v0, v51 offset:1200
	ds_read_b32 v13, v51 offset:1460
	s_waitcnt lgkmcnt(0)
	v_cvt_pk_bf16_f32 v18, v0, v13
	ds_read_b32 v0, v51 offset:1720
	ds_read_b32 v13, v51 offset:1980
	s_waitcnt lgkmcnt(0)
	v_cvt_pk_bf16_f32 v19, v0, v13
	v_or_b32_e32 v0, s4, v56
	v_mul_u32_u24_e32 v0, 0x1600, v0
	v_lshlrev_b32_e32 v0, 1, v0
	v_lshl_add_u64 v[20:21], v[14:15], 0, v[0:1]
	flat_store_dwordx4 v[20:21], v[16:19]
	ds_read_b32 v0, v51 offset:192
	ds_read_b32 v13, v51 offset:452
	s_waitcnt lgkmcnt(0)
	v_cvt_pk_bf16_f32 v16, v0, v13
	ds_read_b32 v0, v51 offset:712
	ds_read_b32 v13, v51 offset:972
	s_waitcnt lgkmcnt(0)
	v_cvt_pk_bf16_f32 v17, v0, v13
	ds_read_b32 v0, v51 offset:1232
	ds_read_b32 v13, v51 offset:1492
	s_waitcnt lgkmcnt(0)
	v_cvt_pk_bf16_f32 v18, v0, v13
	ds_read_b32 v0, v51 offset:1752
	ds_read_b32 v13, v51 offset:2012
	s_waitcnt lgkmcnt(0)
	v_cvt_pk_bf16_f32 v19, v0, v13
	v_or_b32_e32 v0, s4, v57
	v_mul_u32_u24_e32 v0, 0x1600, v0
	v_lshlrev_b32_e32 v0, 1, v0
	v_lshl_add_u64 v[20:21], v[14:15], 0, v[0:1]
	flat_store_dwordx4 v[20:21], v[16:19]
	ds_read_b32 v0, v51 offset:224
	ds_read_b32 v13, v51 offset:484
	s_waitcnt lgkmcnt(0)
	v_cvt_pk_bf16_f32 v16, v0, v13
	ds_read_b32 v0, v51 offset:744
	ds_read_b32 v13, v51 offset:1004
	s_waitcnt lgkmcnt(0)
	v_cvt_pk_bf16_f32 v17, v0, v13
	ds_read_b32 v0, v51 offset:1264
	ds_read_b32 v13, v51 offset:1524
	s_waitcnt lgkmcnt(0)
	v_cvt_pk_bf16_f32 v18, v0, v13
	ds_read_b32 v0, v51 offset:1784
	ds_read_b32 v13, v51 offset:2044
	s_waitcnt lgkmcnt(0)
	v_cvt_pk_bf16_f32 v19, v0, v13
	v_or_b32_e32 v0, s4, v58
	v_mul_u32_u24_e32 v0, 0x1600, v0
	v_lshlrev_b32_e32 v0, 1, v0
	v_lshl_add_u64 v[14:15], v[14:15], 0, v[0:1]
	flat_store_dwordx4 v[14:15], v[16:19]
	s_waitcnt lgkmcnt(0)

.LBB0_800:
	v_add_u32_e32 v0, 0x3c00, v49
	ds_write2_b32 v0, v16, v17 offset0:190 offset1:255
	s_waitcnt lgkmcnt(0)
	ds_read_b32 v0, v51
	ds_read_b32 v13, v51 offset:260
	s_lshl_b32 s90, s7, 1
	v_lshl_add_u64 v[14:15], v[8:9], 0, s[90:91]
	s_waitcnt lgkmcnt(0)
	v_cvt_pk_bf16_f32 v16, v0, v13
	ds_read_b32 v0, v51 offset:520
	ds_read_b32 v13, v51 offset:780
	s_waitcnt lgkmcnt(1)
	s_waitcnt lgkmcnt(0)
	v_cvt_pk_bf16_f32 v17, v0, v13
	ds_read_b32 v0, v51 offset:1040
	ds_read_b32 v13, v51 offset:1300
	s_waitcnt lgkmcnt(1)
	s_waitcnt lgkmcnt(0)
	v_cvt_pk_bf16_f32 v18, v0, v13
	ds_read_b32 v0, v51 offset:1560
	ds_read_b32 v13, v51 offset:1820
	s_waitcnt lgkmcnt(1)
	s_waitcnt lgkmcnt(0)
	v_cvt_pk_bf16_f32 v19, v0, v13
	v_or_b32_e32 v0, s6, v50
	v_lshlrev_b32_e32 v0, 12, v0
	v_lshl_add_u64 v[20:21], v[14:15], 0, v[0:1]
	flat_store_dwordx4 v[20:21], v[16:19]
	ds_read_b32 v0, v51 offset:32
	ds_read_b32 v13, v51 offset:292
	s_waitcnt lgkmcnt(0)
	v_cvt_pk_bf16_f32 v16, v0, v13
	ds_read_b32 v0, v51 offset:552
	ds_read_b32 v13, v51 offset:812
	s_waitcnt lgkmcnt(0)
	v_cvt_pk_bf16_f32 v17, v0, v13
	ds_read_b32 v0, v51 offset:1072
	ds_read_b32 v13, v51 offset:1332
	s_waitcnt lgkmcnt(0)
	v_cvt_pk_bf16_f32 v18, v0, v13
	ds_read_b32 v0, v51 offset:1592
	ds_read_b32 v13, v51 offset:1852
	s_waitcnt lgkmcnt(0)
	v_cvt_pk_bf16_f32 v19, v0, v13
	v_or_b32_e32 v0, s6, v52
	v_lshlrev_b32_e32 v0, 12, v0
	v_lshl_add_u64 v[20:21], v[14:15], 0, v[0:1]
	flat_store_dwordx4 v[20:21], v[16:19]
	ds_read_b32 v0, v51 offset:64
	ds_read_b32 v13, v51 offset:324
	s_waitcnt lgkmcnt(0)
	v_cvt_pk_bf16_f32 v16, v0, v13
	ds_read_b32 v0, v51 offset:584
	ds_read_b32 v13, v51 offset:844
	s_waitcnt lgkmcnt(0)
	v_cvt_pk_bf16_f32 v17, v0, v13
	ds_read_b32 v0, v51 offset:1104
	ds_read_b32 v13, v51 offset:1364
	s_waitcnt lgkmcnt(0)
	v_cvt_pk_bf16_f32 v18, v0, v13
	ds_read_b32 v0, v51 offset:1624
	ds_read_b32 v13, v51 offset:1884
	s_waitcnt lgkmcnt(0)
	v_cvt_pk_bf16_f32 v19, v0, v13
	v_or_b32_e32 v0, s6, v53
	v_lshlrev_b32_e32 v0, 12, v0
	v_lshl_add_u64 v[20:21], v[14:15], 0, v[0:1]
	flat_store_dwordx4 v[20:21], v[16:19]
	ds_read_b32 v0, v51 offset:96
	ds_read_b32 v13, v51 offset:356
	s_waitcnt lgkmcnt(0)
	v_cvt_pk_bf16_f32 v16, v0, v13
	ds_read_b32 v0, v51 offset:616
	ds_read_b32 v13, v51 offset:876
	s_waitcnt lgkmcnt(0)
	v_cvt_pk_bf16_f32 v17, v0, v13
	ds_read_b32 v0, v51 offset:1136
	ds_read_b32 v13, v51 offset:1396
	s_waitcnt lgkmcnt(0)
	v_cvt_pk_bf16_f32 v18, v0, v13
	ds_read_b32 v0, v51 offset:1656
	ds_read_b32 v13, v51 offset:1916
	s_waitcnt lgkmcnt(0)
	v_cvt_pk_bf16_f32 v19, v0, v13
	v_or_b32_e32 v0, s6, v54
	v_lshlrev_b32_e32 v0, 12, v0
	v_lshl_add_u64 v[20:21], v[14:15], 0, v[0:1]
	flat_store_dwordx4 v[20:21], v[16:19]
	ds_read_b32 v0, v51 offset:128
	ds_read_b32 v13, v51 offset:388
	s_waitcnt lgkmcnt(0)
	v_cvt_pk_bf16_f32 v16, v0, v13
	ds_read_b32 v0, v51 offset:648
	ds_read_b32 v13, v51 offset:908
	s_waitcnt lgkmcnt(0)
	v_cvt_pk_bf16_f32 v17, v0, v13
	ds_read_b32 v0, v51 offset:1168
	ds_read_b32 v13, v51 offset:1428
	s_waitcnt lgkmcnt(0)
	v_cvt_pk_bf16_f32 v18, v0, v13
	ds_read_b32 v0, v51 offset:1688
	ds_read_b32 v13, v51 offset:1948
	s_waitcnt lgkmcnt(0)
	v_cvt_pk_bf16_f32 v19, v0, v13
	v_or_b32_e32 v0, s6, v55
	v_lshlrev_b32_e32 v0, 12, v0
	v_lshl_add_u64 v[20:21], v[14:15], 0, v[0:1]
	flat_store_dwordx4 v[20:21], v[16:19]
	ds_read_b32 v0, v51 offset:160
	ds_read_b32 v13, v51 offset:420
	s_waitcnt lgkmcnt(0)
	v_cvt_pk_bf16_f32 v16, v0, v13
	ds_read_b32 v0, v51 offset:680
	ds_read_b32 v13, v51 offset:940
	s_waitcnt lgkmcnt(0)
	v_cvt_pk_bf16_f32 v17, v0, v13
	ds_read_b32 v0, v51 offset:1200
	ds_read_b32 v13, v51 offset:1460
	s_waitcnt lgkmcnt(0)
	v_cvt_pk_bf16_f32 v18, v0, v13
	ds_read_b32 v0, v51 offset:1720
	ds_read_b32 v13, v51 offset:1980
	s_waitcnt lgkmcnt(0)
	v_cvt_pk_bf16_f32 v19, v0, v13
	v_or_b32_e32 v0, s6, v56
	v_lshlrev_b32_e32 v0, 12, v0
	v_lshl_add_u64 v[20:21], v[14:15], 0, v[0:1]
	flat_store_dwordx4 v[20:21], v[16:19]
	ds_read_b32 v0, v51 offset:192
	ds_read_b32 v13, v51 offset:452
	s_waitcnt lgkmcnt(0)
	v_cvt_pk_bf16_f32 v16, v0, v13
	ds_read_b32 v0, v51 offset:712
	ds_read_b32 v13, v51 offset:972
	s_waitcnt lgkmcnt(0)
	v_cvt_pk_bf16_f32 v17, v0, v13
	ds_read_b32 v0, v51 offset:1232
	ds_read_b32 v13, v51 offset:1492
	s_waitcnt lgkmcnt(0)
	v_cvt_pk_bf16_f32 v18, v0, v13
	ds_read_b32 v0, v51 offset:1752
	ds_read_b32 v13, v51 offset:2012
	s_waitcnt lgkmcnt(0)
	v_cvt_pk_bf16_f32 v19, v0, v13
	v_or_b32_e32 v0, s6, v57
	v_lshlrev_b32_e32 v0, 12, v0
	v_lshl_add_u64 v[20:21], v[14:15], 0, v[0:1]
	flat_store_dwordx4 v[20:21], v[16:19]
	ds_read_b32 v0, v51 offset:224
	ds_read_b32 v13, v51 offset:484
	s_waitcnt lgkmcnt(0)
	v_cvt_pk_bf16_f32 v16, v0, v13
	ds_read_b32 v0, v51 offset:744
	ds_read_b32 v13, v51 offset:1004
	s_waitcnt lgkmcnt(0)
	v_cvt_pk_bf16_f32 v17, v0, v13
	ds_read_b32 v0, v51 offset:1264
	ds_read_b32 v13, v51 offset:1524
	s_waitcnt lgkmcnt(0)
	v_cvt_pk_bf16_f32 v18, v0, v13
	ds_read_b32 v0, v51 offset:1784
	ds_read_b32 v13, v51 offset:2044
	s_waitcnt lgkmcnt(0)
	v_cvt_pk_bf16_f32 v19, v0, v13
	v_or_b32_e32 v0, s6, v58
	v_lshlrev_b32_e32 v0, 12, v0
	v_lshl_add_u64 v[14:15], v[14:15], 0, v[0:1]
	flat_store_dwordx4 v[14:15], v[16:19]
	s_waitcnt lgkmcnt(0)

.LBB0_802:
	s_andn2_b64 vcc, exec, s[4:5]
	s_cbranch_vccnz .LBB0_804
	s_add_i32 s4, s63, 0xe300
	s_bfe_u32 s5, s4, 0xb0005
	s_and_b32 s4, s64, 0x7c0
	v_or_b32_e32 v0, s4, v48
	v_lshlrev_b32_e32 v0, 2, v0
	v_lshl_add_u64 v[14:15], s[48:49], 0, v[0:1]
	s_lshl_b32 s90, s5, 19
	v_lshl_add_u64 v[14:15], v[14:15], 0, s[90:91]
	v_add_co_u32_e32 v16, vcc, 0x2000, v14
	global_load_dword v0, v[14:15], off
	s_nop 0
	v_addc_co_u32_e32 v17, vcc, 0, v15, vcc
	global_load_dword v13, v[16:17], off
	v_add_co_u32_e32 v16, vcc, 0x4000, v14
	s_mov_b32 s6, 0x10000
	s_nop 0
	v_addc_co_u32_e32 v17, vcc, 0, v15, vcc
	v_add_co_u32_e32 v18, vcc, 0x6000, v14
	global_load_dword v16, v[16:17], off
	s_nop 0
	v_addc_co_u32_e32 v19, vcc, 0, v15, vcc
	global_load_dword v17, v[18:19], off
	v_add_co_u32_e32 v18, vcc, 0x8000, v14
	s_lshl_b32 s90, s5, 7
	s_nop 0
	v_addc_co_u32_e32 v19, vcc, 0, v15, vcc
	v_add_co_u32_e32 v20, vcc, 0xa000, v14
	global_load_dword v18, v[18:19], off
	s_nop 0
	v_addc_co_u32_e32 v21, vcc, 0, v15, vcc
	global_load_dword v19, v[20:21], off
	v_add_co_u32_e32 v20, vcc, 0xc000, v14
	s_nop 1
	v_addc_co_u32_e32 v21, vcc, 0, v15, vcc
	v_add_co_u32_e32 v22, vcc, 0xe000, v14
	global_load_dword v20, v[20:21], off
	s_nop 0
	v_addc_co_u32_e32 v23, vcc, 0, v15, vcc
	global_load_dword v21, v[22:23], off
	v_add_co_u32_e32 v22, vcc, s6, v14
	s_mov_b32 s6, 0x12000
	s_nop 0
	v_addc_co_u32_e32 v23, vcc, 0, v15, vcc
	v_add_co_u32_e32 v24, vcc, s6, v14
	s_mov_b32 s6, 0x14000
	s_nop 0
	v_addc_co_u32_e32 v25, vcc, 0, v15, vcc
	global_load_dword v22, v[22:23], off
	s_nop 0
	global_load_dword v23, v[24:25], off
	v_add_co_u32_e32 v24, vcc, s6, v14
	s_mov_b32 s6, 0x1a000
	s_nop 0
	v_addc_co_u32_e32 v25, vcc, 0, v15, vcc
	v_add_co_u32_e32 v26, vcc, s14, v14
	global_load_dword v24, v[24:25], off
	s_nop 0
	v_addc_co_u32_e32 v27, vcc, 0, v15, vcc
	global_load_dword v25, v[26:27], off
	v_add_co_u32_e32 v26, vcc, s9, v14
	s_nop 1
	v_addc_co_u32_e32 v27, vcc, 0, v15, vcc
	v_add_co_u32_e32 v28, vcc, s6, v14
	s_mov_b32 s6, 0x1c000
	s_nop 0
	v_addc_co_u32_e32 v29, vcc, 0, v15, vcc
	global_load_dword v26, v[26:27], off
	s_nop 0
	global_load_dword v27, v[28:29], off
	v_add_co_u32_e32 v28, vcc, s6, v14
	s_mov_b32 s6, 0x1e000
	s_nop 0
	v_addc_co_u32_e32 v29, vcc, 0, v15, vcc
	v_add_co_u32_e32 v30, vcc, s6, v14
	s_mov_b32 s6, 0x20000
	s_nop 0
	v_addc_co_u32_e32 v31, vcc, 0, v15, vcc
	global_load_dword v28, v[28:29], off
	s_nop 0
	global_load_dword v29, v[30:31], off
	v_add_co_u32_e32 v30, vcc, s6, v14
	s_mov_b32 s6, 0x22000
	s_nop 0
	v_addc_co_u32_e32 v31, vcc, 0, v15, vcc
	v_add_co_u32_e32 v32, vcc, s6, v14
	s_mov_b32 s6, 0x24000
	s_nop 0
	v_addc_co_u32_e32 v33, vcc, 0, v15, vcc
	global_load_dword v30, v[30:31], off
	s_nop 0
	global_load_dword v31, v[32:33], off
	v_add_co_u32_e32 v32, vcc, s6, v14
	s_mov_b32 s6, 0x26000
	s_nop 0
	v_addc_co_u32_e32 v33, vcc, 0, v15, vcc
	v_add_co_u32_e32 v34, vcc, s6, v14
	s_mov_b32 s6, 0x28000
	s_nop 0
	v_addc_co_u32_e32 v35, vcc, 0, v15, vcc
	global_load_dword v32, v[32:33], off
	s_nop 0
	global_load_dword v33, v[34:35], off
	v_add_co_u32_e32 v34, vcc, s6, v14
	s_mov_b32 s6, 0x2a000
	s_nop 0
	v_addc_co_u32_e32 v35, vcc, 0, v15, vcc
	v_add_co_u32_e32 v36, vcc, s6, v14
	s_mov_b32 s6, 0x2c000
	s_nop 0
	v_addc_co_u32_e32 v37, vcc, 0, v15, vcc
	global_load_dword v34, v[34:35], off
	s_nop 0
	global_load_dword v35, v[36:37], off
	v_add_co_u32_e32 v36, vcc, s6, v14
	s_mov_b32 s6, 0x2e000
	s_nop 0
	v_addc_co_u32_e32 v37, vcc, 0, v15, vcc
	v_add_co_u32_e32 v38, vcc, s6, v14
	s_mov_b32 s6, 0x30000
	s_nop 0
	v_addc_co_u32_e32 v39, vcc, 0, v15, vcc
	global_load_dword v36, v[36:37], off
	s_nop 0
	global_load_dword v37, v[38:39], off
	v_add_co_u32_e32 v38, vcc, s6, v14
	s_mov_b32 s6, 0x32000
	s_nop 0
	v_addc_co_u32_e32 v39, vcc, 0, v15, vcc
	v_add_co_u32_e32 v40, vcc, s6, v14
	s_mov_b32 s6, 0x34000
	s_nop 0
	v_addc_co_u32_e32 v41, vcc, 0, v15, vcc
	global_load_dword v38, v[38:39], off
	s_nop 0
	global_load_dword v39, v[40:41], off
	v_add_co_u32_e32 v40, vcc, s6, v14
	s_mov_b32 s6, 0x36000
	s_nop 0
	v_addc_co_u32_e32 v41, vcc, 0, v15, vcc
	v_add_co_u32_e32 v42, vcc, s6, v14
	s_mov_b32 s6, 0x38000
	s_nop 0
	v_addc_co_u32_e32 v43, vcc, 0, v15, vcc
	global_load_dword v40, v[40:41], off
	s_nop 0
	global_load_dword v41, v[42:43], off
	v_add_co_u32_e32 v42, vcc, s6, v14
	s_mov_b32 s6, 0x3a000
	s_nop 0
	v_addc_co_u32_e32 v43, vcc, 0, v15, vcc
	global_load_dword v44, v[42:43], off
	v_add_co_u32_e32 v42, vcc, s6, v14
	s_mov_b32 s6, 0x3c000
	s_nop 0
	v_addc_co_u32_e32 v43, vcc, 0, v15, vcc
	global_load_dword v45, v[42:43], off
	v_add_co_u32_e32 v42, vcc, s6, v14
	s_mov_b32 s6, 0x3e000
	s_nop 0
	v_addc_co_u32_e32 v43, vcc, 0, v15, vcc
	global_load_dword v46, v[42:43], off
	v_add_co_u32_e32 v42, vcc, s6, v14
	s_mov_b32 s6, 0x40000
	s_nop 0
	v_addc_co_u32_e32 v43, vcc, 0, v15, vcc
	global_load_dword v47, v[42:43], off
	v_add_co_u32_e32 v42, vcc, s6, v14
	s_mov_b32 s6, 0x42000
	s_nop 0
	v_addc_co_u32_e32 v43, vcc, 0, v15, vcc
	global_load_dword v59, v[42:43], off
	v_add_co_u32_e32 v42, vcc, s6, v14
	s_mov_b32 s6, 0x44000
	s_nop 0
	v_addc_co_u32_e32 v43, vcc, 0, v15, vcc
	global_load_dword v60, v[42:43], off
	v_add_co_u32_e32 v42, vcc, s6, v14
	s_mov_b32 s6, 0x46000
	s_nop 0
	v_addc_co_u32_e32 v43, vcc, 0, v15, vcc
	global_load_dword v61, v[42:43], off
	v_add_co_u32_e32 v42, vcc, s6, v14
	s_mov_b32 s6, 0x48000
	s_nop 0
	v_addc_co_u32_e32 v43, vcc, 0, v15, vcc
	global_load_dword v62, v[42:43], off
	v_add_co_u32_e32 v42, vcc, s6, v14
	s_mov_b32 s6, 0x4a000
	s_nop 0
	v_addc_co_u32_e32 v43, vcc, 0, v15, vcc
	global_load_dword v63, v[42:43], off
	v_add_co_u32_e32 v42, vcc, s6, v14
	s_mov_b32 s6, 0x4c000
	s_nop 0
	v_addc_co_u32_e32 v43, vcc, 0, v15, vcc
	global_load_dword v64, v[42:43], off
	v_add_co_u32_e32 v42, vcc, s6, v14
	s_mov_b32 s6, 0x4e000
	s_nop 0
	v_addc_co_u32_e32 v43, vcc, 0, v15, vcc
	global_load_dword v65, v[42:43], off
	v_add_co_u32_e32 v42, vcc, s6, v14
	s_mov_b32 s6, 0x50000
	s_nop 0
	v_addc_co_u32_e32 v43, vcc, 0, v15, vcc
	global_load_dword v66, v[42:43], off
	v_add_co_u32_e32 v42, vcc, s6, v14
	s_mov_b32 s6, 0x52000
	s_nop 0
	v_addc_co_u32_e32 v43, vcc, 0, v15, vcc
	global_load_dword v67, v[42:43], off
	v_add_co_u32_e32 v42, vcc, s6, v14
	s_mov_b32 s6, 0x54000
	s_nop 0
	v_addc_co_u32_e32 v43, vcc, 0, v15, vcc
	global_load_dword v68, v[42:43], off
	v_add_co_u32_e32 v42, vcc, s6, v14
	s_mov_b32 s6, 0x56000
	s_nop 0
	v_addc_co_u32_e32 v43, vcc, 0, v15, vcc
	global_load_dword v69, v[42:43], off
	v_add_co_u32_e32 v42, vcc, s6, v14
	s_mov_b32 s6, 0x58000
	s_nop 0
	v_addc_co_u32_e32 v43, vcc, 0, v15, vcc
	global_load_dword v70, v[42:43], off
	v_add_co_u32_e32 v42, vcc, s6, v14
	s_mov_b32 s6, 0x5a000
	s_nop 0
	v_addc_co_u32_e32 v43, vcc, 0, v15, vcc
	global_load_dword v71, v[42:43], off
	v_add_co_u32_e32 v42, vcc, s6, v14
	s_mov_b32 s6, 0x5c000
	s_nop 0
	v_addc_co_u32_e32 v43, vcc, 0, v15, vcc
	global_load_dword v72, v[42:43], off
	v_add_co_u32_e32 v42, vcc, s6, v14
	s_mov_b32 s6, 0x5e000
	s_nop 0
	v_addc_co_u32_e32 v43, vcc, 0, v15, vcc
	global_load_dword v73, v[42:43], off
	v_add_co_u32_e32 v42, vcc, s6, v14
	s_mov_b32 s6, 0x60000
	s_nop 0
	v_addc_co_u32_e32 v43, vcc, 0, v15, vcc
	global_load_dword v74, v[42:43], off
	v_add_co_u32_e32 v42, vcc, s6, v14
	s_mov_b32 s6, 0x64000
	s_nop 0
	v_addc_co_u32_e32 v43, vcc, 0, v15, vcc
	global_load_dword v75, v[42:43], off
	v_add_co_u32_e32 v42, vcc, s21, v14
	s_nop 1
	v_addc_co_u32_e32 v43, vcc, 0, v15, vcc
	global_load_dword v76, v[42:43], off
	v_add_co_u32_e32 v42, vcc, s6, v14
	s_mov_b32 s6, 0x66000
	s_nop 0
	v_addc_co_u32_e32 v43, vcc, 0, v15, vcc
	global_load_dword v77, v[42:43], off
	v_add_co_u32_e32 v42, vcc, s6, v14
	s_mov_b32 s6, 0x68000
	s_nop 0
	v_addc_co_u32_e32 v43, vcc, 0, v15, vcc
	global_load_dword v78, v[42:43], off
	v_add_co_u32_e32 v42, vcc, s6, v14
	s_mov_b32 s6, 0x6a000
	s_nop 0
	v_addc_co_u32_e32 v43, vcc, 0, v15, vcc
	global_load_dword v79, v[42:43], off
	v_add_co_u32_e32 v42, vcc, s6, v14
	s_mov_b32 s6, 0x6c000
	s_nop 0
	v_addc_co_u32_e32 v43, vcc, 0, v15, vcc
	global_load_dword v80, v[42:43], off
	v_add_co_u32_e32 v42, vcc, s6, v14
	s_mov_b32 s6, 0x70000
	s_nop 0
	v_addc_co_u32_e32 v43, vcc, 0, v15, vcc
	global_load_dword v81, v[42:43], off
	v_add_co_u32_e32 v42, vcc, s16, v14
	s_nop 1
	v_addc_co_u32_e32 v43, vcc, 0, v15, vcc
	global_load_dword v82, v[42:43], off
	v_add_co_u32_e32 v42, vcc, s6, v14
	s_mov_b32 s6, 0x72000
	s_nop 0
	v_addc_co_u32_e32 v43, vcc, 0, v15, vcc
	global_load_dword v83, v[42:43], off
	v_add_co_u32_e32 v42, vcc, s6, v14
	s_mov_b32 s6, 0x74000
	s_nop 0
	v_addc_co_u32_e32 v43, vcc, 0, v15, vcc
	global_load_dword v84, v[42:43], off
	v_add_co_u32_e32 v42, vcc, s6, v14
	s_mov_b32 s6, 0x76000
	s_nop 0
	v_addc_co_u32_e32 v43, vcc, 0, v15, vcc
	global_load_dword v85, v[42:43], off
	v_add_co_u32_e32 v42, vcc, s6, v14
	s_mov_b32 s6, 0x78000
	s_nop 0
	v_addc_co_u32_e32 v43, vcc, 0, v15, vcc
	global_load_dword v86, v[42:43], off
	v_add_co_u32_e32 v42, vcc, s6, v14
	s_mov_b32 s6, 0x7c000
	s_nop 0
	v_addc_co_u32_e32 v43, vcc, 0, v15, vcc
	global_load_dword v87, v[42:43], off
	v_add_co_u32_e32 v42, vcc, s89, v14
	s_nop 1
	v_addc_co_u32_e32 v43, vcc, 0, v15, vcc
	global_load_dword v88, v[42:43], off
	v_add_co_u32_e32 v42, vcc, s6, v14
	s_mov_b32 s6, 0x7e000
	s_nop 0
	v_addc_co_u32_e32 v43, vcc, 0, v15, vcc
	v_add_co_u32_e32 v14, vcc, s6, v14
	global_load_dword v42, v[42:43], off
	s_nop 0
	v_addc_co_u32_e32 v15, vcc, 0, v15, vcc
	global_load_dword v14, v[14:15], off
	s_waitcnt vmcnt(0)
	ds_write2_b32 v49, v0, v13 offset1:65
	ds_write2_b32 v49, v16, v17 offset0:130 offset1:195
	v_add_u32_e32 v0, 0x400, v49
	ds_write2_b32 v0, v18, v19 offset0:4 offset1:69
	ds_write2_b32 v0, v20, v21 offset0:134 offset1:199
	v_add_u32_e32 v0, 0x800, v49
	ds_write2_b32 v0, v22, v23 offset0:8 offset1:73
	ds_write2_b32 v0, v24, v25 offset0:138 offset1:203
	v_add_u32_e32 v0, 0xc00, v49
	ds_write2_b32 v0, v26, v27 offset0:12 offset1:77
	ds_write2_b32 v0, v28, v29 offset0:142 offset1:207
	v_add_u32_e32 v0, 0x1000, v49
	ds_write2_b32 v0, v30, v31 offset0:16 offset1:81
	ds_write2_b32 v0, v32, v33 offset0:146 offset1:211
	v_add_u32_e32 v0, 0x1400, v49
	ds_write2_b32 v0, v34, v35 offset0:20 offset1:85
	ds_write2_b32 v0, v36, v37 offset0:150 offset1:215
	v_add_u32_e32 v0, 0x1800, v49
	ds_write2_b32 v0, v38, v39 offset0:24 offset1:89
	ds_write2_b32 v0, v40, v41 offset0:154 offset1:219
	v_add_u32_e32 v0, 0x1c00, v49
	ds_write2_b32 v0, v44, v45 offset0:28 offset1:93
	ds_write2_b32 v0, v46, v47 offset0:158 offset1:223
	v_add_u32_e32 v0, 0x2000, v49
	ds_write2_b32 v0, v59, v60 offset0:32 offset1:97
	ds_write2_b32 v0, v61, v62 offset0:162 offset1:227
	v_add_u32_e32 v0, 0x2400, v49
	ds_write2_b32 v0, v63, v64 offset0:36 offset1:101
	ds_write2_b32 v0, v65, v66 offset0:166 offset1:231
	v_add_u32_e32 v0, 0x2800, v49
	ds_write2_b32 v0, v67, v68 offset0:40 offset1:105
	ds_write2_b32 v0, v69, v70 offset0:170 offset1:235
	v_add_u32_e32 v0, 0x2c00, v49
	ds_write2_b32 v0, v71, v72 offset0:44 offset1:109
	ds_write2_b32 v0, v73, v74 offset0:174 offset1:239
	v_add_u32_e32 v0, 0x3000, v49
	ds_write2_b32 v0, v75, v76 offset0:48 offset1:113
	ds_write2_b32 v0, v77, v78 offset0:178 offset1:243
	v_add_u32_e32 v0, 0x3400, v49
	ds_write2_b32 v0, v79, v80 offset0:52 offset1:117
	ds_write2_b32 v0, v81, v82 offset0:182 offset1:247
	v_add_u32_e32 v0, 0x3800, v49
	ds_write2_b32 v0, v83, v84 offset0:56 offset1:121
	ds_write2_b32 v0, v85, v86 offset0:186 offset1:251
	v_add_u32_e32 v0, 0x3c00, v49
	ds_write2_b32 v0, v87, v88 offset0:60 offset1:125
	ds_write2_b32 v0, v42, v14 offset0:190 offset1:255
	s_waitcnt lgkmcnt(0)
	ds_read_b32 v0, v51
	ds_read_b32 v13, v51 offset:260
	v_lshl_add_u64 v[14:15], v[10:11], 0, s[90:91]
	s_waitcnt lgkmcnt(0)
	v_cvt_pk_bf16_f32 v16, v0, v13
	ds_read_b32 v0, v51 offset:520
	ds_read_b32 v13, v51 offset:780
	s_waitcnt lgkmcnt(1)
	s_waitcnt lgkmcnt(0)
	v_cvt_pk_bf16_f32 v17, v0, v13
	ds_read_b32 v0, v51 offset:1040
	ds_read_b32 v13, v51 offset:1300
	s_waitcnt lgkmcnt(1)
	s_waitcnt lgkmcnt(0)
	v_cvt_pk_bf16_f32 v18, v0, v13
	ds_read_b32 v0, v51 offset:1560
	ds_read_b32 v13, v51 offset:1820
	s_waitcnt lgkmcnt(1)
	s_waitcnt lgkmcnt(0)
	v_cvt_pk_bf16_f32 v19, v0, v13
	v_or_b32_e32 v0, s4, v50
	v_lshlrev_b32_e32 v0, 12, v0
	v_lshl_add_u64 v[20:21], v[14:15], 0, v[0:1]
	flat_store_dwordx4 v[20:21], v[16:19]
	ds_read_b32 v0, v51 offset:32
	ds_read_b32 v13, v51 offset:292
	s_waitcnt lgkmcnt(0)
	v_cvt_pk_bf16_f32 v16, v0, v13
	ds_read_b32 v0, v51 offset:552
	ds_read_b32 v13, v51 offset:812
	s_waitcnt lgkmcnt(0)
	v_cvt_pk_bf16_f32 v17, v0, v13
	ds_read_b32 v0, v51 offset:1072
	ds_read_b32 v13, v51 offset:1332
	s_waitcnt lgkmcnt(0)
	v_cvt_pk_bf16_f32 v18, v0, v13
	ds_read_b32 v0, v51 offset:1592
	ds_read_b32 v13, v51 offset:1852
	s_waitcnt lgkmcnt(0)
	v_cvt_pk_bf16_f32 v19, v0, v13
	v_or_b32_e32 v0, s4, v52
	v_lshlrev_b32_e32 v0, 12, v0
	v_lshl_add_u64 v[20:21], v[14:15], 0, v[0:1]
	flat_store_dwordx4 v[20:21], v[16:19]
	ds_read_b32 v0, v51 offset:64
	ds_read_b32 v13, v51 offset:324
	s_waitcnt lgkmcnt(0)
	v_cvt_pk_bf16_f32 v16, v0, v13
	ds_read_b32 v0, v51 offset:584
	ds_read_b32 v13, v51 offset:844
	s_waitcnt lgkmcnt(0)
	v_cvt_pk_bf16_f32 v17, v0, v13
	ds_read_b32 v0, v51 offset:1104
	ds_read_b32 v13, v51 offset:1364
	s_waitcnt lgkmcnt(0)
	v_cvt_pk_bf16_f32 v18, v0, v13
	ds_read_b32 v0, v51 offset:1624
	ds_read_b32 v13, v51 offset:1884
	s_waitcnt lgkmcnt(0)
	v_cvt_pk_bf16_f32 v19, v0, v13
	v_or_b32_e32 v0, s4, v53
	v_lshlrev_b32_e32 v0, 12, v0
	v_lshl_add_u64 v[20:21], v[14:15], 0, v[0:1]
	flat_store_dwordx4 v[20:21], v[16:19]
	ds_read_b32 v0, v51 offset:96
	ds_read_b32 v13, v51 offset:356
	s_waitcnt lgkmcnt(0)
	v_cvt_pk_bf16_f32 v16, v0, v13
	ds_read_b32 v0, v51 offset:616
	ds_read_b32 v13, v51 offset:876
	s_waitcnt lgkmcnt(0)
	v_cvt_pk_bf16_f32 v17, v0, v13
	ds_read_b32 v0, v51 offset:1136
	ds_read_b32 v13, v51 offset:1396
	s_waitcnt lgkmcnt(0)
	v_cvt_pk_bf16_f32 v18, v0, v13
	ds_read_b32 v0, v51 offset:1656
	ds_read_b32 v13, v51 offset:1916
	s_waitcnt lgkmcnt(0)
	v_cvt_pk_bf16_f32 v19, v0, v13
	v_or_b32_e32 v0, s4, v54
	v_lshlrev_b32_e32 v0, 12, v0
	v_lshl_add_u64 v[20:21], v[14:15], 0, v[0:1]
	flat_store_dwordx4 v[20:21], v[16:19]
	ds_read_b32 v0, v51 offset:128
	ds_read_b32 v13, v51 offset:388
	s_waitcnt lgkmcnt(0)
	v_cvt_pk_bf16_f32 v16, v0, v13
	ds_read_b32 v0, v51 offset:648
	ds_read_b32 v13, v51 offset:908
	s_waitcnt lgkmcnt(0)
	v_cvt_pk_bf16_f32 v17, v0, v13
	ds_read_b32 v0, v51 offset:1168
	ds_read_b32 v13, v51 offset:1428
	s_waitcnt lgkmcnt(0)
	v_cvt_pk_bf16_f32 v18, v0, v13
	ds_read_b32 v0, v51 offset:1688
	ds_read_b32 v13, v51 offset:1948
	s_waitcnt lgkmcnt(0)
	v_cvt_pk_bf16_f32 v19, v0, v13
	v_or_b32_e32 v0, s4, v55
	v_lshlrev_b32_e32 v0, 12, v0
	v_lshl_add_u64 v[20:21], v[14:15], 0, v[0:1]
	flat_store_dwordx4 v[20:21], v[16:19]
	ds_read_b32 v0, v51 offset:160
	ds_read_b32 v13, v51 offset:420
	s_waitcnt lgkmcnt(0)
	v_cvt_pk_bf16_f32 v16, v0, v13
	ds_read_b32 v0, v51 offset:680
	ds_read_b32 v13, v51 offset:940
	s_waitcnt lgkmcnt(0)
	v_cvt_pk_bf16_f32 v17, v0, v13
	ds_read_b32 v0, v51 offset:1200
	ds_read_b32 v13, v51 offset:1460
	s_waitcnt lgkmcnt(0)
	v_cvt_pk_bf16_f32 v18, v0, v13
	ds_read_b32 v0, v51 offset:1720
	ds_read_b32 v13, v51 offset:1980
	s_waitcnt lgkmcnt(0)
	v_cvt_pk_bf16_f32 v19, v0, v13
	v_or_b32_e32 v0, s4, v56
	v_lshlrev_b32_e32 v0, 12, v0
	v_lshl_add_u64 v[20:21], v[14:15], 0, v[0:1]
	flat_store_dwordx4 v[20:21], v[16:19]
	ds_read_b32 v0, v51 offset:192
	ds_read_b32 v13, v51 offset:452
	s_waitcnt lgkmcnt(0)
	v_cvt_pk_bf16_f32 v16, v0, v13
	ds_read_b32 v0, v51 offset:712
	ds_read_b32 v13, v51 offset:972
	s_waitcnt lgkmcnt(0)
	v_cvt_pk_bf16_f32 v17, v0, v13
	ds_read_b32 v0, v51 offset:1232
	ds_read_b32 v13, v51 offset:1492
	s_waitcnt lgkmcnt(0)
	v_cvt_pk_bf16_f32 v18, v0, v13
	ds_read_b32 v0, v51 offset:1752
	ds_read_b32 v13, v51 offset:2012
	s_waitcnt lgkmcnt(0)
	v_cvt_pk_bf16_f32 v19, v0, v13
	v_or_b32_e32 v0, s4, v57
	v_lshlrev_b32_e32 v0, 12, v0
	v_lshl_add_u64 v[20:21], v[14:15], 0, v[0:1]
	flat_store_dwordx4 v[20:21], v[16:19]
	ds_read_b32 v0, v51 offset:224
	ds_read_b32 v13, v51 offset:484
	s_waitcnt lgkmcnt(0)
	v_cvt_pk_bf16_f32 v16, v0, v13
	ds_read_b32 v0, v51 offset:744
	ds_read_b32 v13, v51 offset:1004
	s_waitcnt lgkmcnt(0)
	v_cvt_pk_bf16_f32 v17, v0, v13
	ds_read_b32 v0, v51 offset:1264
	ds_read_b32 v13, v51 offset:1524
	s_waitcnt lgkmcnt(0)
	v_cvt_pk_bf16_f32 v18, v0, v13
	ds_read_b32 v0, v51 offset:1784
	ds_read_b32 v13, v51 offset:2044
	s_waitcnt lgkmcnt(0)
	v_cvt_pk_bf16_f32 v19, v0, v13
	v_or_b32_e32 v0, s4, v58
	v_lshlrev_b32_e32 v0, 12, v0
	v_lshl_add_u64 v[14:15], v[14:15], 0, v[0:1]
	flat_store_dwordx4 v[14:15], v[16:19]
	s_waitcnt lgkmcnt(0)

.LBB0_805:
	s_andn2_b64 vcc, exec, s[4:5]
	s_cbranch_vccnz .LBB0_807
	s_add_i32 s4, s63, 0xffffe700
	s_lshr_b32 s90, s4, 8
	s_lshl_b64 s[4:5], s[90:91], 22
	s_add_u32 s6, s1, s4
	s_addc_u32 s7, s58, s5
	s_and_b32 s4, s64, 0x7c0
	v_or_b32_e32 v0, s4, v48
	s_and_b32 s5, s66, 0x1c0
	v_lshlrev_b32_e32 v0, 2, v0
	v_lshl_add_u64 v[14:15], s[6:7], 0, v[0:1]
	s_lshl_b32 s6, s5, 13
	s_mov_b32 s7, s91
	v_lshl_add_u64 v[14:15], v[14:15], 0, s[6:7]
	v_add_co_u32_e32 v16, vcc, s12, v14
	global_load_dword v0, v[14:15], off
	s_nop 0
	v_addc_co_u32_e32 v17, vcc, 0, v15, vcc
	global_load_dword v13, v[16:17], off
	v_add_co_u32_e32 v16, vcc, s13, v14
	s_movk_i32 s6, 0x6000
	s_nop 0
	v_addc_co_u32_e32 v17, vcc, 0, v15, vcc
	v_add_co_u32_e32 v18, vcc, s6, v14
	s_mov_b32 s6, 0x8000
	s_nop 0
	v_addc_co_u32_e32 v19, vcc, 0, v15, vcc
	global_load_dword v16, v[16:17], off
	s_nop 0
	global_load_dword v17, v[18:19], off
	v_add_co_u32_e32 v18, vcc, s6, v14
	s_mov_b32 s6, 0xa000
	s_nop 0
	v_addc_co_u32_e32 v19, vcc, 0, v15, vcc
	v_add_co_u32_e32 v20, vcc, s6, v14
	s_mov_b32 s6, 0xc000
	s_nop 0
	v_addc_co_u32_e32 v21, vcc, 0, v15, vcc
	global_load_dword v18, v[18:19], off
	s_nop 0
	global_load_dword v19, v[20:21], off
	v_add_co_u32_e32 v20, vcc, s6, v14
	s_mov_b32 s6, 0xe000
	s_nop 0
	v_addc_co_u32_e32 v21, vcc, 0, v15, vcc
	v_add_co_u32_e32 v22, vcc, s6, v14
	s_mov_b32 s6, 0x10000
	s_nop 0
	v_addc_co_u32_e32 v23, vcc, 0, v15, vcc
	global_load_dword v20, v[20:21], off
	s_nop 0
	global_load_dword v21, v[22:23], off
	v_add_co_u32_e32 v22, vcc, s6, v14
	s_mov_b32 s6, 0x12000
	s_nop 0
	v_addc_co_u32_e32 v23, vcc, 0, v15, vcc
	v_add_co_u32_e32 v24, vcc, s6, v14
	s_mov_b32 s6, 0x14000
	s_nop 0
	v_addc_co_u32_e32 v25, vcc, 0, v15, vcc
	global_load_dword v22, v[22:23], off
	s_nop 0
	global_load_dword v23, v[24:25], off
	v_add_co_u32_e32 v24, vcc, s6, v14
	s_mov_b32 s6, 0x1a000
	s_nop 0
	v_addc_co_u32_e32 v25, vcc, 0, v15, vcc
	v_add_co_u32_e32 v26, vcc, s14, v14
	global_load_dword v24, v[24:25], off
	s_nop 0
	v_addc_co_u32_e32 v27, vcc, 0, v15, vcc
	global_load_dword v25, v[26:27], off
	v_add_co_u32_e32 v26, vcc, s9, v14
	s_nop 1
	v_addc_co_u32_e32 v27, vcc, 0, v15, vcc
	v_add_co_u32_e32 v28, vcc, s6, v14
	s_mov_b32 s6, 0x1c000
	s_nop 0
	v_addc_co_u32_e32 v29, vcc, 0, v15, vcc
	global_load_dword v26, v[26:27], off
	s_nop 0
	global_load_dword v27, v[28:29], off
	v_add_co_u32_e32 v28, vcc, s6, v14
	s_mov_b32 s6, 0x1e000
	s_nop 0
	v_addc_co_u32_e32 v29, vcc, 0, v15, vcc
	v_add_co_u32_e32 v30, vcc, s6, v14
	s_mov_b32 s6, 0x20000
	s_nop 0
	v_addc_co_u32_e32 v31, vcc, 0, v15, vcc
	global_load_dword v28, v[28:29], off
	s_nop 0
	global_load_dword v29, v[30:31], off
	v_add_co_u32_e32 v30, vcc, s6, v14
	s_mov_b32 s6, 0x22000
	s_nop 0
	v_addc_co_u32_e32 v31, vcc, 0, v15, vcc
	v_add_co_u32_e32 v32, vcc, s6, v14
	s_mov_b32 s6, 0x24000
	s_nop 0
	v_addc_co_u32_e32 v33, vcc, 0, v15, vcc
	global_load_dword v30, v[30:31], off
	s_nop 0
	global_load_dword v31, v[32:33], off
	v_add_co_u32_e32 v32, vcc, s6, v14
	s_mov_b32 s6, 0x26000
	s_nop 0
	v_addc_co_u32_e32 v33, vcc, 0, v15, vcc
	v_add_co_u32_e32 v34, vcc, s6, v14
	s_mov_b32 s6, 0x28000
	s_nop 0
	v_addc_co_u32_e32 v35, vcc, 0, v15, vcc
	global_load_dword v32, v[32:33], off
	s_nop 0
	global_load_dword v33, v[34:35], off
	v_add_co_u32_e32 v34, vcc, s6, v14
	s_mov_b32 s6, 0x2a000
	s_nop 0
	v_addc_co_u32_e32 v35, vcc, 0, v15, vcc
	v_add_co_u32_e32 v36, vcc, s6, v14
	s_mov_b32 s6, 0x2c000
	s_nop 0
	v_addc_co_u32_e32 v37, vcc, 0, v15, vcc
	global_load_dword v34, v[34:35], off
	s_nop 0
	global_load_dword v35, v[36:37], off
	v_add_co_u32_e32 v36, vcc, s6, v14
	s_mov_b32 s6, 0x2e000
	s_nop 0
	v_addc_co_u32_e32 v37, vcc, 0, v15, vcc
	global_load_dword v38, v[36:37], off
	v_add_co_u32_e32 v36, vcc, s6, v14
	s_mov_b32 s6, 0x30000
	s_nop 0
	v_addc_co_u32_e32 v37, vcc, 0, v15, vcc
	global_load_dword v39, v[36:37], off
	v_add_co_u32_e32 v36, vcc, s6, v14
	s_mov_b32 s6, 0x32000
	s_nop 0
	v_addc_co_u32_e32 v37, vcc, 0, v15, vcc
	global_load_dword v40, v[36:37], off
	v_add_co_u32_e32 v36, vcc, s6, v14
	s_mov_b32 s6, 0x34000
	s_nop 0
	v_addc_co_u32_e32 v37, vcc, 0, v15, vcc
	global_load_dword v41, v[36:37], off
	v_add_co_u32_e32 v36, vcc, s6, v14
	s_mov_b32 s6, 0x36000
	s_nop 0
	v_addc_co_u32_e32 v37, vcc, 0, v15, vcc
	global_load_dword v42, v[36:37], off
	v_add_co_u32_e32 v36, vcc, s6, v14
	s_mov_b32 s6, 0x38000
	s_nop 0
	v_addc_co_u32_e32 v37, vcc, 0, v15, vcc
	global_load_dword v43, v[36:37], off
	v_add_co_u32_e32 v36, vcc, s6, v14
	s_mov_b32 s6, 0x3a000
	s_nop 0
	v_addc_co_u32_e32 v37, vcc, 0, v15, vcc
	global_load_dword v44, v[36:37], off
	v_add_co_u32_e32 v36, vcc, s6, v14
	s_mov_b32 s6, 0x3c000
	s_nop 0
	v_addc_co_u32_e32 v37, vcc, 0, v15, vcc
	global_load_dword v45, v[36:37], off
	v_add_co_u32_e32 v36, vcc, s6, v14
	s_mov_b32 s6, 0x3e000
	s_nop 0
	v_addc_co_u32_e32 v37, vcc, 0, v15, vcc
	global_load_dword v46, v[36:37], off
	v_add_co_u32_e32 v36, vcc, s6, v14
	s_mov_b32 s6, 0x40000
	s_nop 0
	v_addc_co_u32_e32 v37, vcc, 0, v15, vcc
	global_load_dword v47, v[36:37], off
	v_add_co_u32_e32 v36, vcc, s6, v14
	s_mov_b32 s6, 0x42000
	s_nop 0
	v_addc_co_u32_e32 v37, vcc, 0, v15, vcc
	global_load_dword v59, v[36:37], off
	v_add_co_u32_e32 v36, vcc, s6, v14
	s_mov_b32 s6, 0x44000
	s_nop 0
	v_addc_co_u32_e32 v37, vcc, 0, v15, vcc
	global_load_dword v60, v[36:37], off
	v_add_co_u32_e32 v36, vcc, s6, v14
	s_mov_b32 s6, 0x46000
	s_nop 0
	v_addc_co_u32_e32 v37, vcc, 0, v15, vcc
	global_load_dword v61, v[36:37], off
	v_add_co_u32_e32 v36, vcc, s6, v14
	s_mov_b32 s6, 0x48000
	s_nop 0
	v_addc_co_u32_e32 v37, vcc, 0, v15, vcc
	global_load_dword v62, v[36:37], off
	v_add_co_u32_e32 v36, vcc, s6, v14
	s_mov_b32 s6, 0x4a000
	s_nop 0
	v_addc_co_u32_e32 v37, vcc, 0, v15, vcc
	global_load_dword v63, v[36:37], off
	v_add_co_u32_e32 v36, vcc, s6, v14
	s_mov_b32 s6, 0x4c000
	s_nop 0
	v_addc_co_u32_e32 v37, vcc, 0, v15, vcc
	global_load_dword v64, v[36:37], off
	v_add_co_u32_e32 v36, vcc, s6, v14
	s_mov_b32 s6, 0x4e000
	s_nop 0
	v_addc_co_u32_e32 v37, vcc, 0, v15, vcc
	global_load_dword v65, v[36:37], off
	v_add_co_u32_e32 v36, vcc, s6, v14
	s_mov_b32 s6, 0x50000
	s_nop 0
	v_addc_co_u32_e32 v37, vcc, 0, v15, vcc
	global_load_dword v66, v[36:37], off
	v_add_co_u32_e32 v36, vcc, s6, v14
	s_mov_b32 s6, 0x52000
	s_nop 0
	v_addc_co_u32_e32 v37, vcc, 0, v15, vcc
	global_load_dword v67, v[36:37], off
	v_add_co_u32_e32 v36, vcc, s6, v14
	s_mov_b32 s6, 0x54000
	s_nop 0
	v_addc_co_u32_e32 v37, vcc, 0, v15, vcc
	global_load_dword v68, v[36:37], off
	v_add_co_u32_e32 v36, vcc, s6, v14
	s_mov_b32 s6, 0x56000
	s_nop 0
	v_addc_co_u32_e32 v37, vcc, 0, v15, vcc
	global_load_dword v69, v[36:37], off
	v_add_co_u32_e32 v36, vcc, s6, v14
	s_mov_b32 s6, 0x58000
	s_nop 0
	v_addc_co_u32_e32 v37, vcc, 0, v15, vcc
	global_load_dword v70, v[36:37], off
	v_add_co_u32_e32 v36, vcc, s6, v14
	s_mov_b32 s6, 0x5a000
	s_nop 0
	v_addc_co_u32_e32 v37, vcc, 0, v15, vcc
	global_load_dword v71, v[36:37], off
	v_add_co_u32_e32 v36, vcc, s6, v14
	s_mov_b32 s6, 0x5c000
	s_nop 0
	v_addc_co_u32_e32 v37, vcc, 0, v15, vcc
	global_load_dword v72, v[36:37], off
	v_add_co_u32_e32 v36, vcc, s6, v14
	s_mov_b32 s6, 0x5e000
	s_nop 0
	v_addc_co_u32_e32 v37, vcc, 0, v15, vcc
	global_load_dword v73, v[36:37], off
	v_add_co_u32_e32 v36, vcc, s6, v14
	s_mov_b32 s6, 0x60000
	s_nop 0
	v_addc_co_u32_e32 v37, vcc, 0, v15, vcc
	global_load_dword v74, v[36:37], off
	v_add_co_u32_e32 v36, vcc, s6, v14
	s_mov_b32 s6, 0x64000
	s_nop 0
	v_addc_co_u32_e32 v37, vcc, 0, v15, vcc
	global_load_dword v75, v[36:37], off
	v_add_co_u32_e32 v36, vcc, s21, v14
	s_nop 1
	v_addc_co_u32_e32 v37, vcc, 0, v15, vcc
	global_load_dword v76, v[36:37], off
	v_add_co_u32_e32 v36, vcc, s6, v14
	s_mov_b32 s6, 0x66000
	s_nop 0
	v_addc_co_u32_e32 v37, vcc, 0, v15, vcc
	global_load_dword v77, v[36:37], off
	v_add_co_u32_e32 v36, vcc, s6, v14
	s_mov_b32 s6, 0x68000
	s_nop 0
	v_addc_co_u32_e32 v37, vcc, 0, v15, vcc
	global_load_dword v78, v[36:37], off
	v_add_co_u32_e32 v36, vcc, s6, v14
	s_mov_b32 s6, 0x6a000
	s_nop 0
	v_addc_co_u32_e32 v37, vcc, 0, v15, vcc
	global_load_dword v79, v[36:37], off
	v_add_co_u32_e32 v36, vcc, s6, v14
	s_mov_b32 s6, 0x6c000
	s_nop 0
	v_addc_co_u32_e32 v37, vcc, 0, v15, vcc
	global_load_dword v80, v[36:37], off
	v_add_co_u32_e32 v36, vcc, s6, v14
	s_mov_b32 s6, 0x70000
	s_nop 0
	v_addc_co_u32_e32 v37, vcc, 0, v15, vcc
	global_load_dword v81, v[36:37], off
	v_add_co_u32_e32 v36, vcc, s16, v14
	s_nop 1
	v_addc_co_u32_e32 v37, vcc, 0, v15, vcc
	global_load_dword v82, v[36:37], off
	v_add_co_u32_e32 v36, vcc, s6, v14
	s_mov_b32 s6, 0x72000
	s_nop 0
	v_addc_co_u32_e32 v37, vcc, 0, v15, vcc
	global_load_dword v83, v[36:37], off
	v_add_co_u32_e32 v36, vcc, s6, v14
	s_mov_b32 s6, 0x74000
	s_nop 0
	v_addc_co_u32_e32 v37, vcc, 0, v15, vcc
	global_load_dword v84, v[36:37], off
	v_add_co_u32_e32 v36, vcc, s6, v14
	s_mov_b32 s6, 0x76000
	s_nop 0
	v_addc_co_u32_e32 v37, vcc, 0, v15, vcc
	global_load_dword v85, v[36:37], off
	v_add_co_u32_e32 v36, vcc, s6, v14
	s_mov_b32 s6, 0x78000
	s_nop 0
	v_addc_co_u32_e32 v37, vcc, 0, v15, vcc
	global_load_dword v86, v[36:37], off
	v_add_co_u32_e32 v36, vcc, s6, v14
	s_mov_b32 s6, 0x7c000
	s_nop 0
	v_addc_co_u32_e32 v37, vcc, 0, v15, vcc
	global_load_dword v87, v[36:37], off
	v_add_co_u32_e32 v36, vcc, s89, v14
	s_nop 1
	v_addc_co_u32_e32 v37, vcc, 0, v15, vcc
	global_load_dword v88, v[36:37], off
	v_add_co_u32_e32 v36, vcc, s6, v14
	s_mov_b32 s6, 0x7e000
	s_nop 0
	v_addc_co_u32_e32 v37, vcc, 0, v15, vcc
	v_add_co_u32_e32 v14, vcc, s6, v14
	global_load_dword v36, v[36:37], off
	s_nop 0
	v_addc_co_u32_e32 v15, vcc, 0, v15, vcc
	global_load_dword v14, v[14:15], off
	s_waitcnt vmcnt(0)
	ds_write2_b32 v49, v0, v13 offset1:65
	ds_write2_b32 v49, v16, v17 offset0:130 offset1:195
	v_add_u32_e32 v0, 0x400, v49
	ds_write2_b32 v0, v18, v19 offset0:4 offset1:69
	ds_write2_b32 v0, v20, v21 offset0:134 offset1:199
	v_add_u32_e32 v0, 0x800, v49
	ds_write2_b32 v0, v22, v23 offset0:8 offset1:73
	ds_write2_b32 v0, v24, v25 offset0:138 offset1:203
	v_add_u32_e32 v0, 0xc00, v49
	ds_write2_b32 v0, v26, v27 offset0:12 offset1:77
	ds_write2_b32 v0, v28, v29 offset0:142 offset1:207
	v_add_u32_e32 v0, 0x1000, v49
	ds_write2_b32 v0, v30, v31 offset0:16 offset1:81
	ds_write2_b32 v0, v32, v33 offset0:146 offset1:211
	v_add_u32_e32 v0, 0x1400, v49
	ds_write2_b32 v0, v34, v35 offset0:20 offset1:85
	ds_write2_b32 v0, v38, v39 offset0:150 offset1:215
	v_add_u32_e32 v0, 0x1800, v49
	ds_write2_b32 v0, v40, v41 offset0:24 offset1:89
	ds_write2_b32 v0, v42, v43 offset0:154 offset1:219
	v_add_u32_e32 v0, 0x1c00, v49
	ds_write2_b32 v0, v44, v45 offset0:28 offset1:93
	ds_write2_b32 v0, v46, v47 offset0:158 offset1:223
	v_add_u32_e32 v0, 0x2000, v49
	ds_write2_b32 v0, v59, v60 offset0:32 offset1:97
	ds_write2_b32 v0, v61, v62 offset0:162 offset1:227
	v_add_u32_e32 v0, 0x2400, v49
	ds_write2_b32 v0, v63, v64 offset0:36 offset1:101
	ds_write2_b32 v0, v65, v66 offset0:166 offset1:231
	v_add_u32_e32 v0, 0x2800, v49
	ds_write2_b32 v0, v67, v68 offset0:40 offset1:105
	ds_write2_b32 v0, v69, v70 offset0:170 offset1:235
	v_add_u32_e32 v0, 0x2c00, v49
	ds_write2_b32 v0, v71, v72 offset0:44 offset1:109
	ds_write2_b32 v0, v73, v74 offset0:174 offset1:239
	v_add_u32_e32 v0, 0x3000, v49
	ds_write2_b32 v0, v75, v76 offset0:48 offset1:113
	ds_write2_b32 v0, v77, v78 offset0:178 offset1:243
	v_add_u32_e32 v0, 0x3400, v49
	ds_write2_b32 v0, v79, v80 offset0:52 offset1:117
	ds_write2_b32 v0, v81, v82 offset0:182 offset1:247
	v_add_u32_e32 v0, 0x3800, v49
	s_lshl_b32 s6, s90, 10
	ds_write2_b32 v0, v83, v84 offset0:56 offset1:121
	ds_write2_b32 v0, v85, v86 offset0:186 offset1:251
	v_add_u32_e32 v0, 0x3c00, v49
	s_add_u32 s6, s52, s6
	ds_write2_b32 v0, v87, v88 offset0:60 offset1:125
	ds_write2_b32 v0, v36, v14 offset0:190 offset1:255
	s_addc_u32 s7, s53, 0
	s_lshl_b32 s5, s5, 1
	s_waitcnt lgkmcnt(0)
	s_add_u32 s6, s6, s5
	s_addc_u32 s7, s7, 0
	v_mov_b32_e32 v13, v1
	v_lshl_add_u64 v[14:15], s[6:7], 0, v[12:13]
	ds_read_b32 v0, v51
	ds_read_b32 v13, v51 offset:260
	s_waitcnt lgkmcnt(0)
	v_cvt_pk_bf16_f32 v16, v0, v13
	ds_read_b32 v0, v51 offset:520
	ds_read_b32 v13, v51 offset:780
	s_waitcnt lgkmcnt(1)
	s_waitcnt lgkmcnt(0)
	v_cvt_pk_bf16_f32 v17, v0, v13
	ds_read_b32 v0, v51 offset:1040
	ds_read_b32 v13, v51 offset:1300
	s_waitcnt lgkmcnt(1)
	s_waitcnt lgkmcnt(0)
	v_cvt_pk_bf16_f32 v18, v0, v13
	ds_read_b32 v0, v51 offset:1560
	ds_read_b32 v13, v51 offset:1820
	s_waitcnt lgkmcnt(1)
	s_waitcnt lgkmcnt(0)
	v_cvt_pk_bf16_f32 v19, v0, v13
	v_or_b32_e32 v0, s4, v50
	v_lshlrev_b32_e32 v0, 12, v0
	v_lshl_add_u64 v[20:21], v[14:15], 0, v[0:1]
	flat_store_dwordx4 v[20:21], v[16:19]
	ds_read_b32 v0, v51 offset:32
	ds_read_b32 v13, v51 offset:292
	s_waitcnt lgkmcnt(0)
	v_cvt_pk_bf16_f32 v16, v0, v13
	ds_read_b32 v0, v51 offset:552
	ds_read_b32 v13, v51 offset:812
	s_waitcnt lgkmcnt(0)
	v_cvt_pk_bf16_f32 v17, v0, v13
	ds_read_b32 v0, v51 offset:1072
	ds_read_b32 v13, v51 offset:1332
	s_waitcnt lgkmcnt(0)
	v_cvt_pk_bf16_f32 v18, v0, v13
	ds_read_b32 v0, v51 offset:1592
	ds_read_b32 v13, v51 offset:1852
	s_waitcnt lgkmcnt(0)
	v_cvt_pk_bf16_f32 v19, v0, v13
	v_or_b32_e32 v0, s4, v52
	v_lshlrev_b32_e32 v0, 12, v0
	v_lshl_add_u64 v[20:21], v[14:15], 0, v[0:1]
	flat_store_dwordx4 v[20:21], v[16:19]
	ds_read_b32 v0, v51 offset:64
	ds_read_b32 v13, v51 offset:324
	s_waitcnt lgkmcnt(0)
	v_cvt_pk_bf16_f32 v16, v0, v13
	ds_read_b32 v0, v51 offset:584
	ds_read_b32 v13, v51 offset:844
	s_waitcnt lgkmcnt(0)
	v_cvt_pk_bf16_f32 v17, v0, v13
	ds_read_b32 v0, v51 offset:1104
	ds_read_b32 v13, v51 offset:1364
	s_waitcnt lgkmcnt(0)
	v_cvt_pk_bf16_f32 v18, v0, v13
	ds_read_b32 v0, v51 offset:1624
	ds_read_b32 v13, v51 offset:1884
	s_waitcnt lgkmcnt(0)
	v_cvt_pk_bf16_f32 v19, v0, v13
	v_or_b32_e32 v0, s4, v53
	v_lshlrev_b32_e32 v0, 12, v0
	v_lshl_add_u64 v[20:21], v[14:15], 0, v[0:1]
	flat_store_dwordx4 v[20:21], v[16:19]
	ds_read_b32 v0, v51 offset:96
	ds_read_b32 v13, v51 offset:356
	s_waitcnt lgkmcnt(0)
	v_cvt_pk_bf16_f32 v16, v0, v13
	ds_read_b32 v0, v51 offset:616
	ds_read_b32 v13, v51 offset:876
	s_waitcnt lgkmcnt(0)
	v_cvt_pk_bf16_f32 v17, v0, v13
	ds_read_b32 v0, v51 offset:1136
	ds_read_b32 v13, v51 offset:1396
	s_waitcnt lgkmcnt(0)
	v_cvt_pk_bf16_f32 v18, v0, v13
	ds_read_b32 v0, v51 offset:1656
	ds_read_b32 v13, v51 offset:1916
	s_waitcnt lgkmcnt(0)
	v_cvt_pk_bf16_f32 v19, v0, v13
	v_or_b32_e32 v0, s4, v54
	v_lshlrev_b32_e32 v0, 12, v0
	v_lshl_add_u64 v[20:21], v[14:15], 0, v[0:1]
	flat_store_dwordx4 v[20:21], v[16:19]
	ds_read_b32 v0, v51 offset:128
	ds_read_b32 v13, v51 offset:388
	s_waitcnt lgkmcnt(0)
	v_cvt_pk_bf16_f32 v16, v0, v13
	ds_read_b32 v0, v51 offset:648
	ds_read_b32 v13, v51 offset:908
	s_waitcnt lgkmcnt(0)
	v_cvt_pk_bf16_f32 v17, v0, v13
	ds_read_b32 v0, v51 offset:1168
	ds_read_b32 v13, v51 offset:1428
	s_waitcnt lgkmcnt(0)
	v_cvt_pk_bf16_f32 v18, v0, v13
	ds_read_b32 v0, v51 offset:1688
	ds_read_b32 v13, v51 offset:1948
	s_waitcnt lgkmcnt(0)
	v_cvt_pk_bf16_f32 v19, v0, v13
	v_or_b32_e32 v0, s4, v55
	v_lshlrev_b32_e32 v0, 12, v0
	v_lshl_add_u64 v[20:21], v[14:15], 0, v[0:1]
	flat_store_dwordx4 v[20:21], v[16:19]
	ds_read_b32 v0, v51 offset:160
	ds_read_b32 v13, v51 offset:420
	s_waitcnt lgkmcnt(0)
	v_cvt_pk_bf16_f32 v16, v0, v13
	ds_read_b32 v0, v51 offset:680
	ds_read_b32 v13, v51 offset:940
	s_waitcnt lgkmcnt(0)
	v_cvt_pk_bf16_f32 v17, v0, v13
	ds_read_b32 v0, v51 offset:1200
	ds_read_b32 v13, v51 offset:1460
	s_waitcnt lgkmcnt(0)
	v_cvt_pk_bf16_f32 v18, v0, v13
	ds_read_b32 v0, v51 offset:1720
	ds_read_b32 v13, v51 offset:1980
	s_waitcnt lgkmcnt(0)
	v_cvt_pk_bf16_f32 v19, v0, v13
	v_or_b32_e32 v0, s4, v56
	v_lshlrev_b32_e32 v0, 12, v0
	v_lshl_add_u64 v[20:21], v[14:15], 0, v[0:1]
	flat_store_dwordx4 v[20:21], v[16:19]
	ds_read_b32 v0, v51 offset:192
	ds_read_b32 v13, v51 offset:452
	s_waitcnt lgkmcnt(0)
	v_cvt_pk_bf16_f32 v16, v0, v13
	ds_read_b32 v0, v51 offset:712
	ds_read_b32 v13, v51 offset:972
	s_waitcnt lgkmcnt(0)
	v_cvt_pk_bf16_f32 v17, v0, v13
	ds_read_b32 v0, v51 offset:1232
	ds_read_b32 v13, v51 offset:1492
	s_waitcnt lgkmcnt(0)
	v_cvt_pk_bf16_f32 v18, v0, v13
	ds_read_b32 v0, v51 offset:1752
	ds_read_b32 v13, v51 offset:2012
	s_waitcnt lgkmcnt(0)
	v_cvt_pk_bf16_f32 v19, v0, v13
	v_or_b32_e32 v0, s4, v57
	v_lshlrev_b32_e32 v0, 12, v0
	v_lshl_add_u64 v[20:21], v[14:15], 0, v[0:1]
	flat_store_dwordx4 v[20:21], v[16:19]
	ds_read_b32 v0, v51 offset:224
	ds_read_b32 v13, v51 offset:484
	s_waitcnt lgkmcnt(0)
	v_cvt_pk_bf16_f32 v16, v0, v13
	ds_read_b32 v0, v51 offset:744
	ds_read_b32 v13, v51 offset:1004
	s_waitcnt lgkmcnt(0)
	v_cvt_pk_bf16_f32 v17, v0, v13
	ds_read_b32 v0, v51 offset:1264
	ds_read_b32 v13, v51 offset:1524
	s_waitcnt lgkmcnt(0)
	v_cvt_pk_bf16_f32 v18, v0, v13
	ds_read_b32 v0, v51 offset:1784
	ds_read_b32 v13, v51 offset:2044
	s_waitcnt lgkmcnt(0)
	v_cvt_pk_bf16_f32 v19, v0, v13
	v_or_b32_e32 v0, s4, v58
	v_lshlrev_b32_e32 v0, 12, v0
	v_lshl_add_u64 v[14:15], v[14:15], 0, v[0:1]
	flat_store_dwordx4 v[14:15], v[16:19]
	s_waitcnt lgkmcnt(0)

.LBB0_1050:
	v_mov_b32_e32 v34, 0
	v_mov_b32_e32 v35, 0
	v_mov_b32_e32 v36, 0
	v_mov_b32_e32 v37, 0
	s_and_saveexec_b64 s[46:47], s[42:43]
	s_cbranch_execz .LBB0_1049
	v_or_b32_e32 v36, s7, v57
	v_mov_b64_e32 v[34:35], s[4:5]
	v_mad_i64_i32 v[34:35], s[34:35], v36, s20, v[34:35]
	v_lshl_add_u64 v[34:35], s[38:39], 2, v[34:35]
	v_lshl_add_u64 v[58:59], v[34:35], 0, v[0:1]
	v_lshl_add_u64 v[34:35], v[58:59], 0, s[94:95]
	v_add_co_u32_e32 v58, vcc, 0x12c01000, v58
	flat_load_dwordx4 v[34:37], v[34:35] offset:16
	s_nop 0
	v_addc_co_u32_e32 v59, vcc, 0, v59, vcc
	flat_load_dwordx4 v[58:61], v[58:59] offset:2048
	s_waitcnt vmcnt(0) lgkmcnt(0)
	v_and_b32_sdwa v64, v37, v225 dst_sel:DWORD dst_unused:UNUSED_PAD src0_sel:WORD_1 src1_sel:DWORD
	v_and_b32_sdwa v65, v36, v225 dst_sel:DWORD dst_unused:UNUSED_PAD src0_sel:WORD_1 src1_sel:DWORD
	v_bfe_u32 v63, v58, 16, 1
	v_add3_u32 v62, v36, v65, s23
	v_add3_u32 v37, v37, v64, s23
	v_bfe_u32 v64, v59, 16, 1
	v_cvt_pk_bf16_f32 v36, v34, v35
	v_add3_u32 v34, v58, v63, s23
	v_add3_u32 v58, v59, v64, s23
	v_lshrrev_b32_e32 v34, 16, v34
	v_cvt_pk_bf16_f32 v35, v60, v61
	v_and_or_b32 v34, v58, s15, v34
	v_perm_b32 v37, v37, v62, s22
	s_branch .LBB0_1049

.LBB0_1133:
	v_ashrrev_i32_e32 v98, 9, v99
	v_cmp_eq_u32_e32 vcc, 2, v98
	s_mov_b32 s10, 0xff800000
	s_nop 0
	v_cndmask_b32_e64 v0, 0, 4, vcc
	v_cmp_ne_u32_e32 vcc, 1, v98
	s_nop 1
	v_cndmask_b32_e32 v0, 2, v0, vcc
	v_lshrrev_b32_e64 v2, v0, 32
	v_add_u32_e32 v2, -1, v2
	v_bitop3_b32 v2, v2, v99, 31 bitop3:0x80
	v_cmp_eq_u32_e32 vcc, 3, v98
	v_lshlrev_b32_e32 v3, 7, v2
	v_sub_u32_e32 v2, 0x7f, v3
	v_cndmask_b32_e32 v97, v229, v230, vcc
	v_cmp_le_u32_e32 vcc, v116, v97
	v_cmp_gt_i32_e64 s[46:47], v115, v2
	s_and_b64 vcc, vcc, s[46:47]
	v_cndmask_b32_e32 v56, v231, v56, vcc
	v_cmp_le_u32_e32 vcc, v117, v97
	v_cmp_ge_i32_e64 s[46:47], v115, v2
	s_and_b64 vcc, vcc, s[46:47]
	v_cndmask_b32_e32 v57, v231, v57, vcc
	v_cmp_le_u32_e32 vcc, v119, v97
	v_cmp_gt_i32_e64 s[46:47], v118, v2
	s_and_b64 vcc, vcc, s[46:47]
	v_cndmask_b32_e32 v58, v231, v58, vcc
	v_cmp_le_u32_e32 vcc, v121, v97
	v_cmp_gt_i32_e64 s[46:47], v120, v2
	s_and_b64 vcc, vcc, s[46:47]
	v_cndmask_b32_e32 v59, v231, v59, vcc
	v_cmp_le_u32_e32 vcc, v123, v97
	v_cmp_gt_i32_e64 s[46:47], v122, v2
	s_and_b64 vcc, vcc, s[46:47]
	v_cndmask_b32_e32 v72, v231, v72, vcc
	v_cmp_le_u32_e32 vcc, v124, v97
	v_cmp_ge_i32_e64 s[46:47], v122, v2
	s_and_b64 vcc, vcc, s[46:47]
	v_cndmask_b32_e32 v73, v231, v73, vcc
	v_cmp_le_u32_e32 vcc, v126, v97
	v_cmp_gt_i32_e64 s[46:47], v125, v2
	s_and_b64 vcc, vcc, s[46:47]
	v_cndmask_b32_e32 v74, v231, v74, vcc
	v_cmp_le_u32_e32 vcc, v128, v97
	v_cmp_gt_i32_e64 s[46:47], v127, v2
	s_and_b64 vcc, vcc, s[46:47]
	v_cndmask_b32_e32 v75, v231, v75, vcc
	v_cmp_le_u32_e32 vcc, v130, v97
	v_cmp_gt_i32_e64 s[46:47], v129, v2
	s_and_b64 vcc, vcc, s[46:47]
	v_cndmask_b32_e32 v88, v231, v88, vcc
	v_cmp_le_u32_e32 vcc, v131, v97
	v_cmp_ge_i32_e64 s[46:47], v129, v2
	s_and_b64 vcc, vcc, s[46:47]
	v_cndmask_b32_e32 v89, v231, v89, vcc
	v_cmp_le_u32_e32 vcc, v133, v97
	v_cmp_gt_i32_e64 s[46:47], v132, v2
	s_and_b64 vcc, vcc, s[46:47]
	v_cndmask_b32_e32 v90, v231, v90, vcc
	v_cmp_le_u32_e32 vcc, v135, v97
	v_cmp_gt_i32_e64 s[46:47], v134, v2
	s_and_b64 vcc, vcc, s[46:47]
	v_cndmask_b32_e32 v91, v231, v91, vcc
	v_cmp_le_u32_e32 vcc, v137, v97
	v_cmp_gt_i32_e64 s[46:47], v136, v2
	s_and_b64 vcc, vcc, s[46:47]
	v_cndmask_b32_e32 v84, v231, v84, vcc
	v_cmp_le_u32_e32 vcc, v138, v97
	v_cmp_ge_i32_e64 s[46:47], v136, v2
	s_and_b64 vcc, vcc, s[46:47]
	v_cndmask_b32_e32 v85, v231, v85, vcc
	v_cmp_le_u32_e32 vcc, v140, v97
	v_cmp_gt_i32_e64 s[46:47], v139, v2
	s_and_b64 vcc, vcc, s[46:47]
	v_cndmask_b32_e32 v86, v231, v86, vcc
	v_cmp_le_u32_e32 vcc, v142, v97
	v_cmp_gt_i32_e64 s[46:47], v141, v2
	s_and_b64 vcc, vcc, s[46:47]
	v_cndmask_b32_e32 v87, v231, v87, vcc
	v_cmp_le_u32_e32 vcc, v144, v97
	v_cmp_gt_i32_e64 s[46:47], v143, v2
	s_and_b64 vcc, vcc, s[46:47]
	v_cndmask_b32_e32 v80, v231, v80, vcc
	v_cmp_le_u32_e32 vcc, v145, v97
	v_cmp_ge_i32_e64 s[46:47], v143, v2
	s_and_b64 vcc, vcc, s[46:47]
	v_cndmask_b32_e32 v81, v231, v81, vcc
	v_cmp_le_u32_e32 vcc, v147, v97
	v_cmp_gt_i32_e64 s[46:47], v146, v2
	s_and_b64 vcc, vcc, s[46:47]
	v_cndmask_b32_e32 v82, v231, v82, vcc
	v_cmp_le_u32_e32 vcc, v149, v97
	v_cmp_gt_i32_e64 s[46:47], v148, v2
	s_and_b64 vcc, vcc, s[46:47]
	v_cndmask_b32_e32 v83, v231, v83, vcc
	v_cmp_le_u32_e32 vcc, v151, v97
	v_cmp_gt_i32_e64 s[46:47], v150, v2
	s_and_b64 vcc, vcc, s[46:47]
	v_cndmask_b32_e32 v76, v231, v76, vcc
	v_cmp_le_u32_e32 vcc, v152, v97
	v_cmp_ge_i32_e64 s[46:47], v150, v2
	s_and_b64 vcc, vcc, s[46:47]
	v_cndmask_b32_e32 v77, v231, v77, vcc
	v_cmp_le_u32_e32 vcc, v154, v97
	v_cmp_gt_i32_e64 s[46:47], v153, v2
	s_and_b64 vcc, vcc, s[46:47]
	v_cndmask_b32_e32 v78, v231, v78, vcc
	v_cmp_le_u32_e32 vcc, v156, v97
	v_cmp_gt_i32_e64 s[46:47], v155, v2
	s_and_b64 vcc, vcc, s[46:47]
	v_cndmask_b32_e32 v79, v231, v79, vcc
	v_cmp_le_u32_e32 vcc, v158, v97
	v_cmp_gt_i32_e64 s[46:47], v157, v2
	s_and_b64 vcc, vcc, s[46:47]
	v_cndmask_b32_e32 v64, v231, v64, vcc
	v_cmp_le_u32_e32 vcc, v159, v97
	v_cmp_ge_i32_e64 s[46:47], v157, v2
	s_and_b64 vcc, vcc, s[46:47]
	v_cndmask_b32_e32 v65, v231, v65, vcc
	v_cmp_le_u32_e32 vcc, v161, v97
	v_cmp_gt_i32_e64 s[46:47], v160, v2
	s_and_b64 vcc, vcc, s[46:47]
	v_max3_f32 v200, v56, s10, v57
	v_cndmask_b32_e32 v66, v231, v66, vcc
	v_cmp_le_u32_e32 vcc, v163, v97
	v_cmp_gt_i32_e64 s[46:47], v162, v2
	v_max3_f32 v200, v200, v58, v59
	s_and_b64 vcc, vcc, s[46:47]
	v_max3_f32 v200, v200, v72, v73
	v_cndmask_b32_e32 v67, v231, v67, vcc
	v_cmp_le_u32_e32 vcc, v165, v97
	v_cmp_gt_i32_e64 s[46:47], v164, v2
	v_max3_f32 v200, v200, v74, v75
	s_and_b64 vcc, vcc, s[46:47]
	v_max3_f32 v200, v200, v88, v89
	v_cndmask_b32_e32 v68, v231, v68, vcc
	v_cmp_le_u32_e32 vcc, v166, v97
	v_cmp_ge_i32_e64 s[46:47], v164, v2
	v_max3_f32 v200, v200, v90, v91
	s_and_b64 vcc, vcc, s[46:47]
	v_max3_f32 v200, v200, v84, v85
	v_cndmask_b32_e32 v69, v231, v69, vcc
	v_cmp_le_u32_e32 vcc, v168, v97
	v_cmp_gt_i32_e64 s[46:47], v167, v2
	v_max3_f32 v200, v200, v86, v87
	s_and_b64 vcc, vcc, s[46:47]
	v_max3_f32 v200, v200, v80, v81
	v_cndmask_b32_e32 v70, v231, v70, vcc
	v_cmp_le_u32_e32 vcc, v170, v97
	v_cmp_gt_i32_e64 s[46:47], v169, v2
	v_max3_f32 v200, v200, v82, v83
	s_and_b64 vcc, vcc, s[46:47]
	v_max3_f32 v200, v200, v76, v77
	v_cndmask_b32_e32 v71, v231, v71, vcc
	v_cmp_le_u32_e32 vcc, v172, v97
	v_cmp_gt_i32_e64 s[46:47], v171, v2
	v_max3_f32 v200, v200, v78, v79
	s_and_b64 vcc, vcc, s[46:47]
	v_max3_f32 v200, v200, v64, v65
	v_cndmask_b32_e32 v60, v231, v60, vcc
	v_cmp_le_u32_e32 vcc, v173, v97
	v_cmp_ge_i32_e64 s[46:47], v171, v2
	v_max3_f32 v200, v200, v66, v67
	s_and_b64 vcc, vcc, s[46:47]
	v_max3_f32 v200, v200, v68, v69
	v_cndmask_b32_e32 v201, v231, v61, vcc
	v_cmp_le_u32_e32 vcc, v175, v97
	v_cmp_gt_i32_e64 s[46:47], v174, v2
	v_max3_f32 v200, v200, v70, v71
	s_and_b64 vcc, vcc, s[46:47]
	v_max3_f32 v61, v200, v60, v201
	v_cndmask_b32_e32 v200, v231, v62, vcc
	v_cmp_le_u32_e32 vcc, v177, v97
	v_cmp_gt_i32_e64 s[46:47], v176, v2
	s_and_b64 vcc, vcc, s[46:47]
	v_cndmask_b32_e32 v202, v231, v63, vcc
	v_cmp_le_u32_e32 vcc, v191, v97
	v_cmp_gt_i32_e64 s[46:47], v190, v2
	s_and_b64 vcc, vcc, s[46:47]
	v_cndmask_b32_e32 v203, v231, v52, vcc
	v_cmp_le_u32_e32 vcc, v192, v97
	v_cmp_ge_i32_e64 s[46:47], v190, v2
	s_and_b64 vcc, vcc, s[46:47]
	v_cndmask_b32_e32 v204, v231, v53, vcc
	v_cmp_le_u32_e32 vcc, v194, v97
	v_cmp_gt_i32_e64 s[46:47], v193, v2
	s_and_b64 vcc, vcc, s[46:47]
	v_cndmask_b32_e32 v205, v231, v54, vcc
	v_cmp_le_u32_e32 vcc, v196, v97
	v_cmp_gt_i32_e64 s[46:47], v195, v2
	v_max3_f32 v61, v61, v200, v202
	s_and_b64 vcc, vcc, s[46:47]
	v_max3_f32 v52, v61, v203, v204
	v_cndmask_b32_e32 v55, v231, v55, vcc
	v_and_b32_e32 v53, 64, v226
	v_max3_f32 v2, v52, v205, v55
	v_xor_b32_e32 v52, 16, v226
	v_add_u32_e32 v53, 64, v53
	v_cmp_lt_i32_e32 vcc, v52, v53
	v_sub_u32_e32 v62, 5, v0
	s_lshl_b32 s10, s8, 1
	v_cndmask_b32_e32 v52, v226, v52, vcc
	v_lshlrev_b32_e32 v54, 2, v52
	ds_bpermute_b32 v52, v54, v2
	s_add_i32 s10, s10, s12
	v_add_u32_e32 v3, v3, v103
	s_waitcnt lgkmcnt(0)
	v_max_f32_e32 v52, v52, v52
	v_max_f32_e32 v2, v2, v52
	v_xor_b32_e32 v52, 32, v226
	v_cmp_lt_i32_e32 vcc, v52, v53
	v_and_b32_e32 v53, 31, v99
	v_lshrrev_b32_e32 v53, v62, v53
	v_cndmask_b32_e32 v52, v226, v52, vcc
	v_lshlrev_b32_e32 v52, 2, v52
	ds_bpermute_b32 v61, v52, v2
	v_cmp_ne_u32_e32 vcc, 3, v98
	s_waitcnt lgkmcnt(0)
	v_max_f32_e32 v61, v61, v61
	v_max_f32_e32 v2, v2, v61
	v_sub_f32_e32 v62, v72, v2
	v_sub_f32_e32 v72, v74, v2
	v_sub_f32_e32 v74, v88, v2
	v_mul_f32_e32 v74, 0x3fb8aa3b, v74
	v_exp_f32_e32 v88, v74
	v_sub_f32_e32 v74, v89, v2
	v_mul_f32_e32 v74, 0x3fb8aa3b, v74
	v_exp_f32_e32 v89, v74
	v_sub_f32_e32 v74, v90, v2
	v_mul_f32_e32 v74, 0x3fb8aa3b, v74
	v_exp_f32_e32 v90, v74
	v_sub_f32_e32 v74, v91, v2
	v_sub_f32_e32 v56, v56, v2
	v_mul_f32_e32 v74, 0x3fb8aa3b, v74
	v_mul_f32_e32 v56, 0x3fb8aa3b, v56
	v_sub_f32_e32 v57, v57, v2
	v_exp_f32_e32 v91, v74
	v_sub_f32_e32 v74, v84, v2
	v_exp_f32_e32 v56, v56
	v_mul_f32_e32 v57, 0x3fb8aa3b, v57
	v_sub_f32_e32 v58, v58, v2
	v_mul_f32_e32 v74, 0x3fb8aa3b, v74
	v_exp_f32_e32 v57, v57
	v_mul_f32_e32 v58, 0x3fb8aa3b, v58
	v_sub_f32_e32 v59, v59, v2
	v_exp_f32_e32 v84, v74
	v_sub_f32_e32 v74, v85, v2
	v_exp_f32_e32 v58, v58
	v_mul_f32_e32 v59, 0x3fb8aa3b, v59
	v_mul_f32_e32 v74, 0x3fb8aa3b, v74
	v_exp_f32_e32 v59, v59
	v_mul_f32_e32 v62, 0x3fb8aa3b, v62
	v_sub_f32_e32 v63, v73, v2
	v_exp_f32_e32 v85, v74
	v_sub_f32_e32 v74, v86, v2
	v_add_f32_e32 v61, 0, v56
	v_exp_f32_e32 v62, v62
	v_mul_f32_e32 v63, 0x3fb8aa3b, v63
	v_mul_f32_e32 v74, 0x3fb8aa3b, v74
	v_add_f32_e32 v61, v57, v61
	v_exp_f32_e32 v63, v63
	v_mul_f32_e32 v72, 0x3fb8aa3b, v72
	v_sub_f32_e32 v73, v75, v2
	v_exp_f32_e32 v86, v74
	v_sub_f32_e32 v74, v87, v2
	v_add_f32_e32 v61, v58, v61
	v_exp_f32_e32 v72, v72
	v_mul_f32_e32 v73, 0x3fb8aa3b, v73
	v_mul_f32_e32 v74, 0x3fb8aa3b, v74
	v_add_f32_e32 v61, v59, v61
	v_exp_f32_e32 v73, v73
	v_exp_f32_e32 v87, v74
	v_sub_f32_e32 v74, v80, v2
	v_add_f32_e32 v61, v62, v61
	v_mul_f32_e32 v74, 0x3fb8aa3b, v74
	v_add_f32_e32 v61, v63, v61
	v_exp_f32_e32 v97, v74
	v_sub_f32_e32 v74, v81, v2
	v_add_f32_e32 v61, v72, v61
	v_mul_f32_e32 v74, 0x3fb8aa3b, v74
	v_add_f32_e32 v61, v73, v61
	v_exp_f32_e32 v206, v74
	v_sub_f32_e32 v74, v82, v2
	v_add_f32_e32 v61, v88, v61
	v_mul_f32_e32 v74, 0x3fb8aa3b, v74
	v_add_f32_e32 v61, v89, v61
	v_exp_f32_e32 v207, v74
	v_sub_f32_e32 v74, v83, v2
	v_add_f32_e32 v61, v90, v61
	v_mul_f32_e32 v74, 0x3fb8aa3b, v74
	v_add_f32_e32 v61, v91, v61
	v_exp_f32_e32 v208, v74
	v_sub_f32_e32 v74, v76, v2
	v_add_f32_e32 v61, v84, v61
	v_mul_f32_e32 v74, 0x3fb8aa3b, v74
	v_sub_f32_e32 v64, v64, v2
	v_add_f32_e32 v61, v85, v61
	v_exp_f32_e32 v209, v74
	v_sub_f32_e32 v74, v77, v2
	v_mul_f32_e32 v64, 0x3fb8aa3b, v64
	v_add_f32_e32 v61, v86, v61
	v_mul_f32_e32 v74, 0x3fb8aa3b, v74
	v_exp_f32_e32 v213, v64
	v_sub_f32_e32 v64, v65, v2
	v_add_f32_e32 v61, v87, v61
	v_exp_f32_e32 v210, v74
	v_sub_f32_e32 v74, v78, v2
	v_mul_f32_e32 v64, 0x3fb8aa3b, v64
	v_add_f32_e32 v61, v97, v61
	v_mul_f32_e32 v74, 0x3fb8aa3b, v74
	v_exp_f32_e32 v214, v64
	v_sub_f32_e32 v64, v66, v2
	v_add_f32_e32 v61, v206, v61
	v_exp_f32_e32 v211, v74
	v_sub_f32_e32 v74, v79, v2
	v_mul_f32_e32 v64, 0x3fb8aa3b, v64
	v_add_f32_e32 v61, v207, v61
	v_mul_f32_e32 v74, 0x3fb8aa3b, v74
	v_exp_f32_e32 v215, v64
	v_sub_f32_e32 v64, v67, v2
	v_add_f32_e32 v61, v208, v61
	v_exp_f32_e32 v212, v74
	v_mul_f32_e32 v64, 0x3fb8aa3b, v64
	v_add_f32_e32 v61, v209, v61
	v_exp_f32_e32 v216, v64
	v_sub_f32_e32 v64, v68, v2
	v_add_f32_e32 v61, v210, v61
	v_mul_f32_e32 v64, 0x3fb8aa3b, v64
	v_sub_f32_e32 v60, v60, v2
	v_add_f32_e32 v61, v211, v61
	v_exp_f32_e32 v217, v64
	v_sub_f32_e32 v64, v69, v2
	v_mul_f32_e32 v60, 0x3fb8aa3b, v60
	v_add_f32_e32 v61, v212, v61
	v_mul_f32_e32 v64, 0x3fb8aa3b, v64
	v_exp_f32_e32 v221, v60
	v_add_f32_e32 v61, v213, v61
	v_exp_f32_e32 v218, v64
	v_sub_f32_e32 v64, v70, v2
	v_add_f32_e32 v61, v214, v61
	v_mul_f32_e32 v64, 0x3fb8aa3b, v64
	v_add_f32_e32 v61, v215, v61
	v_exp_f32_e32 v219, v64
	v_cvt_pk_bf16_f32 v56, v56, v57
	v_add_f32_e32 v61, v216, v61
	v_add_f32_e32 v61, v217, v61
	v_cvt_pk_bf16_f32 v57, v58, v59
	v_add_f32_e32 v61, v218, v61
	v_lshl_add_u32 v74, v92, 1, s10
	v_and_b32_sdwa v64, v72, v225 dst_sel:DWORD dst_unused:UNUSED_PAD src0_sel:WORD_1 src1_sel:DWORD
	v_add_f32_e32 v76, v219, v61
	v_sub_f32_e32 v61, v71, v2
	v_cvt_pk_bf16_f32 v58, v62, v63
	v_and_b32_sdwa v59, v73, v225 dst_sel:DWORD dst_unused:UNUSED_PAD src0_sel:WORD_1 src1_sel:DWORD
	v_lshl_add_u32 v68, v197, 1, v74
	v_add3_u32 v69, v72, v64, s23
	v_lshl_add_u32 v72, v198, 1, v74
	v_mul_f32_e32 v61, 0x3fb8aa3b, v61
	v_add_u32_e32 v232, 0x9000, v68
	v_add_u32_e32 v233, 0xb000, v68
	v_add3_u32 v59, v73, v59, s23
	v_add_u32_e32 v234, 0xd000, v68
	v_add_u32_e32 v235, 0x9000, v72
	v_exp_f32_e32 v220, v61
	ds_read2_b64 v[60:63], v232 offset1:4
	ds_read2_b64 v[64:67], v233 offset0:32 offset1:36
	v_perm_b32 v59, v59, v69, s22
	ds_read2_b64 v[68:71], v234 offset0:64 offset1:68
	ds_read2_b64 v[72:75], v235 offset1:4
	v_add_f32_e32 v76, v220, v76
	v_add_f32_e32 v236, v221, v76
	v_sub_f32_e32 v76, v201, v2
	s_waitcnt lgkmcnt(0)
	v_mfma_f32_16x16x32_bf16 v[60:63], v[60:63], v[56:59], 0
	v_mul_f32_e32 v76, 0x3fb8aa3b, v76
	v_exp_f32_e32 v201, v76
	ds_read2_b64 v[76:79], v232 offset0:8 offset1:12
	v_mfma_f32_16x16x32_bf16 v[64:67], v[64:67], v[56:59], 0
	v_sub_f32_e32 v200, v200, v2
	ds_read2_b64 v[80:83], v233 offset0:40 offset1:44
	v_sub_f32_e32 v55, v55, v2
	v_mfma_f32_16x16x32_bf16 v[68:71], v[68:71], v[56:59], 0
	v_mul_f32_e32 v55, 0x3fb8aa3b, v55
	v_exp_f32_e32 v55, v55
	s_movk_i32 s10, 0x1000
	v_mfma_f32_16x16x32_bf16 v[56:59], v[72:75], v[56:59], 0
	v_cvt_pk_bf16_f32 v72, v88, v89
	v_cvt_pk_bf16_f32 v73, v90, v91
	v_cvt_pk_bf16_f32 v74, v84, v85
	v_cvt_pk_bf16_f32 v75, v86, v87
	ds_read2_b64 v[84:87], v234 offset0:72 offset1:76
	v_sub_f32_e32 v91, v203, v2
	s_waitcnt lgkmcnt(0)
	v_mfma_f32_16x16x32_bf16 v[60:63], v[76:79], v[72:75], v[60:63]
	v_mul_f32_e32 v76, 0x3fb8aa3b, v200
	v_exp_f32_e32 v88, v76
	ds_read2_b64 v[76:79], v235 offset0:8 offset1:12
	v_mfma_f32_16x16x32_bf16 v[64:67], v[80:83], v[72:75], v[64:67]
	v_add_f32_e32 v80, v201, v236
	v_add_f32_e32 v89, v88, v80
	v_sub_f32_e32 v80, v202, v2
	v_mfma_f32_16x16x32_bf16 v[68:71], v[84:87], v[72:75], v[68:71]
	v_mul_f32_e32 v80, 0x3fb8aa3b, v80
	s_waitcnt lgkmcnt(0)
	v_mfma_f32_16x16x32_bf16 v[56:59], v[76:79], v[72:75], v[56:59]
	ds_read2_b64 v[76:79], v232 offset0:16 offset1:20
	v_cvt_pk_bf16_f32 v72, v97, v206
	v_cvt_pk_bf16_f32 v73, v207, v208
	v_cvt_pk_bf16_f32 v74, v209, v210
	v_cvt_pk_bf16_f32 v75, v211, v212
	v_exp_f32_e32 v90, v80
	ds_read2_b64 v[80:83], v233 offset0:48 offset1:52
	s_waitcnt lgkmcnt(0)
	v_mfma_f32_16x16x32_bf16 v[60:63], v[76:79], v[72:75], v[60:63]
	v_mul_f32_e32 v76, 0x3fb8aa3b, v91
	ds_read2_b64 v[84:87], v234 offset0:80 offset1:84
	v_exp_f32_e32 v91, v76
	ds_read2_b64 v[76:79], v235 offset0:16 offset1:20
	v_mfma_f32_16x16x32_bf16 v[64:67], v[80:83], v[72:75], v[64:67]
	v_sub_f32_e32 v200, v205, v2
	v_add_f32_e32 v80, v90, v89
	v_add_f32_e32 v89, v91, v80
	s_waitcnt lgkmcnt(0)
	v_mfma_f32_16x16x32_bf16 v[68:71], v[84:87], v[72:75], v[68:71]
	v_sub_f32_e32 v80, v204, v2
	v_mfma_f32_16x16x32_bf16 v[56:59], v[76:79], v[72:75], v[56:59]
	ds_read2_b64 v[76:79], v232 offset0:24 offset1:28
	v_cvt_pk_bf16_f32 v72, v213, v214
	v_cvt_pk_bf16_f32 v73, v215, v216
	v_cvt_pk_bf16_f32 v74, v217, v218
	v_cvt_pk_bf16_f32 v75, v219, v220
	v_mul_f32_e32 v80, 0x3fb8aa3b, v80
	ds_read2_b64 v[84:87], v234 offset0:88 offset1:92
	s_waitcnt lgkmcnt(0)
	v_mfma_f32_16x16x32_bf16 v[60:63], v[76:79], v[72:75], v[60:63]
	v_mul_f32_e32 v76, 0x3fb8aa3b, v200
	v_exp_f32_e32 v200, v76
	ds_read2_b64 v[76:79], v235 offset0:24 offset1:28
	v_exp_f32_e32 v97, v80
	ds_read2_b64 v[80:83], v233 offset0:56 offset1:60
	s_waitcnt lgkmcnt(0)
	v_mfma_f32_16x16x32_bf16 v[76:79], v[76:79], v[72:75], v[56:59]
	s_nop 2
	v_mfma_f32_16x16x32_bf16 v[68:71], v[84:87], v[72:75], v[68:71]
	v_cvt_pk_bf16_f32 v84, v221, v201
	v_mfma_f32_16x16x32_bf16 v[80:83], v[80:83], v[72:75], v[64:67]
	v_cvt_pk_bf16_f32 v85, v88, v90
	v_add_f32_e32 v64, v97, v89
	v_add_f32_e32 v64, v200, v64
	v_add_f32_e32 v204, v55, v64
	ds_read2_b64 v[56:59], v232 offset0:32 offset1:36
	ds_read2_b64 v[72:75], v233 offset0:64 offset1:68
	v_cvt_pk_bf16_f32 v86, v91, v97
	v_and_b32_sdwa v65, v200, v225 dst_sel:DWORD dst_unused:UNUSED_PAD src0_sel:WORD_1 src1_sel:DWORD
	v_add3_u32 v65, v200, v65, s23
	ds_read2_b64 v[88:91], v234 offset0:96 offset1:100
	ds_read2_b64 v[200:203], v235 offset0:32 offset1:36
	ds_bpermute_b32 v54, v54, v204
	v_and_b32_sdwa v64, v55, v225 dst_sel:DWORD dst_unused:UNUSED_PAD src0_sel:WORD_1 src1_sel:DWORD
	v_add3_u32 v55, v55, v64, s23
	v_perm_b32 v87, v55, v65, s22
	v_lshlrev_b32_e32 v55, 4, v99
	v_and_or_b32 v53, v55, s10, v53
	s_waitcnt lgkmcnt(0)
	v_mfma_f32_16x16x32_bf16 v[64:67], v[56:59], v[84:87], v[60:63]
	v_mfma_f32_16x16x32_bf16 v[60:63], v[72:75], v[84:87], v[80:83]
	v_add_f32_e32 v73, v204, v54
	ds_bpermute_b32 v75, v52, v73
	v_lshl_add_u32 v72, v3, v0, v53
	v_mfma_f32_16x16x32_bf16 v[56:59], v[88:91], v[84:87], v[68:71]
	v_bfe_u32 v74, v99, 5, 3
	v_lshlrev_b32_e32 v0, 7, v74
	s_waitcnt lgkmcnt(0)
	v_add_f32_e32 v3, v73, v75
	v_mfma_f32_16x16x32_bf16 v[52:55], v[200:203], v[84:87], v[76:79]
	v_ashrrev_i32_e32 v73, 31, v72
	v_lshlrev_b32_e32 v70, 1, v92
	s_and_saveexec_b64 s[34:35], vcc
	s_xor_b64 s[46:47], exec, s[34:35]
	s_cbranch_execz .LBB0_1138
	v_ashrrev_i32_e32 v99, 31, v98
	v_lshlrev_b64 v[68:69], 13, v[98:99]
	v_lshl_add_u64 v[68:69], v[68:69], 0, v[72:73]
	v_lshlrev_b64 v[72:73], 10, v[68:69]
	v_lshl_add_u64 v[72:73], s[52:53], 0, v[72:73]
	v_lshl_add_u64 v[72:73], v[72:73], 0, v[0:1]
	v_bfe_u32 v0, v64, 16, 1
	v_add3_u32 v0, v64, v0, s23
	v_bfe_u32 v64, v65, 16, 1
	v_lshrrev_b32_e32 v0, 16, v0
	v_add3_u32 v64, v65, v64, s23
	v_and_or_b32 v64, v64, s15, v0
	v_cvt_pk_bf16_f32 v65, v66, v67
	v_bfe_u32 v0, v60, 16, 1
	v_add3_u32 v0, v60, v0, s23
	v_bfe_u32 v60, v61, 16, 1
	v_lshrrev_b32_e32 v0, 16, v0
	v_add3_u32 v60, v61, v60, s23
	v_and_or_b32 v60, v60, s15, v0
	v_cvt_pk_bf16_f32 v61, v62, v63
	v_bfe_u32 v0, v56, 16, 1
	v_add3_u32 v0, v56, v0, s23
	v_bfe_u32 v56, v57, 16, 1
	v_lshrrev_b32_e32 v0, 16, v0
	v_add3_u32 v56, v57, v56, s23
	v_and_or_b32 v56, v56, s15, v0
	v_cvt_pk_bf16_f32 v57, v58, v59
	v_bfe_u32 v0, v52, 16, 1
	v_add3_u32 v0, v52, v0, s23
	v_bfe_u32 v52, v53, 16, 1
	v_lshrrev_b32_e32 v0, 16, v0
	v_add3_u32 v52, v53, v52, s23
	v_and_or_b32 v52, v52, s15, v0
	v_mov_b32_e32 v71, v1
	v_lshl_add_u64 v[70:71], v[72:73], 0, v[70:71]
	v_cvt_pk_bf16_f32 v53, v54, v55
	flat_store_dwordx2 v[70:71], v[64:65] nt
	flat_store_dwordx2 v[70:71], v[60:61] offset:32 nt
	flat_store_dwordx2 v[70:71], v[56:57] offset:64 nt
	flat_store_dwordx2 v[70:71], v[52:53] offset:96 nt
	s_and_saveexec_b64 s[58:59], s[42:43]
	s_cbranch_execz .LBB0_1136
	v_lshlrev_b64 v[52:53], 6, v[68:69]
	v_lshl_add_u64 v[52:53], s[54:55], 0, v[52:53]
	v_lshlrev_b32_e32 v0, 3, v74
	v_lshl_add_u64 v[52:53], v[52:53], 0, v[0:1]
	flat_store_dwordx2 v[52:53], v[2:3]

.LBB0_1139:
	v_cmp_gt_f32_e32 vcc, s19, v3
	s_mov_b32 s10, 0x3f317217
	v_readlane_b32 s64, v252, 16
	v_cndmask_b32_e64 v68, 0, 32, vcc
	v_ldexp_f32 v68, v3, v68
	v_log_f32_e32 v68, v68
	v_readlane_b32 s66, v252, 18
	v_readlane_b32 s67, v252, 19
	v_readlane_b32 s65, v252, 17
	v_mul_f32_e32 v69, 0x3f317217, v68
	v_fma_f32 v69, v68, s10, -v69
	v_fmac_f32_e32 v69, 0x3377d1cf, v68
	s_mov_b32 s10, 0x7f800000
	v_fmac_f32_e32 v69, 0x3f317217, v68
	v_cmp_lt_f32_e64 s[46:47], |v68|, s10
	s_mov_b32 s10, 0x23c00000
	v_readlane_b32 s68, v252, 20
	v_cndmask_b32_e64 v68, v68, v69, s[46:47]
	v_cndmask_b32_e32 v69, 0, v228, vcc
	v_sub_f32_e32 v68, v68, v69
	v_add_f32_e32 v2, v2, v68
	v_or_b32_e32 v68, s90, v74
	v_mov_b32_e32 v69, v1
	v_lshl_add_u64 v[68:69], v[68:69], 2, s[66:67]
	global_load_dword v68, v[68:69], off
	v_readlane_b32 s69, v252, 21
	v_readlane_b32 s70, v252, 22
	v_readlane_b32 s71, v252, 23
	v_readlane_b32 s72, v252, 24
	v_readlane_b32 s73, v252, 25
	v_readlane_b32 s74, v252, 26
	v_readlane_b32 s75, v252, 27
	v_readlane_b32 s76, v252, 28
	v_readlane_b32 s77, v252, 29
	v_readlane_b32 s78, v252, 30
	v_readlane_b32 s79, v252, 31
	s_waitcnt vmcnt(0)
	v_sub_f32_e32 v2, v68, v2
	v_mul_f32_e32 v2, 0x3fb8aa3b, v2
	v_exp_f32_e32 v2, v2
	s_nop 0
	v_add_f32_e32 v2, 1.0, v2
	s_nop 0
	v_rcp_f32_e32 v2, v2
	s_nop 0
	v_div_scale_f32 v68, s[34:35], v3, v3, v2
	v_rcp_f32_e32 v69, v68
	s_mov_b64 s[34:35], 0x23c00c00
	v_fma_f32 v71, -v68, v69, 1.0
	v_fmac_f32_e32 v69, v71, v69
	v_div_scale_f32 v71, vcc, v2, v3, v2
	v_mul_f32_e32 v74, v71, v69
	v_fma_f32 v75, -v68, v74, v71
	v_fmac_f32_e32 v74, v75, v69
	v_fma_f32 v68, -v68, v74, v71
	v_div_fmas_f32 v68, v68, v69, v74
	v_div_fixup_f32 v68, v68, v3, v2
	v_lshlrev_b64 v[2:3], 12, v[72:73]
	v_mov_b32_e32 v73, v66
	v_mov_b32_e32 v66, v65
	v_mov_b32_e32 v72, v64
	v_pk_mul_f32 v[64:65], v[66:67], v[68:69] op_sel_hi:[1,0]
	v_lshl_add_u64 v[2:3], s[0:1], 0, v[2:3]
	v_pk_mul_f32 v[72:73], v[72:73], v[68:69] op_sel_hi:[1,0]
	v_and_b32_sdwa v69, v64, v225 dst_sel:DWORD dst_unused:UNUSED_PAD src0_sel:WORD_1 src1_sel:DWORD
	v_lshl_add_u64 v[2:3], v[2:3], 0, v[0:1]
	v_mov_b32_e32 v71, v1
	v_and_b32_sdwa v66, v72, v225 dst_sel:DWORD dst_unused:UNUSED_PAD src0_sel:WORD_1 src1_sel:DWORD
	v_add3_u32 v64, v64, v69, s23
	v_lshl_add_u64 v[70:71], v[2:3], 0, v[70:71]
	v_add3_u32 v66, v72, v66, s23
	v_and_b32_e32 v64, 0xffff0000, v64
	v_or_b32_sdwa v64, v64, v66 dst_sel:DWORD dst_unused:UNUSED_PAD src0_sel:DWORD src1_sel:WORD_1
	v_add_co_u32_e32 v66, vcc, s10, v70
	v_cvt_pk_bf16_f32 v65, v73, v65
	s_nop 0
	v_addc_co_u32_e32 v67, vcc, 0, v71, vcc
	flat_store_dwordx2 v[66:67], v[64:65] offset:3072 nt
	v_mov_b32_e32 v64, v60
	v_mov_b32_e32 v65, v62
	v_pk_mul_f32 v[64:65], v[64:65], v[68:69] op_sel_hi:[1,0]
	v_mov_b32_e32 v62, v61
	v_pk_mul_f32 v[60:61], v[62:63], v[68:69] op_sel_hi:[1,0]
	v_and_b32_sdwa v62, v64, v225 dst_sel:DWORD dst_unused:UNUSED_PAD src0_sel:WORD_1 src1_sel:DWORD
	v_add3_u32 v62, v64, v62, s23
	v_and_b32_sdwa v64, v60, v225 dst_sel:DWORD dst_unused:UNUSED_PAD src0_sel:WORD_1 src1_sel:DWORD
	v_add3_u32 v60, v60, v64, s23
	v_and_b32_e32 v60, 0xffff0000, v60
	v_lshl_add_u64 v[2:3], v[70:71], 0, s[34:35]
	v_cvt_pk_bf16_f32 v61, v65, v61
	v_or_b32_sdwa v60, v60, v62 dst_sel:DWORD dst_unused:UNUSED_PAD src0_sel:DWORD src1_sel:WORD_1
	flat_store_dwordx2 v[2:3], v[60:61] offset:32 nt
	v_mov_b32_e32 v60, v56
	v_mov_b32_e32 v61, v58
	v_pk_mul_f32 v[60:61], v[60:61], v[68:69] op_sel_hi:[1,0]
	v_mov_b32_e32 v58, v57
	v_pk_mul_f32 v[56:57], v[58:59], v[68:69] op_sel_hi:[1,0]
	v_and_b32_sdwa v58, v60, v225 dst_sel:DWORD dst_unused:UNUSED_PAD src0_sel:WORD_1 src1_sel:DWORD
	v_add3_u32 v58, v60, v58, s23
	v_and_b32_sdwa v60, v56, v225 dst_sel:DWORD dst_unused:UNUSED_PAD src0_sel:WORD_1 src1_sel:DWORD
	v_add3_u32 v56, v56, v60, s23
	v_and_b32_e32 v56, 0xffff0000, v56
	v_cvt_pk_bf16_f32 v57, v61, v57
	v_or_b32_sdwa v56, v56, v58 dst_sel:DWORD dst_unused:UNUSED_PAD src0_sel:DWORD src1_sel:WORD_1
	flat_store_dwordx2 v[2:3], v[56:57] offset:64 nt
	v_mov_b32_e32 v56, v52
	v_mov_b32_e32 v57, v54
	v_pk_mul_f32 v[56:57], v[56:57], v[68:69] op_sel_hi:[1,0]
	v_mov_b32_e32 v54, v53
	v_pk_mul_f32 v[52:53], v[54:55], v[68:69] op_sel_hi:[1,0]
	v_and_b32_sdwa v54, v56, v225 dst_sel:DWORD dst_unused:UNUSED_PAD src0_sel:WORD_1 src1_sel:DWORD
	v_add3_u32 v54, v56, v54, s23
	v_and_b32_sdwa v56, v52, v225 dst_sel:DWORD dst_unused:UNUSED_PAD src0_sel:WORD_1 src1_sel:DWORD
	v_add3_u32 v52, v52, v56, s23
	v_and_b32_e32 v52, 0xffff0000, v52
	v_cvt_pk_bf16_f32 v53, v57, v53
	v_or_b32_sdwa v52, v52, v54 dst_sel:DWORD dst_unused:UNUSED_PAD src0_sel:DWORD src1_sel:WORD_1
	flat_store_dwordx2 v[2:3], v[52:53] offset:96 nt
	s_or_b64 exec, exec, s[58:59]
	s_xor_b32 s10, s11, 1
	s_and_saveexec_b64 s[46:47], s[44:45]
	s_cbranch_execz .LBB0_1120

.LBB0_1197:
	s_add_i32 s6, s12, s44
	v_mov_b64_e32 v[202:203], s[0:1]
	v_or_b32_e32 v206, 16, v92
	s_lshl_b32 s100, s6, 6
	s_mov_b32 s101, 0
	v_mad_i64_i32 v[204:205], vcc, v92, s20, v[202:203]
	v_mad_i64_i32 v[206:207], vcc, v206, s20, v[202:203]
	v_lshl_add_u64 v[204:205], v[204:205], 0, s[100:101]
	v_lshl_add_u64 v[206:207], v[206:207], 0, s[100:101]
	v_lshl_add_u64 v[204:205], v[204:205], 0, s[94:95]
	v_lshl_add_u64 v[206:207], v[206:207], 0, s[94:95]
	v_lshl_add_u64 v[208:209], v[204:205], 0, v[0:1]
	v_lshl_add_u64 v[210:211], v[206:207], 0, v[0:1]
	global_load_dwordx4 v[140:143], v[208:209], off
	global_load_dwordx4 v[152:155], v[210:211], off
	v_mov_b32_e32 v208, v82
	v_mov_b32_e32 v209, 0
	s_mov_b64 s[100:101], exec
	s_and_b64 exec, exec, s[42:43]
	v_lshl_add_u64 v[210:211], v[204:205], 0, v[208:209]
	global_load_dwordx4 v[132:135], v[210:211], off
	global_load_dwordx4 v[136:139], v[210:211], off offset:16
	v_lshl_add_u64 v[210:211], v[206:207], 0, v[208:209]
	global_load_dwordx4 v[144:147], v[210:211], off
	global_load_dwordx4 v[148:151], v[210:211], off offset:16
	s_mov_b64 exec, s[100:101]
	s_ashr_i32 s7, s6, 31
	s_lshl_b64 s[4:5], s[6:7], 16
	v_lshl_add_u64 v[2:3], v[94:95], 0, s[4:5]
	s_add_i32 s4, s6, s60
	s_ashr_i32 s5, s4, 31
	s_lshl_b64 s[34:35], s[4:5], 10
	flat_load_dwordx2 v[96:97], v[2:3]
	v_lshl_add_u64 v[2:3], v[66:67], 0, s[34:35]
	flat_load_dwordx4 v[126:129], v[2:3]
	s_lshl_b64 s[34:35], s[4:5], 12
	v_lshl_add_u64 v[4:5], v[68:69], 0, s[34:35]
	flat_load_dwordx4 v[8:11], v[4:5]
	flat_load_dwordx4 v[12:15], v[4:5] offset:512
	flat_load_dwordx4 v[16:19], v[4:5] offset:1024
	flat_load_dwordx4 v[20:23], v[4:5] offset:1536
	flat_load_dwordx4 v[24:27], v[4:5] offset:2048
	flat_load_dwordx4 v[28:31], v[4:5] offset:2560
	flat_load_dwordx4 v[32:35], v[4:5] offset:3072
	flat_load_dwordx4 v[36:39], v[4:5] offset:3584
	v_lshl_or_b32 v4, v64, 8, s34
	v_mov_b32_e32 v5, s35
	v_lshl_add_u64 v[56:57], v[70:71], 0, v[4:5]
	v_lshl_add_u64 v[58:59], v[72:73], 0, v[4:5]
	global_load_dwordx4 v[48:51], v[56:57], off
	global_load_dwordx4 v[40:43], v[56:57], off offset:16
	global_load_dwordx4 v[4:7], v[58:59], off offset:16
	global_load_dwordx4 v[44:47], v[58:59], off
	s_lshl_b64 s[4:5], s[4:5], 6
	v_lshl_add_u32 v81, s6, 5, v65
	s_mov_b64 s[38:39], -1
	s_mov_b32 s18, 0
	s_waitcnt vmcnt(0) lgkmcnt(0)
	v_mov_b32_e32 v2, v126
	v_mov_b32_e32 v3, v127
	v_cndmask_b32_e64 v11, v11, 0, s[40:41]
	v_cndmask_b32_e64 v10, v10, 0, s[40:41]
	v_cndmask_b32_e64 v9, v9, 0, s[40:41]
	v_cndmask_b32_e64 v8, v8, 0, s[40:41]
	v_cndmask_b32_e64 v15, v15, 0, s[40:41]
	v_cndmask_b32_e64 v14, v14, 0, s[40:41]
	v_cndmask_b32_e64 v13, v13, 0, s[40:41]
	v_cndmask_b32_e64 v12, v12, 0, s[40:41]
	v_cndmask_b32_e64 v19, v19, 0, s[40:41]
	v_xor_b32_e32 v83, 0x80000000, v4
	v_xor_b32_e32 v60, 0x80000000, v44
	v_xor_b32_e32 v61, 0x80000000, v45
	v_xor_b32_e32 v62, 0x80000000, v46
	v_xor_b32_e32 v63, 0x80000000, v47
	v_xor_b32_e32 v93, 0x80000000, v5
	v_xor_b32_e32 v98, 0x80000000, v6
	v_xor_b32_e32 v99, 0x80000000, v7
	global_load_dwordx4 v[52:55], v[56:57], off offset:128
	global_load_dwordx4 v[44:47], v[56:57], off offset:144
	global_load_dwordx4 v[4:7], v[58:59], off offset:144
	s_nop 0
	global_load_dwordx4 v[56:59], v[58:59], off offset:128
	v_cvt_pk_bf16_f32 v43, v42, v43
	v_cvt_pk_bf16_f32 v42, v40, v41
	v_cvt_pk_bf16_f32 v41, v50, v51
	v_cvt_pk_bf16_f32 v40, v48, v49
	v_cndmask_b32_e64 v18, v18, 0, s[40:41]
	v_cndmask_b32_e64 v17, v17, 0, s[40:41]
	v_cndmask_b32_e64 v16, v16, 0, s[40:41]
	v_cndmask_b32_e64 v23, v23, 0, s[40:41]
	v_cndmask_b32_e64 v22, v22, 0, s[40:41]
	v_cndmask_b32_e64 v21, v21, 0, s[40:41]
	v_cndmask_b32_e64 v20, v20, 0, s[40:41]
	v_cndmask_b32_e64 v27, v27, 0, s[40:41]
	v_cndmask_b32_e64 v26, v26, 0, s[40:41]
	v_cndmask_b32_e64 v25, v25, 0, s[40:41]
	v_cndmask_b32_e64 v24, v24, 0, s[40:41]
	v_cndmask_b32_e64 v31, v31, 0, s[40:41]
	v_cndmask_b32_e64 v30, v30, 0, s[40:41]
	v_cndmask_b32_e64 v29, v29, 0, s[40:41]
	v_cndmask_b32_e64 v28, v28, 0, s[40:41]
	v_cndmask_b32_e64 v35, v35, 0, s[40:41]
	v_cndmask_b32_e64 v34, v34, 0, s[40:41]
	v_cndmask_b32_e64 v33, v33, 0, s[40:41]
	v_cndmask_b32_e64 v32, v32, 0, s[40:41]
	v_cndmask_b32_e64 v39, v39, 0, s[40:41]
	v_cndmask_b32_e64 v38, v38, 0, s[40:41]
	v_cndmask_b32_e64 v37, v37, 0, s[40:41]
	v_cndmask_b32_e64 v36, v36, 0, s[40:41]
	s_waitcnt vmcnt(3)
	s_waitcnt vmcnt(2)
	s_waitcnt vmcnt(1)
	v_xor_b32_e32 v114, 0x80000000, v4
	v_xor_b32_e32 v115, 0x80000000, v5
	v_lshl_add_u64 v[4:5], v[74:75], 0, s[4:5]
	v_xor_b32_e32 v116, 0x80000000, v6
	v_xor_b32_e32 v117, 0x80000000, v7
	global_load_dwordx4 v[4:7], v[4:5], off
	v_cvt_pk_bf16_f32 v47, v46, v47
	v_cvt_pk_bf16_f32 v46, v44, v45
	v_cvt_pk_bf16_f32 v45, v54, v55
	v_cvt_pk_bf16_f32 v44, v52, v53
	s_waitcnt vmcnt(1)
	v_xor_b32_e32 v56, 0x80000000, v56
	v_xor_b32_e32 v57, 0x80000000, v57
	v_xor_b32_e32 v58, 0x80000000, v58
	v_xor_b32_e32 v59, 0x80000000, v59
	v_cvt_pk_bf16_f32 v51, v98, v99
	v_cvt_pk_bf16_f32 v50, v83, v93
	v_cvt_pk_bf16_f32 v49, v62, v63
	v_cvt_pk_bf16_f32 v48, v60, v61
	v_bfe_u32 v60, v59, 16, 1
	v_bfe_u32 v61, v58, 16, 1
	s_lshl_b32 s4, s6, 4
	v_add3_u32 v58, v58, v61, s23
	v_add3_u32 v59, v59, v60, s23
	s_ashr_i32 s5, s4, 31
	v_cvt_pk_bf16_f32 v55, v116, v117
	v_cvt_pk_bf16_f32 v54, v114, v115
	v_perm_b32 v53, v59, v58, s22
	v_cvt_pk_bf16_f32 v52, v56, v57
	v_pk_mov_b32 v[98:99], v[2:3], v[2:3] op_sel:[1,0]
	s_branch .LBB0_1199
.LBB0_1198:
	s_or_b64 exec, exec, s[6:7]
	v_mfma_f32_16x16x32_bf16 v[114:117], v[60:63], v[8:11], 0
	v_lshl_add_u64 v[56:57], v[56:57], 0, v[0:1]
	v_add_u32_e32 v83, 0x400, v101
	v_mov_b32_e32 v56, v140
	v_mov_b32_e32 v57, v141
	v_mov_b32_e32 v58, v142
	v_mov_b32_e32 v59, v143
	v_mfma_f32_16x16x32_bf16 v[118:121], v[60:63], v[12:15], 0
	s_nop 7
	ds_write2_b32 v101, v114, v118 offset1:16
	ds_write2_b32 v101, v115, v119 offset0:132 offset1:148
	ds_write2_b32 v83, v116, v120 offset0:8 offset1:24
	ds_write2_b32 v83, v117, v121 offset0:140 offset1:156
	v_mfma_f32_16x16x32_bf16 v[114:117], v[60:63], v[16:19], 0
	s_nop 7
	ds_write_b32 v101, v114 offset:128
	ds_write_b32 v101, v115 offset:656
	ds_write_b32 v101, v116 offset:1184
	ds_write_b32 v101, v117 offset:1712
	v_mfma_f32_16x16x32_bf16 v[114:117], v[60:63], v[20:23], 0
	v_add_u32_e32 v93, 0x400, v103
	s_xor_b64 s[6:7], s[38:39], -1
	s_mov_b64 s[38:39], 0
	v_mfma_f32_16x16x32_bf16 v[118:121], v[60:63], v[28:31], 0
	s_nop 3
	ds_write2_b32 v103, v114, v115 offset1:132
	ds_write2_b32 v93, v116, v117 offset0:8 offset1:140
	v_mfma_f32_16x16x32_bf16 v[114:117], v[60:63], v[24:27], 0
	s_nop 7
	ds_write2_b32 v101, v114, v118 offset0:64 offset1:80
	ds_write2_b32 v101, v115, v119 offset0:196 offset1:212
	ds_write2_b32 v83, v116, v120 offset0:72 offset1:88
	ds_write2_b32 v83, v117, v121 offset0:204 offset1:220
	v_mfma_f32_16x16x32_bf16 v[114:117], v[60:63], v[32:35], 0
	s_nop 7
	ds_write_b32 v101, v114 offset:384
	ds_write_b32 v101, v115 offset:912
	ds_write_b32 v101, v116 offset:1440
	ds_write_b32 v101, v117 offset:1968
	v_mfma_f32_16x16x32_bf16 v[60:63], v[60:63], v[36:39], 0
	s_nop 7
	ds_write2_b32 v104, v60, v61 offset1:132
	v_add_u32_e32 v60, 0x400, v104
	ds_write2_b32 v60, v62, v63 offset0:8 offset1:140
	s_waitcnt lgkmcnt(0)
	v_add_u32_e32 v164, 16, v105
	v_add_u32_e32 v165, 32, v105
	v_add_u32_e32 v166, 48, v105
	v_add_u32_e32 v167, 64, v105
	v_add_u32_e32 v168, 80, v105
	v_add_u32_e32 v169, 96, v105
	v_add_u32_e32 v170, 112, v105
	v_add_u32_e32 v171, 128, v105
	v_add_u32_e32 v172, 144, v105
	v_add_u32_e32 v173, 160, v105
	v_add_u32_e32 v174, 176, v105
	v_add_u32_e32 v175, 192, v105
	v_add_u32_e32 v176, 208, v105
	v_add_u32_e32 v177, 224, v105
	v_add_u32_e32 v218, 240, v105
	ds_read2st64_b32 v[156:157], v105 offset0:0 offset1:1
	ds_read2st64_b32 v[158:159], v164 offset0:2 offset1:3
	ds_read2st64_b32 v[160:161], v165 offset0:4 offset1:5
	ds_read2st64_b32 v[162:163], v166 offset0:6 offset1:7
	s_waitcnt lgkmcnt(3)
	v_mul_f32_e32 v212, v3, v97
	v_fma_f32 v212, v2, v96, -v212
	v_mul_f32_e32 v213, v2, v97
	v_fmac_f32_e32 v213, v3, v96
	v_add_f32_e32 v214, v212, v156
	v_add_f32_e32 v215, v213, v157
	ds_read2st64_b32 v[156:157], v167 offset0:8 offset1:9
	ds_write2st64_b32 v105, v214, v215 offset0:0 offset1:1
	s_waitcnt lgkmcnt(4)
	v_mul_f32_e32 v212, v3, v215
	v_fma_f32 v212, v2, v214, -v212
	v_mul_f32_e32 v213, v2, v215
	v_fmac_f32_e32 v213, v3, v214
	v_add_f32_e32 v216, v212, v158
	v_add_f32_e32 v217, v213, v159
	ds_read2st64_b32 v[158:159], v168 offset0:10 offset1:11
	ds_write2st64_b32 v164, v216, v217 offset0:2 offset1:3
	s_waitcnt lgkmcnt(5)
	v_mul_f32_e32 v212, v3, v217
	v_fma_f32 v212, v2, v216, -v212
	v_mul_f32_e32 v213, v2, v217
	v_fmac_f32_e32 v213, v3, v216
	v_add_f32_e32 v214, v212, v160
	v_add_f32_e32 v215, v213, v161
	ds_read2st64_b32 v[160:161], v169 offset0:12 offset1:13
	ds_write2st64_b32 v165, v214, v215 offset0:4 offset1:5
	s_waitcnt lgkmcnt(6)
	v_mul_f32_e32 v212, v3, v215
	v_fma_f32 v212, v2, v214, -v212
	v_mul_f32_e32 v213, v2, v215
	v_fmac_f32_e32 v213, v3, v214
	v_add_f32_e32 v216, v212, v162
	v_add_f32_e32 v217, v213, v163
	ds_read2st64_b32 v[162:163], v170 offset0:14 offset1:15
	ds_write2st64_b32 v166, v216, v217 offset0:6 offset1:7
	s_waitcnt lgkmcnt(7)
	v_mul_f32_e32 v212, v3, v217
	v_fma_f32 v212, v2, v216, -v212
	v_mul_f32_e32 v213, v2, v217
	v_fmac_f32_e32 v213, v3, v216
	v_add_f32_e32 v214, v212, v156
	v_add_f32_e32 v215, v213, v157
	ds_read2st64_b32 v[156:157], v171 offset0:16 offset1:17
	ds_write2st64_b32 v167, v214, v215 offset0:8 offset1:9
	s_waitcnt lgkmcnt(7)
	v_mul_f32_e32 v212, v3, v215
	v_fma_f32 v212, v2, v214, -v212
	v_mul_f32_e32 v213, v2, v215
	v_fmac_f32_e32 v213, v3, v214
	v_add_f32_e32 v216, v212, v158
	v_add_f32_e32 v217, v213, v159
	ds_read2st64_b32 v[158:159], v172 offset0:18 offset1:19
	ds_write2st64_b32 v168, v216, v217 offset0:10 offset1:11
	s_waitcnt lgkmcnt(7)
	v_mul_f32_e32 v212, v3, v217
	v_fma_f32 v212, v2, v216, -v212
	v_mul_f32_e32 v213, v2, v217
	v_fmac_f32_e32 v213, v3, v216
	v_add_f32_e32 v214, v212, v160
	v_add_f32_e32 v215, v213, v161
	ds_read2st64_b32 v[160:161], v173 offset0:20 offset1:21
	ds_write2st64_b32 v169, v214, v215 offset0:12 offset1:13
	s_waitcnt lgkmcnt(7)
	v_mul_f32_e32 v212, v3, v215
	v_fma_f32 v212, v2, v214, -v212
	v_mul_f32_e32 v213, v2, v215
	v_fmac_f32_e32 v213, v3, v214
	v_add_f32_e32 v216, v212, v162
	v_add_f32_e32 v217, v213, v163
	ds_read2st64_b32 v[162:163], v174 offset0:22 offset1:23
	ds_write2st64_b32 v170, v216, v217 offset0:14 offset1:15
	s_waitcnt lgkmcnt(7)
	v_mul_f32_e32 v212, v3, v217
	v_fma_f32 v212, v2, v216, -v212
	v_mul_f32_e32 v213, v2, v217
	v_fmac_f32_e32 v213, v3, v216
	v_add_f32_e32 v214, v212, v156
	v_add_f32_e32 v215, v213, v157
	ds_read2st64_b32 v[156:157], v175 offset0:24 offset1:25
	ds_write2st64_b32 v171, v214, v215 offset0:16 offset1:17
	s_waitcnt lgkmcnt(7)
	v_mul_f32_e32 v212, v3, v215
	v_fma_f32 v212, v2, v214, -v212
	v_mul_f32_e32 v213, v2, v215
	v_fmac_f32_e32 v213, v3, v214
	v_add_f32_e32 v216, v212, v158
	v_add_f32_e32 v217, v213, v159
	ds_read2st64_b32 v[158:159], v176 offset0:26 offset1:27
	ds_write2st64_b32 v172, v216, v217 offset0:18 offset1:19
	s_waitcnt lgkmcnt(7)
	v_mul_f32_e32 v212, v3, v217
	v_fma_f32 v212, v2, v216, -v212
	v_mul_f32_e32 v213, v2, v217
	v_fmac_f32_e32 v213, v3, v216
	v_add_f32_e32 v214, v212, v160
	v_add_f32_e32 v215, v213, v161
	ds_read2st64_b32 v[160:161], v177 offset0:28 offset1:29
	ds_write2st64_b32 v173, v214, v215 offset0:20 offset1:21
	s_waitcnt lgkmcnt(7)
	v_mul_f32_e32 v212, v3, v215
	v_fma_f32 v212, v2, v214, -v212
	v_mul_f32_e32 v213, v2, v215
	v_fmac_f32_e32 v213, v3, v214
	v_add_f32_e32 v216, v212, v162
	v_add_f32_e32 v217, v213, v163
	ds_read2st64_b32 v[162:163], v218 offset0:30 offset1:31
	ds_write2st64_b32 v174, v216, v217 offset0:22 offset1:23
	s_waitcnt lgkmcnt(7)
	v_mul_f32_e32 v212, v3, v217
	v_fma_f32 v212, v2, v216, -v212
	v_mul_f32_e32 v213, v2, v217
	v_fmac_f32_e32 v213, v3, v216
	v_add_f32_e32 v214, v212, v156
	v_add_f32_e32 v215, v213, v157
	ds_write2st64_b32 v175, v214, v215 offset0:24 offset1:25
	s_waitcnt lgkmcnt(6)
	v_mul_f32_e32 v212, v3, v215
	v_fma_f32 v212, v2, v214, -v212
	v_mul_f32_e32 v213, v2, v215
	v_fmac_f32_e32 v213, v3, v214
	v_add_f32_e32 v216, v212, v158
	v_add_f32_e32 v217, v213, v159
	ds_write2st64_b32 v176, v216, v217 offset0:26 offset1:27
	s_waitcnt lgkmcnt(5)
	v_mul_f32_e32 v212, v3, v217
	v_fma_f32 v212, v2, v216, -v212
	v_mul_f32_e32 v213, v2, v217
	v_fmac_f32_e32 v213, v3, v216
	v_add_f32_e32 v214, v212, v160
	v_add_f32_e32 v215, v213, v161
	ds_write2st64_b32 v177, v214, v215 offset0:28 offset1:29
	s_waitcnt lgkmcnt(4)
	v_mul_f32_e32 v212, v3, v215
	v_fma_f32 v212, v2, v214, -v212
	v_mul_f32_e32 v213, v2, v215
	v_fmac_f32_e32 v213, v3, v214
	v_add_f32_e32 v96, v212, v162
	v_add_f32_e32 v97, v213, v163
	ds_write2st64_b32 v218, v96, v97 offset0:30 offset1:31
	s_waitcnt lgkmcnt(0)
	ds_read_b128 v[60:63], v100
	ds_read_b128 v[114:117], v100 offset:16
	s_waitcnt lgkmcnt(0)
	v_cvt_pk_bf16_f32 v60, v60, v61
	v_cvt_pk_bf16_f32 v61, v62, v63
	v_cvt_pk_bf16_f32 v62, v114, v115
	v_and_b32_sdwa v63, v117, v225 dst_sel:DWORD dst_unused:UNUSED_PAD src0_sel:WORD_1 src1_sel:DWORD
	v_and_b32_sdwa v83, v116, v225 dst_sel:DWORD dst_unused:UNUSED_PAD src0_sel:WORD_1 src1_sel:DWORD
	v_add3_u32 v83, v116, v83, s23
	v_add3_u32 v63, v117, v63, s23
	ds_read_b128 v[114:117], v100 offset:128
	ds_read_b128 v[118:121], v100 offset:144
	v_perm_b32 v63, v63, v83, s22
	s_waitcnt lgkmcnt(0)
	v_cvt_pk_bf16_f32 v114, v114, v115
	v_cvt_pk_bf16_f32 v115, v116, v117
	v_mfma_f32_16x16x32_bf16 v[60:63], v[40:43], v[60:63], 0
	v_cvt_pk_bf16_f32 v116, v118, v119
	v_cvt_pk_bf16_f32 v117, v120, v121
	s_nop 1
	v_mfma_f32_16x16x32_bf16 v[60:63], v[44:47], v[114:117], v[60:63]
	ds_read_b128 v[114:117], v100 offset:256
	ds_read_b128 v[118:121], v100 offset:272
	s_waitcnt lgkmcnt(0)
	v_cvt_pk_bf16_f32 v114, v114, v115
	v_cvt_pk_bf16_f32 v115, v116, v117
	v_cvt_pk_bf16_f32 v116, v118, v119
	v_cvt_pk_bf16_f32 v117, v120, v121
	s_nop 1
	v_mfma_f32_16x16x32_bf16 v[60:63], v[48:51], v[114:117], v[60:63]
	ds_read_b128 v[114:117], v100 offset:384
	ds_read_b128 v[118:121], v100 offset:400
	s_waitcnt lgkmcnt(0)
	s_waitcnt lgkmcnt(0)
	v_cvt_pk_bf16_f32 v114, v114, v115
	v_cvt_pk_bf16_f32 v115, v116, v117
	v_cvt_pk_bf16_f32 v116, v118, v119
	v_cvt_pk_bf16_f32 v117, v120, v121
	s_nop 1
	v_mfma_f32_16x16x32_bf16 v[60:63], v[52:55], v[114:117], v[60:63]
	s_waitcnt vmcnt(0)
	s_nop 6
	v_pk_fma_f32 v[56:57], v[4:5], v[56:57], v[60:61]
	v_pk_fma_f32 v[58:59], v[6:7], v[58:59], v[62:63]
	v_mul_f32_e32 v62, 0x3d372713, v56
	v_mul_f32_e32 v83, 0x3d372713, v57
	v_mul_f32_e32 v62, v56, v62
	v_mul_f32_e32 v83, v57, v83
	v_mov_b32_e32 v60, v56
	v_fma_f32 v56, v56, v62, v56
	v_mov_b32_e32 v62, v57
	v_fmac_f32_e32 v57, v57, v83
	v_mul_f32_e32 v57, 0x3f4c422a, v57
	v_add_f32_e32 v57, v57, v57
	v_mul_f32_e32 v57, 0x3fb8aa3b, v57
	v_exp_f32_e32 v114, v57
	v_mul_f32_e32 v57, 0x3d372713, v58
	v_mul_f32_e32 v57, v58, v57
	v_fma_f32 v57, v58, v57, v58
	v_mul_f32_e32 v56, 0x3f4c422a, v56
	v_mul_f32_e32 v57, 0x3f4c422a, v57
	v_add_f32_e32 v56, v56, v56
	v_add_f32_e32 v57, v57, v57
	v_mul_f32_e32 v56, 0x3fb8aa3b, v56
	v_mul_f32_e32 v57, 0x3fb8aa3b, v57
	v_exp_f32_e32 v56, v56
	v_exp_f32_e32 v57, v57
	v_mov_b32_e32 v61, v58
	v_mov_b32_e32 v63, v59
	v_pk_mul_f32 v[60:61], v[60:61], 0.5 op_sel_hi:[1,0]
	v_pk_add_f32 v[56:57], v[56:57], 1.0 op_sel_hi:[1,0]
	s_nop 0
	s_nop 0
	v_rcp_f32_e32 v57, v57
	s_nop 0
	s_nop 0
	v_rcp_f32_e32 v56, v56
	s_nop 0
	v_mul_f32_e32 v58, 0x3d372713, v59
	v_mul_f32_e32 v58, v59, v58
	v_fmac_f32_e32 v59, v59, v58
	v_mul_f32_e32 v58, 0x3f4c422a, v59
	v_add_f32_e32 v58, v58, v58
	v_mul_f32_e32 v58, 0x3fb8aa3b, v58
	v_exp_f32_e32 v115, v58
	v_pk_fma_f32 v[56:57], v[56:57], 2.0, 1.0 op_sel_hi:[1,0,0] neg_lo:[1,0,0] neg_hi:[1,0,0]
	v_pk_add_f32 v[58:59], v[114:115], 1.0 op_sel_hi:[1,0]
	v_pk_add_f32 v[56:57], v[56:57], 1.0 op_sel_hi:[1,0]
	s_nop 0
	v_pk_mul_f32 v[56:57], v[60:61], v[56:57]
	s_nop 0
	v_rcp_f32_e32 v59, v59
	s_nop 0
	s_nop 0
	v_rcp_f32_e32 v58, v58
	s_nop 0
	v_pk_fma_f32 v[58:59], v[58:59], 2.0, 1.0 op_sel_hi:[1,0,0] neg_lo:[1,0,0] neg_hi:[1,0,0]
	v_pk_mul_f32 v[60:61], v[62:63], 0.5 op_sel_hi:[1,0]
	v_pk_add_f32 v[58:59], v[58:59], 1.0 op_sel_hi:[1,0]
	s_andn2_b64 vcc, exec, s[6:7]
	v_pk_mul_f32 v[58:59], v[60:61], v[58:59]
	v_cvt_pk_bf16_f32 v56, v56, v58
	v_or_b32_e32 v58, s18, v64
	v_cvt_pk_bf16_f32 v57, v57, v59
	v_mad_u32_u24 v58, v58, s17, v81
	s_mov_b32 s18, 16
	ds_write_b64 v58, v[56:57]
	s_cbranch_vccz .LBB0_1196
	v_mov_b32_e32 v132, v144
	v_mov_b32_e32 v133, v145
	v_mov_b32_e32 v134, v146
	v_mov_b32_e32 v135, v147
	v_mov_b32_e32 v136, v148
	v_mov_b32_e32 v137, v149
	v_mov_b32_e32 v138, v150
	v_mov_b32_e32 v139, v151
	v_mov_b32_e32 v140, v152
	v_mov_b32_e32 v141, v153
	v_mov_b32_e32 v142, v154
	v_mov_b32_e32 v143, v155
.LBB0_1199:
	v_or_b32_e32 v58, s18, v92
	v_mov_b64_e32 v[56:57], s[0:1]
	v_mad_i64_i32 v[56:57], s[6:7], v58, s20, v[56:57]
	v_lshl_add_u64 v[56:57], s[4:5], 2, v[56:57]
	v_lshl_add_u64 v[56:57], v[56:57], 0, s[94:95]
	v_mov_b32_e32 v60, 0
	v_mov_b32_e32 v61, 0
	v_mov_b32_e32 v62, 0
	v_mov_b32_e32 v63, 0
	s_and_saveexec_b64 s[6:7], s[42:43]
	s_cbranch_execz .LBB0_1198
	v_mov_b32_e32 v83, v1
	v_lshl_add_u64 v[62:63], v[56:57], 0, v[82:83]
	v_mov_b32_e32 v58, v132
	v_mov_b32_e32 v59, v133
	v_mov_b32_e32 v60, v134
	v_mov_b32_e32 v61, v135
	v_mov_b32_e32 v114, v136
	v_mov_b32_e32 v115, v137
	v_mov_b32_e32 v116, v138
	v_mov_b32_e32 v117, v139
	s_waitcnt vmcnt(0) lgkmcnt(0)
	v_bfe_u32 v62, v58, 16, 1
	v_bfe_u32 v63, v59, 16, 1
	v_add3_u32 v58, v58, v62, s23
	v_add3_u32 v59, v59, v63, s23
	v_lshrrev_b32_e32 v58, 16, v58
	v_cvt_pk_bf16_f32 v61, v60, v61
	v_cvt_pk_bf16_f32 v62, v114, v115
	v_and_or_b32 v60, v59, s15, v58
	v_cvt_pk_bf16_f32 v63, v116, v117
	s_branch .LBB0_1198

.LBB0_1202:
	s_mov_b64 s[4:5], 0x300000
	v_lshl_add_u64 v[30:31], v[78:79], 0, s[4:5]
	s_mov_b64 s[4:5], 0x304000
	v_lshl_add_u64 v[32:33], v[78:79], 0, s[4:5]
	s_mov_b64 s[4:5], 0x308000
	v_lshl_add_u64 v[56:57], v[78:79], 0, s[4:5]
	s_mov_b64 s[4:5], 0x30c000
	v_lshl_add_u64 v[42:43], v[78:79], 0, s[4:5]
	global_load_dwordx4 v[126:129], v[30:31], off
	global_load_dwordx4 v[130:133], v[32:33], off
	global_load_dwordx4 v[134:137], v[56:57], off
	global_load_dwordx4 v[138:141], v[42:43], off
	global_load_dwordx4 v[142:145], v[30:31], off offset:64
	global_load_dwordx4 v[146:149], v[32:33], off offset:64
	global_load_dwordx4 v[150:153], v[56:57], off offset:64
	global_load_dwordx4 v[154:157], v[42:43], off offset:64
	global_load_dwordx4 v[158:161], v[30:31], off offset:128
	global_load_dwordx4 v[162:165], v[32:33], off offset:128
	global_load_dwordx4 v[166:169], v[56:57], off offset:128
	global_load_dwordx4 v[170:173], v[42:43], off offset:128
	global_load_dwordx4 v[174:177], v[30:31], off offset:192
	global_load_dwordx4 v[190:193], v[32:33], off offset:192
	global_load_dwordx4 v[194:197], v[56:57], off offset:192
	global_load_dwordx4 v[198:201], v[42:43], off offset:192
	global_load_dwordx4 v[202:205], v[76:77], off
	global_load_dwordx4 v[206:209], v[76:77], off offset:64
	global_load_dwordx4 v[210:213], v[76:77], off offset:128
	global_load_dwordx4 v[214:217], v[76:77], off offset:192
	ds_read_b128 v[38:41], v112
	ds_read_b128 v[44:47], v112 offset:16640
	ds_read_b128 v[48:51], v112 offset:64
	ds_read_b128 v[52:55], v112 offset:16704
	s_waitcnt vmcnt(16) lgkmcnt(2)
	v_mfma_f32_16x16x32_bf16 v[34:37], v[126:129], v[38:41], v[34:37]
	v_mfma_f32_16x16x32_bf16 v[26:29], v[126:129], v[44:47], v[26:29]
	v_mfma_f32_16x16x32_bf16 v[22:25], v[130:133], v[38:41], v[22:25]
	v_mfma_f32_16x16x32_bf16 v[18:21], v[130:133], v[44:47], v[18:21]
	v_mfma_f32_16x16x32_bf16 v[14:17], v[134:137], v[38:41], v[14:17]
	v_mfma_f32_16x16x32_bf16 v[10:13], v[134:137], v[44:47], v[10:13]
	v_mfma_f32_16x16x32_bf16 v[6:9], v[138:141], v[38:41], v[6:9]
	v_mfma_f32_16x16x32_bf16 v[2:5], v[138:141], v[44:47], v[2:5]
	global_load_dwordx4 v[126:129], v[30:31], off offset:256
	global_load_dwordx4 v[130:133], v[32:33], off offset:256
	global_load_dwordx4 v[134:137], v[56:57], off offset:256
	global_load_dwordx4 v[138:141], v[42:43], off offset:256
	ds_read_b128 v[38:41], v112 offset:128
	ds_read_b128 v[44:47], v112 offset:16768
	s_waitcnt vmcnt(16) lgkmcnt(2)
	v_mfma_f32_16x16x32_bf16 v[34:37], v[142:145], v[48:51], v[34:37]
	v_mfma_f32_16x16x32_bf16 v[26:29], v[142:145], v[52:55], v[26:29]
	v_mfma_f32_16x16x32_bf16 v[22:25], v[146:149], v[48:51], v[22:25]
	v_mfma_f32_16x16x32_bf16 v[18:21], v[146:149], v[52:55], v[18:21]
	v_mfma_f32_16x16x32_bf16 v[14:17], v[150:153], v[48:51], v[14:17]
	v_mfma_f32_16x16x32_bf16 v[10:13], v[150:153], v[52:55], v[10:13]
	v_mfma_f32_16x16x32_bf16 v[6:9], v[154:157], v[48:51], v[6:9]
	v_mfma_f32_16x16x32_bf16 v[2:5], v[154:157], v[52:55], v[2:5]
	global_load_dwordx4 v[142:145], v[30:31], off offset:320
	global_load_dwordx4 v[146:149], v[32:33], off offset:320
	global_load_dwordx4 v[150:153], v[56:57], off offset:320
	global_load_dwordx4 v[154:157], v[42:43], off offset:320
	ds_read_b128 v[48:51], v112 offset:192
	ds_read_b128 v[52:55], v112 offset:16832
	s_waitcnt vmcnt(16) lgkmcnt(2)
	v_mfma_f32_16x16x32_bf16 v[34:37], v[158:161], v[38:41], v[34:37]
	v_mfma_f32_16x16x32_bf16 v[26:29], v[158:161], v[44:47], v[26:29]
	v_mfma_f32_16x16x32_bf16 v[22:25], v[162:165], v[38:41], v[22:25]
	v_mfma_f32_16x16x32_bf16 v[18:21], v[162:165], v[44:47], v[18:21]
	v_mfma_f32_16x16x32_bf16 v[14:17], v[166:169], v[38:41], v[14:17]
	v_mfma_f32_16x16x32_bf16 v[10:13], v[166:169], v[44:47], v[10:13]
	v_mfma_f32_16x16x32_bf16 v[6:9], v[170:173], v[38:41], v[6:9]
	v_mfma_f32_16x16x32_bf16 v[2:5], v[170:173], v[44:47], v[2:5]
	global_load_dwordx4 v[158:161], v[30:31], off offset:384
	global_load_dwordx4 v[162:165], v[32:33], off offset:384
	global_load_dwordx4 v[166:169], v[56:57], off offset:384
	global_load_dwordx4 v[170:173], v[42:43], off offset:384
	ds_read_b128 v[38:41], v112 offset:256
	ds_read_b128 v[44:47], v112 offset:16896
	s_waitcnt vmcnt(16) lgkmcnt(2)
	v_mfma_f32_16x16x32_bf16 v[34:37], v[174:177], v[48:51], v[34:37]
	v_mfma_f32_16x16x32_bf16 v[26:29], v[174:177], v[52:55], v[26:29]
	v_mfma_f32_16x16x32_bf16 v[22:25], v[190:193], v[48:51], v[22:25]
	v_mfma_f32_16x16x32_bf16 v[18:21], v[190:193], v[52:55], v[18:21]
	v_mfma_f32_16x16x32_bf16 v[14:17], v[194:197], v[48:51], v[14:17]
	v_mfma_f32_16x16x32_bf16 v[10:13], v[194:197], v[52:55], v[10:13]
	v_mfma_f32_16x16x32_bf16 v[6:9], v[198:201], v[48:51], v[6:9]
	v_mfma_f32_16x16x32_bf16 v[2:5], v[198:201], v[52:55], v[2:5]
	global_load_dwordx4 v[174:177], v[30:31], off offset:448
	global_load_dwordx4 v[190:193], v[32:33], off offset:448
	global_load_dwordx4 v[194:197], v[56:57], off offset:448
	global_load_dwordx4 v[198:201], v[42:43], off offset:448
	ds_read_b128 v[48:51], v112 offset:320
	ds_read_b128 v[52:55], v112 offset:16960
	s_waitcnt vmcnt(12) lgkmcnt(2)
	v_mfma_f32_16x16x32_bf16 v[34:37], v[126:129], v[38:41], v[34:37]
	v_mfma_f32_16x16x32_bf16 v[26:29], v[126:129], v[44:47], v[26:29]
	v_mfma_f32_16x16x32_bf16 v[22:25], v[130:133], v[38:41], v[22:25]
	v_mfma_f32_16x16x32_bf16 v[18:21], v[130:133], v[44:47], v[18:21]
	v_mfma_f32_16x16x32_bf16 v[14:17], v[134:137], v[38:41], v[14:17]
	v_mfma_f32_16x16x32_bf16 v[10:13], v[134:137], v[44:47], v[10:13]
	v_mfma_f32_16x16x32_bf16 v[6:9], v[138:141], v[38:41], v[6:9]
	v_mfma_f32_16x16x32_bf16 v[2:5], v[138:141], v[44:47], v[2:5]
	global_load_dwordx4 v[126:129], v[30:31], off offset:512
	global_load_dwordx4 v[130:133], v[32:33], off offset:512
	global_load_dwordx4 v[134:137], v[56:57], off offset:512
	global_load_dwordx4 v[138:141], v[42:43], off offset:512
	ds_read_b128 v[38:41], v112 offset:384
	ds_read_b128 v[44:47], v112 offset:17024
	s_waitcnt vmcnt(12) lgkmcnt(2)
	v_mfma_f32_16x16x32_bf16 v[34:37], v[142:145], v[48:51], v[34:37]
	v_mfma_f32_16x16x32_bf16 v[26:29], v[142:145], v[52:55], v[26:29]
	v_mfma_f32_16x16x32_bf16 v[22:25], v[146:149], v[48:51], v[22:25]
	v_mfma_f32_16x16x32_bf16 v[18:21], v[146:149], v[52:55], v[18:21]
	v_mfma_f32_16x16x32_bf16 v[14:17], v[150:153], v[48:51], v[14:17]
	v_mfma_f32_16x16x32_bf16 v[10:13], v[150:153], v[52:55], v[10:13]
	v_mfma_f32_16x16x32_bf16 v[6:9], v[154:157], v[48:51], v[6:9]
	v_mfma_f32_16x16x32_bf16 v[2:5], v[154:157], v[52:55], v[2:5]
	global_load_dwordx4 v[142:145], v[30:31], off offset:576
	global_load_dwordx4 v[146:149], v[32:33], off offset:576
	global_load_dwordx4 v[150:153], v[56:57], off offset:576
	global_load_dwordx4 v[154:157], v[42:43], off offset:576
	ds_read_b128 v[48:51], v112 offset:448
	ds_read_b128 v[52:55], v112 offset:17088
	s_waitcnt vmcnt(12) lgkmcnt(2)
	v_mfma_f32_16x16x32_bf16 v[34:37], v[158:161], v[38:41], v[34:37]
	v_mfma_f32_16x16x32_bf16 v[26:29], v[158:161], v[44:47], v[26:29]
	v_mfma_f32_16x16x32_bf16 v[22:25], v[162:165], v[38:41], v[22:25]
	v_mfma_f32_16x16x32_bf16 v[18:21], v[162:165], v[44:47], v[18:21]
	v_mfma_f32_16x16x32_bf16 v[14:17], v[166:169], v[38:41], v[14:17]
	v_mfma_f32_16x16x32_bf16 v[10:13], v[166:169], v[44:47], v[10:13]
	v_mfma_f32_16x16x32_bf16 v[6:9], v[170:173], v[38:41], v[6:9]
	v_mfma_f32_16x16x32_bf16 v[2:5], v[170:173], v[44:47], v[2:5]
	global_load_dwordx4 v[158:161], v[30:31], off offset:640
	global_load_dwordx4 v[162:165], v[32:33], off offset:640
	global_load_dwordx4 v[166:169], v[56:57], off offset:640
	global_load_dwordx4 v[170:173], v[42:43], off offset:640
	ds_read_b128 v[38:41], v112 offset:512
	ds_read_b128 v[44:47], v112 offset:17152
	s_waitcnt vmcnt(12) lgkmcnt(2)
	v_mfma_f32_16x16x32_bf16 v[34:37], v[174:177], v[48:51], v[34:37]
	v_mfma_f32_16x16x32_bf16 v[26:29], v[174:177], v[52:55], v[26:29]
	v_mfma_f32_16x16x32_bf16 v[22:25], v[190:193], v[48:51], v[22:25]
	v_mfma_f32_16x16x32_bf16 v[18:21], v[190:193], v[52:55], v[18:21]
	v_mfma_f32_16x16x32_bf16 v[14:17], v[194:197], v[48:51], v[14:17]
	v_mfma_f32_16x16x32_bf16 v[10:13], v[194:197], v[52:55], v[10:13]
	v_mfma_f32_16x16x32_bf16 v[6:9], v[198:201], v[48:51], v[6:9]
	v_mfma_f32_16x16x32_bf16 v[2:5], v[198:201], v[52:55], v[2:5]
	global_load_dwordx4 v[174:177], v[30:31], off offset:704
	global_load_dwordx4 v[190:193], v[32:33], off offset:704
	global_load_dwordx4 v[194:197], v[56:57], off offset:704
	global_load_dwordx4 v[198:201], v[42:43], off offset:704
	ds_read_b128 v[48:51], v112 offset:576
	ds_read_b128 v[52:55], v112 offset:17216
	s_waitcnt vmcnt(12) lgkmcnt(2)
	v_mfma_f32_16x16x32_bf16 v[34:37], v[126:129], v[38:41], v[34:37]
	v_mfma_f32_16x16x32_bf16 v[26:29], v[126:129], v[44:47], v[26:29]
	v_mfma_f32_16x16x32_bf16 v[22:25], v[130:133], v[38:41], v[22:25]
	v_mfma_f32_16x16x32_bf16 v[18:21], v[130:133], v[44:47], v[18:21]
	v_mfma_f32_16x16x32_bf16 v[14:17], v[134:137], v[38:41], v[14:17]
	v_mfma_f32_16x16x32_bf16 v[10:13], v[134:137], v[44:47], v[10:13]
	v_mfma_f32_16x16x32_bf16 v[6:9], v[138:141], v[38:41], v[6:9]
	v_mfma_f32_16x16x32_bf16 v[2:5], v[138:141], v[44:47], v[2:5]
	global_load_dwordx4 v[126:129], v[30:31], off offset:768
	global_load_dwordx4 v[130:133], v[32:33], off offset:768
	global_load_dwordx4 v[134:137], v[56:57], off offset:768
	global_load_dwordx4 v[138:141], v[42:43], off offset:768
	ds_read_b128 v[38:41], v112 offset:640
	ds_read_b128 v[44:47], v112 offset:17280
	s_waitcnt vmcnt(12) lgkmcnt(2)
	v_mfma_f32_16x16x32_bf16 v[34:37], v[142:145], v[48:51], v[34:37]
	v_mfma_f32_16x16x32_bf16 v[26:29], v[142:145], v[52:55], v[26:29]
	v_mfma_f32_16x16x32_bf16 v[22:25], v[146:149], v[48:51], v[22:25]
	v_mfma_f32_16x16x32_bf16 v[18:21], v[146:149], v[52:55], v[18:21]
	v_mfma_f32_16x16x32_bf16 v[14:17], v[150:153], v[48:51], v[14:17]
	v_mfma_f32_16x16x32_bf16 v[10:13], v[150:153], v[52:55], v[10:13]
	v_mfma_f32_16x16x32_bf16 v[6:9], v[154:157], v[48:51], v[6:9]
	v_mfma_f32_16x16x32_bf16 v[2:5], v[154:157], v[52:55], v[2:5]
	global_load_dwordx4 v[142:145], v[30:31], off offset:832
	global_load_dwordx4 v[146:149], v[32:33], off offset:832
	global_load_dwordx4 v[150:153], v[56:57], off offset:832
	global_load_dwordx4 v[154:157], v[42:43], off offset:832
	ds_read_b128 v[48:51], v112 offset:704
	ds_read_b128 v[52:55], v112 offset:17344
	s_waitcnt vmcnt(12) lgkmcnt(2)
	v_mfma_f32_16x16x32_bf16 v[34:37], v[158:161], v[38:41], v[34:37]
	v_mfma_f32_16x16x32_bf16 v[26:29], v[158:161], v[44:47], v[26:29]
	v_mfma_f32_16x16x32_bf16 v[22:25], v[162:165], v[38:41], v[22:25]
	v_mfma_f32_16x16x32_bf16 v[18:21], v[162:165], v[44:47], v[18:21]
	v_mfma_f32_16x16x32_bf16 v[14:17], v[166:169], v[38:41], v[14:17]
	v_mfma_f32_16x16x32_bf16 v[10:13], v[166:169], v[44:47], v[10:13]
	v_mfma_f32_16x16x32_bf16 v[6:9], v[170:173], v[38:41], v[6:9]
	v_mfma_f32_16x16x32_bf16 v[2:5], v[170:173], v[44:47], v[2:5]
	global_load_dwordx4 v[158:161], v[30:31], off offset:896
	global_load_dwordx4 v[162:165], v[32:33], off offset:896
	global_load_dwordx4 v[166:169], v[56:57], off offset:896
	global_load_dwordx4 v[170:173], v[42:43], off offset:896
	ds_read_b128 v[38:41], v112 offset:768
	ds_read_b128 v[44:47], v112 offset:17408
	s_waitcnt vmcnt(12) lgkmcnt(2)
	v_mfma_f32_16x16x32_bf16 v[34:37], v[174:177], v[48:51], v[34:37]
	v_mfma_f32_16x16x32_bf16 v[26:29], v[174:177], v[52:55], v[26:29]
	v_mfma_f32_16x16x32_bf16 v[22:25], v[190:193], v[48:51], v[22:25]
	v_mfma_f32_16x16x32_bf16 v[18:21], v[190:193], v[52:55], v[18:21]
	v_mfma_f32_16x16x32_bf16 v[14:17], v[194:197], v[48:51], v[14:17]
	v_mfma_f32_16x16x32_bf16 v[10:13], v[194:197], v[52:55], v[10:13]
	v_mfma_f32_16x16x32_bf16 v[6:9], v[198:201], v[48:51], v[6:9]
	v_mfma_f32_16x16x32_bf16 v[2:5], v[198:201], v[52:55], v[2:5]
	global_load_dwordx4 v[174:177], v[30:31], off offset:960
	global_load_dwordx4 v[190:193], v[32:33], off offset:960
	global_load_dwordx4 v[194:197], v[56:57], off offset:960
	global_load_dwordx4 v[198:201], v[42:43], off offset:960
	ds_read_b128 v[48:51], v112 offset:832
	ds_read_b128 v[52:55], v112 offset:17472
	s_waitcnt vmcnt(12) lgkmcnt(2)
	v_mfma_f32_16x16x32_bf16 v[34:37], v[126:129], v[38:41], v[34:37]
	v_mfma_f32_16x16x32_bf16 v[26:29], v[126:129], v[44:47], v[26:29]
	v_mfma_f32_16x16x32_bf16 v[22:25], v[130:133], v[38:41], v[22:25]
	v_mfma_f32_16x16x32_bf16 v[18:21], v[130:133], v[44:47], v[18:21]
	v_mfma_f32_16x16x32_bf16 v[14:17], v[134:137], v[38:41], v[14:17]
	v_mfma_f32_16x16x32_bf16 v[10:13], v[134:137], v[44:47], v[10:13]
	v_mfma_f32_16x16x32_bf16 v[6:9], v[138:141], v[38:41], v[6:9]
	v_mfma_f32_16x16x32_bf16 v[2:5], v[138:141], v[44:47], v[2:5]
	ds_read_b128 v[38:41], v112 offset:896
	ds_read_b128 v[44:47], v112 offset:17536
	s_waitcnt vmcnt(8) lgkmcnt(2)
	v_mfma_f32_16x16x32_bf16 v[34:37], v[142:145], v[48:51], v[34:37]
	v_mfma_f32_16x16x32_bf16 v[26:29], v[142:145], v[52:55], v[26:29]
	v_mfma_f32_16x16x32_bf16 v[22:25], v[146:149], v[48:51], v[22:25]
	v_mfma_f32_16x16x32_bf16 v[18:21], v[146:149], v[52:55], v[18:21]
	v_mfma_f32_16x16x32_bf16 v[14:17], v[150:153], v[48:51], v[14:17]
	v_mfma_f32_16x16x32_bf16 v[10:13], v[150:153], v[52:55], v[10:13]
	v_mfma_f32_16x16x32_bf16 v[6:9], v[154:157], v[48:51], v[6:9]
	v_mfma_f32_16x16x32_bf16 v[2:5], v[154:157], v[52:55], v[2:5]
	ds_read_b128 v[48:51], v112 offset:960
	ds_read_b128 v[52:55], v112 offset:17600
	s_waitcnt vmcnt(4) lgkmcnt(2)
	v_mfma_f32_16x16x32_bf16 v[34:37], v[158:161], v[38:41], v[34:37]
	v_mfma_f32_16x16x32_bf16 v[26:29], v[158:161], v[44:47], v[26:29]
	v_mfma_f32_16x16x32_bf16 v[22:25], v[162:165], v[38:41], v[22:25]
	v_mfma_f32_16x16x32_bf16 v[18:21], v[162:165], v[44:47], v[18:21]
	v_mfma_f32_16x16x32_bf16 v[14:17], v[166:169], v[38:41], v[14:17]
	v_mfma_f32_16x16x32_bf16 v[10:13], v[166:169], v[44:47], v[10:13]
	v_mfma_f32_16x16x32_bf16 v[6:9], v[170:173], v[38:41], v[6:9]
	v_mfma_f32_16x16x32_bf16 v[2:5], v[170:173], v[44:47], v[2:5]
	s_waitcnt vmcnt(0) lgkmcnt(0)
	v_mfma_f32_16x16x32_bf16 v[34:37], v[174:177], v[48:51], v[34:37]
	v_mfma_f32_16x16x32_bf16 v[26:29], v[174:177], v[52:55], v[26:29]
	v_mfma_f32_16x16x32_bf16 v[22:25], v[190:193], v[48:51], v[22:25]
	v_mfma_f32_16x16x32_bf16 v[18:21], v[190:193], v[52:55], v[18:21]
	v_mfma_f32_16x16x32_bf16 v[14:17], v[194:197], v[48:51], v[14:17]
	v_mfma_f32_16x16x32_bf16 v[10:13], v[194:197], v[52:55], v[10:13]
	v_mfma_f32_16x16x32_bf16 v[6:9], v[198:201], v[48:51], v[6:9]
	v_mfma_f32_16x16x32_bf16 v[2:5], v[198:201], v[52:55], v[2:5]
	s_mov_b64 s[4:5], 0x400
	v_mov_b32_e32 v30, v202
	v_mov_b32_e32 v31, v203
	v_mov_b32_e32 v32, v204
	v_mov_b32_e32 v33, v205
	ds_read_b64 v[38:39], v113
	v_ashrrev_i32_e32 v93, 31, v92
	s_mov_b64 s[6:7], 0x23c00400
	v_readlane_b32 s48, v255, 0
	v_readlane_b32 s54, v255, 6
	s_add_i32 s11, s11, s54
	s_cmpk_gt_i32 s11, 0xff
	v_readlane_b32 s49, v255, 1
	v_readlane_b32 s50, v255, 2
	v_readlane_b32 s51, v255, 3
	v_readlane_b32 s52, v255, 4
	v_readlane_b32 s53, v255, 5
	v_readlane_b32 s55, v255, 7
	v_pk_add_f32 v[34:35], v[34:35], v[30:31]
	v_pk_add_f32 v[36:37], v[36:37], v[32:33]
	v_mul_f32_e32 v35, 0xbfb8aa3b, v35
	v_mul_f32_e32 v34, 0xbfb8aa3b, v34
	v_exp_f32_e32 v40, v35
	v_mul_f32_e32 v35, 0xbfb8aa3b, v36
	v_exp_f32_e32 v34, v34
	v_exp_f32_e32 v35, v35
	v_mul_f32_e32 v36, 0xbfb8aa3b, v37
	v_exp_f32_e32 v41, v36
	s_waitcnt lgkmcnt(0)
	v_lshlrev_b32_e32 v37, 16, v39
	v_pk_add_f32 v[34:35], v[34:35], 1.0 op_sel_hi:[1,0]
	v_lshlrev_b32_e32 v36, 16, v38
	v_and_b32_e32 v39, 0xffff0000, v39
	v_and_b32_e32 v38, 0xffff0000, v38
	v_pk_add_f32 v[26:27], v[26:27], v[30:31]
	v_rcp_f32_e32 v35, v35
	s_nop 0
	v_mul_f32_e32 v26, 0xbfb8aa3b, v26
	v_pk_add_f32 v[32:33], v[28:29], v[32:33]
	v_rcp_f32_e32 v34, v34
	s_nop 0
	v_pk_mul_f32 v[34:35], v[34:35], v[36:37]
	v_pk_add_f32 v[36:37], v[40:41], 1.0 op_sel_hi:[1,0]
	s_nop 0
	s_nop 0
	v_rcp_f32_e32 v37, v37
	s_nop 0
	s_nop 0
	v_rcp_f32_e32 v36, v36
	s_nop 0
	v_pk_mul_f32 v[36:37], v[36:37], v[38:39]
	v_cvt_pk_bf16_f32 v37, v35, v37
	v_cvt_pk_bf16_f32 v36, v34, v36
	v_lshlrev_b64 v[34:35], 12, v[92:93]
	v_lshl_add_u64 v[34:35], s[0:1], 0, v[34:35]
	v_lshl_add_u64 v[34:35], v[34:35], 0, s[6:7]
	v_lshl_add_u64 v[38:39], v[34:35], 0, v[84:85]
	global_store_dwordx2 v[38:39], v[36:37], off
	v_exp_f32_e32 v38, v26
	v_mul_f32_e32 v26, 0xbfb8aa3b, v27
	v_exp_f32_e32 v28, v26
	v_mul_f32_e32 v26, 0xbfb8aa3b, v32
	ds_read_b64 v[36:37], v113 offset:16640
	v_exp_f32_e32 v39, v26
	v_mul_f32_e32 v26, 0xbfb8aa3b, v33
	v_exp_f32_e32 v29, v26
	v_pk_add_f32 v[32:33], v[38:39], 1.0 op_sel_hi:[1,0]
	s_waitcnt lgkmcnt(0)
	v_lshlrev_b32_e32 v30, 16, v36
	v_and_b32_e32 v26, 0xffff0000, v36
	v_lshlrev_b32_e32 v31, 16, v37
	v_and_b32_e32 v27, 0xffff0000, v37
	v_pk_add_f32 v[28:29], v[28:29], 1.0 op_sel_hi:[1,0]
	v_rcp_f32_e32 v33, v33
	s_nop 0
	s_nop 0
	v_rcp_f32_e32 v32, v32
	s_nop 0
	v_pk_mul_f32 v[30:31], v[32:33], v[30:31]
	s_nop 0
	v_rcp_f32_e32 v29, v29
	s_nop 0
	s_nop 0
	v_rcp_f32_e32 v28, v28
	s_nop 0
	v_pk_mul_f32 v[26:27], v[28:29], v[26:27]
	v_and_b32_sdwa v29, v30, v225 dst_sel:DWORD dst_unused:UNUSED_PAD src0_sel:WORD_1 src1_sel:DWORD
	v_and_b32_sdwa v28, v31, v225 dst_sel:DWORD dst_unused:UNUSED_PAD src0_sel:WORD_1 src1_sel:DWORD
	v_add3_u32 v29, v30, v29, s23
	v_and_b32_sdwa v30, v27, v225 dst_sel:DWORD dst_unused:UNUSED_PAD src0_sel:WORD_1 src1_sel:DWORD
	v_add3_u32 v28, v31, v28, s23
	v_and_b32_sdwa v31, v26, v225 dst_sel:DWORD dst_unused:UNUSED_PAD src0_sel:WORD_1 src1_sel:DWORD
	v_add3_u32 v27, v27, v30, s23
	v_add3_u32 v26, v26, v31, s23
	v_and_b32_e32 v27, 0xffff0000, v27
	v_and_b32_e32 v26, 0xffff0000, v26
	v_or_b32_sdwa v27, v27, v28 dst_sel:DWORD dst_unused:UNUSED_PAD src0_sel:DWORD src1_sel:WORD_1
	v_or_b32_e32 v28, s8, v102
	v_or_b32_sdwa v26, v26, v29 dst_sel:DWORD dst_unused:UNUSED_PAD src0_sel:DWORD src1_sel:WORD_1
	v_ashrrev_i32_e32 v29, 31, v28
	v_lshlrev_b64 v[28:29], 12, v[28:29]
	v_lshl_add_u64 v[28:29], s[0:1], 0, v[28:29]
	v_lshl_add_u64 v[30:31], v[28:29], 0, s[6:7]
	v_lshl_add_u64 v[28:29], v[30:31], 0, v[84:85]
	global_store_dwordx2 v[28:29], v[26:27], off
	v_mov_b32_e32 v26, v206
	v_mov_b32_e32 v27, v207
	v_mov_b32_e32 v28, v208
	v_mov_b32_e32 v29, v209
	ds_read_b64 v[32:33], v106
	v_pk_add_f32 v[22:23], v[22:23], v[26:27]
	v_pk_add_f32 v[24:25], v[24:25], v[28:29]
	v_mul_f32_e32 v23, 0xbfb8aa3b, v23
	v_mul_f32_e32 v22, 0xbfb8aa3b, v22
	v_exp_f32_e32 v36, v23
	v_mul_f32_e32 v23, 0xbfb8aa3b, v24
	v_exp_f32_e32 v22, v22
	v_exp_f32_e32 v23, v23
	v_mul_f32_e32 v24, 0xbfb8aa3b, v25
	v_exp_f32_e32 v37, v24
	s_waitcnt lgkmcnt(0)
	v_lshlrev_b32_e32 v25, 16, v33
	v_pk_add_f32 v[22:23], v[22:23], 1.0 op_sel_hi:[1,0]
	v_lshlrev_b32_e32 v24, 16, v32
	v_and_b32_e32 v33, 0xffff0000, v33
	v_and_b32_e32 v32, 0xffff0000, v32
	v_pk_add_f32 v[18:19], v[18:19], v[26:27]
	v_rcp_f32_e32 v23, v23
	s_nop 0
	v_pk_add_f32 v[20:21], v[20:21], v[28:29]
	v_mul_f32_e32 v19, 0xbfb8aa3b, v19
	v_mul_f32_e32 v18, 0xbfb8aa3b, v18
	v_rcp_f32_e32 v22, v22
	s_nop 0
	v_pk_mul_f32 v[22:23], v[22:23], v[24:25]
	v_pk_add_f32 v[24:25], v[36:37], 1.0 op_sel_hi:[1,0]
	v_exp_f32_e32 v18, v18
	s_nop 0
	v_rcp_f32_e32 v25, v25
	s_nop 0
	s_nop 0
	v_rcp_f32_e32 v24, v24
	s_nop 0
	v_pk_mul_f32 v[24:25], v[24:25], v[32:33]
	v_cvt_pk_bf16_f32 v23, v23, v25
	v_cvt_pk_bf16_f32 v22, v22, v24
	v_lshl_add_u64 v[24:25], v[34:35], 0, v[86:87]
	global_store_dwordx2 v[24:25], v[22:23], off
	v_exp_f32_e32 v24, v19
	v_mul_f32_e32 v19, 0xbfb8aa3b, v20
	v_exp_f32_e32 v19, v19
	ds_read_b64 v[22:23], v107
	v_mul_f32_e32 v20, 0xbfb8aa3b, v21
	v_exp_f32_e32 v25, v20
	v_pk_add_f32 v[18:19], v[18:19], 1.0 op_sel_hi:[1,0]
	s_waitcnt lgkmcnt(0)
	v_lshlrev_b32_e32 v21, 16, v23
	v_lshlrev_b32_e32 v20, 16, v22
	v_and_b32_e32 v23, 0xffff0000, v23
	v_and_b32_e32 v22, 0xffff0000, v22
	v_rcp_f32_e32 v19, v19
	s_nop 0
	s_nop 0
	v_rcp_f32_e32 v18, v18
	s_nop 0
	v_pk_mul_f32 v[18:19], v[18:19], v[20:21]
	v_pk_add_f32 v[20:21], v[24:25], 1.0 op_sel_hi:[1,0]
	s_nop 0
	s_nop 0
	v_rcp_f32_e32 v21, v21
	s_nop 0
	s_nop 0
	v_rcp_f32_e32 v20, v20
	s_nop 0
	v_pk_mul_f32 v[20:21], v[20:21], v[22:23]
	v_cvt_pk_bf16_f32 v19, v19, v21
	v_cvt_pk_bf16_f32 v18, v18, v20
	v_lshl_add_u64 v[20:21], v[30:31], 0, v[86:87]
	global_store_dwordx2 v[20:21], v[18:19], off
	v_mov_b32_e32 v18, v210
	v_mov_b32_e32 v19, v211
	v_mov_b32_e32 v20, v212
	v_mov_b32_e32 v21, v213
	ds_read_b64 v[22:23], v108
	v_pk_add_f32 v[14:15], v[14:15], v[18:19]
	v_pk_add_f32 v[16:17], v[16:17], v[20:21]
	v_mul_f32_e32 v15, 0xbfb8aa3b, v15
	v_mul_f32_e32 v14, 0xbfb8aa3b, v14
	v_exp_f32_e32 v24, v15
	v_mul_f32_e32 v15, 0xbfb8aa3b, v16
	v_exp_f32_e32 v14, v14
	v_exp_f32_e32 v15, v15
	v_mul_f32_e32 v16, 0xbfb8aa3b, v17
	v_exp_f32_e32 v25, v16
	s_waitcnt lgkmcnt(0)
	v_lshlrev_b32_e32 v17, 16, v23
	v_pk_add_f32 v[14:15], v[14:15], 1.0 op_sel_hi:[1,0]
	v_lshlrev_b32_e32 v16, 16, v22
	v_and_b32_e32 v23, 0xffff0000, v23
	v_and_b32_e32 v22, 0xffff0000, v22
	v_pk_add_f32 v[10:11], v[10:11], v[18:19]
	v_rcp_f32_e32 v15, v15
	s_nop 0
	v_pk_add_f32 v[12:13], v[12:13], v[20:21]
	v_mul_f32_e32 v11, 0xbfb8aa3b, v11
	v_mul_f32_e32 v10, 0xbfb8aa3b, v10
	v_rcp_f32_e32 v14, v14
	s_nop 0
	v_pk_mul_f32 v[14:15], v[14:15], v[16:17]
	v_pk_add_f32 v[16:17], v[24:25], 1.0 op_sel_hi:[1,0]
	v_exp_f32_e32 v10, v10
	s_nop 0
	v_rcp_f32_e32 v17, v17
	s_nop 0
	s_nop 0
	v_rcp_f32_e32 v16, v16
	s_nop 0
	v_pk_mul_f32 v[16:17], v[16:17], v[22:23]
	v_cvt_pk_bf16_f32 v15, v15, v17
	v_cvt_pk_bf16_f32 v14, v14, v16
	v_lshl_add_u64 v[16:17], v[34:35], 0, v[88:89]
	global_store_dwordx2 v[16:17], v[14:15], off
	v_exp_f32_e32 v16, v11
	v_mul_f32_e32 v11, 0xbfb8aa3b, v12
	v_exp_f32_e32 v11, v11
	ds_read_b64 v[14:15], v109
	v_mul_f32_e32 v12, 0xbfb8aa3b, v13
	v_exp_f32_e32 v17, v12
	v_pk_add_f32 v[10:11], v[10:11], 1.0 op_sel_hi:[1,0]
	s_waitcnt lgkmcnt(0)
	v_lshlrev_b32_e32 v13, 16, v15
	v_lshlrev_b32_e32 v12, 16, v14
	v_and_b32_e32 v15, 0xffff0000, v15
	v_and_b32_e32 v14, 0xffff0000, v14
	v_rcp_f32_e32 v11, v11
	s_nop 0
	s_nop 0
	v_rcp_f32_e32 v10, v10
	s_nop 0
	v_pk_mul_f32 v[10:11], v[10:11], v[12:13]
	v_pk_add_f32 v[12:13], v[16:17], 1.0 op_sel_hi:[1,0]
	s_nop 0
	s_nop 0
	v_rcp_f32_e32 v13, v13
	s_nop 0
	s_nop 0
	v_rcp_f32_e32 v12, v12
	s_nop 0
	v_pk_mul_f32 v[12:13], v[12:13], v[14:15]
	v_cvt_pk_bf16_f32 v11, v11, v13
	v_cvt_pk_bf16_f32 v10, v10, v12
	v_lshl_add_u64 v[12:13], v[30:31], 0, v[88:89]
	global_store_dwordx2 v[12:13], v[10:11], off
	v_mov_b32_e32 v10, v214
	v_mov_b32_e32 v11, v215
	v_mov_b32_e32 v12, v216
	v_mov_b32_e32 v13, v217
	ds_read_b64 v[14:15], v110
	v_pk_add_f32 v[6:7], v[6:7], v[10:11]
	v_pk_add_f32 v[8:9], v[8:9], v[12:13]
	v_mul_f32_e32 v7, 0xbfb8aa3b, v7
	v_mul_f32_e32 v6, 0xbfb8aa3b, v6
	v_exp_f32_e32 v16, v7
	v_mul_f32_e32 v7, 0xbfb8aa3b, v8
	v_exp_f32_e32 v6, v6
	v_exp_f32_e32 v7, v7
	v_mul_f32_e32 v8, 0xbfb8aa3b, v9
	v_exp_f32_e32 v17, v8
	s_waitcnt lgkmcnt(0)
	v_lshlrev_b32_e32 v9, 16, v15
	v_pk_add_f32 v[6:7], v[6:7], 1.0 op_sel_hi:[1,0]
	v_lshlrev_b32_e32 v8, 16, v14
	v_and_b32_e32 v15, 0xffff0000, v15
	v_and_b32_e32 v14, 0xffff0000, v14
	v_pk_add_f32 v[2:3], v[2:3], v[10:11]
	v_rcp_f32_e32 v7, v7
	s_nop 0
	v_pk_add_f32 v[4:5], v[4:5], v[12:13]
	v_mul_f32_e32 v3, 0xbfb8aa3b, v3
	v_mul_f32_e32 v2, 0xbfb8aa3b, v2
	v_rcp_f32_e32 v6, v6
	s_nop 0
	v_pk_mul_f32 v[6:7], v[6:7], v[8:9]
	v_pk_add_f32 v[8:9], v[16:17], 1.0 op_sel_hi:[1,0]
	v_exp_f32_e32 v2, v2
	s_nop 0
	v_rcp_f32_e32 v9, v9
	s_nop 0
	s_nop 0
	v_rcp_f32_e32 v8, v8
	s_nop 0
	v_pk_mul_f32 v[8:9], v[8:9], v[14:15]
	v_cvt_pk_bf16_f32 v7, v7, v9
	v_cvt_pk_bf16_f32 v6, v6, v8
	v_lshl_add_u64 v[8:9], v[34:35], 0, v[90:91]
	global_store_dwordx2 v[8:9], v[6:7], off
	v_exp_f32_e32 v8, v3
	v_mul_f32_e32 v3, 0xbfb8aa3b, v4
	v_exp_f32_e32 v3, v3
	ds_read_b64 v[6:7], v111
	v_mul_f32_e32 v4, 0xbfb8aa3b, v5
	v_exp_f32_e32 v9, v4
	v_pk_add_f32 v[2:3], v[2:3], 1.0 op_sel_hi:[1,0]
	s_waitcnt lgkmcnt(0)
	v_lshlrev_b32_e32 v5, 16, v7
	v_lshlrev_b32_e32 v4, 16, v6
	v_and_b32_e32 v7, 0xffff0000, v7
	v_and_b32_e32 v6, 0xffff0000, v6
	v_rcp_f32_e32 v3, v3
	s_nop 0
	s_nop 0
	v_rcp_f32_e32 v2, v2
	s_nop 0
	v_pk_mul_f32 v[2:3], v[2:3], v[4:5]
	v_pk_add_f32 v[4:5], v[8:9], 1.0 op_sel_hi:[1,0]
	s_nop 0
	s_nop 0
	v_rcp_f32_e32 v5, v5
	s_nop 0
	s_nop 0
	v_rcp_f32_e32 v4, v4
	s_nop 0
	v_pk_mul_f32 v[4:5], v[4:5], v[6:7]
	v_cvt_pk_bf16_f32 v3, v3, v5
	v_cvt_pk_bf16_f32 v2, v2, v4
	v_lshl_add_u64 v[4:5], v[30:31], 0, v[90:91]
	global_store_dwordx2 v[4:5], v[2:3], off
	s_waitcnt lgkmcnt(0)
	s_barrier
	s_cbranch_scc0 .LBB0_1195

.LBB0_1215:
	v_mov_b32_e32 v104, s91
	v_cndmask_b32_e64 v103, v74, v104, s[40:41]
	v_cndmask_b32_e64 v74, v103, v74, s[42:43]
	v_cndmask_b32_e64 v75, 0, v75, s[42:43]
	v_cndmask_b32_e64 v76, v76, 0, s[44:45]
	v_cndmask_b32_e64 v77, v77, 0, s[46:47]
	v_cvt_pk_bf16_f32 v74, v74, v75
	v_cvt_pk_bf16_f32 v75, v76, v77
	v_cvt_pk_bf16_f32 v76, v87, v89
	v_add_u32_e32 v103, v0, v122
	v_cvt_pk_bf16_f32 v77, v86, v88
	v_add_u32_e32 v86, v103, v123
	v_add_u32_e32 v104, v103, v124
	v_add_u32_e32 v108, v103, v125
	v_add_u32_e32 v103, v103, v126
	v_add_u32_e32 v127, 0x4800, v86
	v_add_u32_e32 v132, 0x4800, v104
	v_add_u32_e32 v133, 0x4800, v108
	v_add_u32_e32 v103, 0x4800, v103
	ds_read2_b64 v[86:89], v127 offset1:4
	ds_read2_b64 v[104:107], v132 offset1:4
	ds_read2_b64 v[108:111], v133 offset1:4
	ds_read2_b64 v[128:131], v103 offset1:4
	s_waitcnt lgkmcnt(0)
	v_mfma_f32_16x16x32_bf16 v[86:89], v[86:89], v[74:77], 0
	s_lshl_b32 s10, s34, 9
	s_add_i32 s10, s10, 0
	s_add_i32 s10, s10, 0x1b000
	v_mfma_f32_16x16x32_bf16 v[104:107], v[104:107], v[74:77], 0
	v_mfma_f32_16x16x32_bf16 v[108:111], v[108:111], v[74:77], 0
	v_mfma_f32_16x16x32_bf16 v[74:77], v[128:131], v[74:77], 0
	v_cvt_pk_bf16_f32 v78, v78, v81
	v_cvt_pk_bf16_f32 v79, v79, v80
	v_cvt_pk_bf16_f32 v80, v82, v85
	v_cvt_pk_bf16_f32 v81, v83, v84
	ds_read2_b64 v[82:85], v127 offset0:8 offset1:12
	v_add_u32_e32 v127, v0, v124
	s_waitcnt lgkmcnt(0)
	v_mfma_f32_16x16x32_bf16 v[82:85], v[82:85], v[78:81], v[86:89]
	s_nop 2
	ds_read2_b64 v[86:89], v132 offset0:8 offset1:12
	v_add_u32_e32 v128, v0, v125
	s_waitcnt lgkmcnt(0)
	v_mfma_f32_16x16x32_bf16 v[86:89], v[86:89], v[78:81], v[104:107]
	s_nop 2
	ds_read2_b64 v[104:107], v133 offset0:8 offset1:12
	s_waitcnt lgkmcnt(0)
	v_mfma_f32_16x16x32_bf16 v[104:107], v[104:107], v[78:81], v[108:111]
	s_nop 2
	ds_read2_b64 v[108:111], v103 offset0:8 offset1:12
	v_add_u32_e32 v103, v0, v123
	v_add_u32_e32 v0, v0, v126
	s_waitcnt lgkmcnt(0)
	v_mfma_f32_16x16x32_bf16 v[74:77], v[108:111], v[78:81], v[74:77]
	ds_read_b128 v[78:81], v103 offset:36864
	s_waitcnt lgkmcnt(0)
	v_mfma_f32_16x16x32_bf16 v[78:81], v[78:81], v[70:73], v[82:85]
	s_nop 2
	ds_read_b128 v[82:85], v127 offset:36864
	s_waitcnt lgkmcnt(0)
	v_mfma_f32_16x16x32_bf16 v[86:89], v[82:85], v[70:73], v[86:89]
	ds_read_b128 v[82:85], v128 offset:36864
	s_waitcnt lgkmcnt(0)
	v_mfma_f32_16x16x32_bf16 v[104:107], v[82:85], v[70:73], v[104:107]
	ds_read_b128 v[82:85], v0 offset:36864
	s_waitcnt lgkmcnt(0)
	v_mfma_f32_16x16x32_bf16 v[108:111], v[82:85], v[70:73], v[74:77]
	ds_read_b128 v[70:73], v103 offset:36928
	s_waitcnt lgkmcnt(0)
	v_mfma_f32_16x16x32_bf16 v[82:85], v[70:73], v[66:69], v[78:81]
	ds_read_b128 v[70:73], v127 offset:36928
	s_nop 1
	ds_read_b128 v[78:81], v0 offset:36928
	s_nop 3
	v_mul_f32_e32 v0, v83, v83
	s_waitcnt lgkmcnt(0)
	v_mfma_f32_16x16x32_bf16 v[74:77], v[70:73], v[66:69], v[86:89]
	ds_read_b128 v[70:73], v128 offset:36928
	v_fmac_f32_e32 v0, v82, v82
	s_waitcnt lgkmcnt(0)
	v_mfma_f32_16x16x32_bf16 v[70:73], v[70:73], v[66:69], v[104:107]
	v_mfma_f32_16x16x32_bf16 v[66:69], v[78:81], v[66:69], v[108:111]
	v_mul_f32_e32 v78, v85, v85
	v_fmac_f32_e32 v78, v84, v84
	v_add_f32_e32 v0, v0, v78
	v_mul_f32_e32 v78, v75, v75
	v_mul_f32_e32 v79, v77, v77
	v_fmac_f32_e32 v78, v74, v74
	v_fmac_f32_e32 v79, v76, v76
	v_add_f32_e32 v78, v78, v79
	v_add_f32_e32 v0, v0, v78
	v_mul_f32_e32 v78, v71, v71
	v_mul_f32_e32 v79, v73, v73
	v_fmac_f32_e32 v78, v70, v70
	v_fmac_f32_e32 v79, v72, v72
	v_add_f32_e32 v78, v78, v79
	v_add_f32_e32 v0, v0, v78
	v_mul_f32_e32 v78, v67, v67
	v_mul_f32_e32 v79, v69, v69
	v_fmac_f32_e32 v78, v66, v66
	v_fmac_f32_e32 v79, v68, v68
	v_add_f32_e32 v78, v78, v79
	v_add_f32_e32 v0, v0, v78
	ds_bpermute_b32 v78, v119, v0
	s_waitcnt lgkmcnt(0)
	v_add_f32_e32 v0, v0, v78
	ds_bpermute_b32 v78, v120, v0
	s_and_saveexec_b64 s[84:85], s[48:49]
	s_cbranch_execz .LBB0_1217
	s_lshl_b32 s90, s88, 2
	s_add_i32 s90, s10, s90
	v_lshl_add_u32 v79, v93, 2, s90
	s_waitcnt lgkmcnt(0)
	v_add_f32_e32 v0, v0, v78
	ds_write_b32 v79, v0
.LBB0_1217:
	s_or_b64 exec, exec, s[84:85]
	v_lshl_add_u32 v0, v115, 2, s10
	s_waitcnt lgkmcnt(0)
	s_barrier
	ds_read2st64_b32 v[78:79], v0 offset1:1
	s_and_b32 s10, s12, 0xfffff000
	s_and_b32 s84, s8, 0xfc0
	s_or_b32 s10, s10, s84
	v_mov_b64_e32 v[80:81], s[0:1]
	s_waitcnt lgkmcnt(0)
	v_add_f32_e32 v0, v78, v79
	v_fmamk_f32 v0, v0, 0x3c000000, v224
	v_cmp_gt_f32_e32 vcc, s19, v0
	v_mul_f32_e32 v78, 0x4b800000, v0
	v_mov_b32_e32 v128, v82
	v_cndmask_b32_e32 v0, v0, v78, vcc
	v_rsq_f32_e32 v0, v0
	v_mov_b32_e32 v129, v84
	v_mul_f32_e32 v78, 0x45800000, v0
	v_cndmask_b32_e32 v0, v0, v78, vcc
	v_or_b32_e32 v78, s10, v115
	s_and_b32 s10, s87, 0x180
	v_mad_i64_i32 v[80:81], s[84:85], v78, s20, v[80:81]
	s_lshl_b32 s90, s10, 2
	v_lshl_add_u64 v[80:81], v[80:81], 0, s[90:91]
	s_mov_b64 s[84:85], 0x12c01000
	v_ashrrev_i32_e32 v79, 31, v78
	v_lshl_add_u64 v[104:105], v[80:81], 0, s[84:85]
	s_add_u32 s84, s11, s90
	v_lshlrev_b64 v[106:107], 12, v[78:79]
	s_addc_u32 s85, s18, 0
	v_lshlrev_b64 v[78:79], 2, v[94:95]
	v_lshl_add_u64 v[80:81], s[84:85], 0, v[78:79]
	v_lshl_add_u64 v[78:79], v[104:105], 0, v[78:79]
	global_load_dwordx4 v[86:89], v[80:81], off
	v_pk_mul_f32 v[128:129], v[128:129], v[0:1] op_sel_hi:[1,0]
	flat_load_dwordx4 v[78:81], v[78:79]
	s_lshl_b32 s90, s10, 1
	s_xor_b32 s34, s34, 1
	s_waitcnt vmcnt(0)
	v_mov_b32_e32 v130, v86
	v_mov_b32_e32 v131, v88
	s_waitcnt lgkmcnt(0)
	v_mul_f32_e32 v103, 0xbfb8aa3b, v78
	v_exp_f32_e32 v108, v103
	v_mul_f32_e32 v103, 0xbfb8aa3b, v79
	v_exp_f32_e32 v110, v103
	v_mul_f32_e32 v103, 0xbfb8aa3b, v80
	v_exp_f32_e32 v109, v103
	v_mul_f32_e32 v103, 0xbfb8aa3b, v81
	v_exp_f32_e32 v111, v103
	v_pk_mul_f32 v[128:129], v[130:131], v[128:129]
	v_pk_add_f32 v[108:109], v[108:109], 1.0 op_sel_hi:[1,0]
	v_mov_b32_e32 v130, v78
	v_mov_b32_e32 v131, v80
	v_rcp_f32_e32 v109, v109
	s_nop 0
	s_nop 0
	v_mov_b32_e32 v84, v83
	v_rcp_f32_e32 v108, v108
	s_nop 0
	v_pk_mul_f32 v[82:83], v[84:85], v[0:1] op_sel_hi:[1,0]
	v_pk_add_f32 v[84:85], v[110:111], 1.0 op_sel_hi:[1,0]
	v_mov_b32_e32 v88, v87
	v_pk_mul_f32 v[82:83], v[88:89], v[82:83]
	v_pk_mul_f32 v[108:109], v[130:131], v[108:109]
	v_rcp_f32_e32 v85, v85
	s_nop 0
	v_pk_mul_f32 v[108:109], v[108:109], v[128:129]
	v_mov_b32_e32 v128, v74
	v_mov_b32_e32 v129, v76
	v_rcp_f32_e32 v84, v84
	s_nop 0
	v_mov_b32_e32 v80, v79
	v_pk_mul_f32 v[78:79], v[80:81], v[84:85]
	v_pk_mul_f32 v[78:79], v[78:79], v[82:83]
	v_cvt_pk_bf16_f32 v79, v109, v79
	v_cvt_pk_bf16_f32 v78, v108, v78
	v_lshl_add_u64 v[80:81], s[76:77], 0, v[106:107]
	v_lshl_add_u64 v[86:87], v[80:81], 0, s[90:91]
	v_lshl_add_u64 v[80:81], v[94:95], 1, v[86:87]
	flat_store_dwordx2 v[80:81], v[78:79]
	v_lshlrev_b64 v[78:79], 2, v[98:99]
	v_lshl_add_u64 v[106:107], v[104:105], 0, v[78:79]
	v_lshl_add_u64 v[88:89], s[84:85], 0, v[78:79]
	flat_load_dwordx4 v[78:81], v[106:107] offset:64
	global_load_dwordx4 v[82:85], v[88:89], off offset:64
	v_pk_mul_f32 v[128:129], v[128:129], v[0:1] op_sel_hi:[1,0]
	s_waitcnt vmcnt(0) lgkmcnt(0)
	v_mul_f32_e32 v103, 0xbfb8aa3b, v78
	v_exp_f32_e32 v108, v103
	v_mul_f32_e32 v103, 0xbfb8aa3b, v79
	v_exp_f32_e32 v110, v103
	v_mul_f32_e32 v103, 0xbfb8aa3b, v80
	v_exp_f32_e32 v109, v103
	v_mov_b32_e32 v130, v82
	v_mul_f32_e32 v103, 0xbfb8aa3b, v81
	v_mov_b32_e32 v131, v84
	v_pk_add_f32 v[108:109], v[108:109], 1.0 op_sel_hi:[1,0]
	v_exp_f32_e32 v111, v103
	v_pk_mul_f32 v[128:129], v[130:131], v[128:129]
	v_mov_b32_e32 v130, v78
	v_mov_b32_e32 v131, v80
	v_rcp_f32_e32 v109, v109
	s_nop 0
	s_nop 0
	v_mov_b32_e32 v76, v75
	v_rcp_f32_e32 v108, v108
	s_nop 0
	v_pk_mul_f32 v[74:75], v[76:77], v[0:1] op_sel_hi:[1,0]
	v_pk_add_f32 v[76:77], v[110:111], 1.0 op_sel_hi:[1,0]
	v_mov_b32_e32 v84, v83
	v_pk_mul_f32 v[74:75], v[84:85], v[74:75]
	v_pk_mul_f32 v[108:109], v[130:131], v[108:109]
	v_rcp_f32_e32 v77, v77
	s_nop 0
	v_pk_mul_f32 v[108:109], v[128:129], v[108:109]
	v_rcp_f32_e32 v76, v76
	s_nop 0
	v_mov_b32_e32 v80, v79
	v_pk_mul_f32 v[76:77], v[80:81], v[76:77]
	s_nop 0
	v_pk_mul_f32 v[74:75], v[74:75], v[76:77]
	v_cvt_pk_bf16_f32 v75, v109, v75
	v_cvt_pk_bf16_f32 v74, v108, v74
	v_lshl_add_u64 v[78:79], v[98:99], 1, v[86:87]
	flat_store_dwordx2 v[78:79], v[74:75] offset:32
	global_load_dwordx4 v[82:85], v[88:89], off offset:128
	s_nop 0
	flat_load_dwordx4 v[74:77], v[106:107] offset:128
	v_mov_b32_e32 v106, v70
	v_mov_b32_e32 v107, v72
	v_pk_mul_f32 v[106:107], v[106:107], v[0:1] op_sel_hi:[1,0]
	s_waitcnt vmcnt(0)
	v_mov_b32_e32 v108, v82
	s_waitcnt lgkmcnt(0)
	v_mul_f32_e32 v81, 0xbfb8aa3b, v75
	v_mul_f32_e32 v80, 0xbfb8aa3b, v74
	v_exp_f32_e32 v88, v81
	v_mul_f32_e32 v81, 0xbfb8aa3b, v76
	v_exp_f32_e32 v80, v80
	v_exp_f32_e32 v81, v81
	v_mov_b32_e32 v109, v84
	v_mul_f32_e32 v89, 0xbfb8aa3b, v77
	v_exp_f32_e32 v89, v89
	v_pk_add_f32 v[80:81], v[80:81], 1.0 op_sel_hi:[1,0]
	v_pk_mul_f32 v[106:107], v[108:109], v[106:107]
	v_mov_b32_e32 v108, v74
	v_mov_b32_e32 v109, v76
	v_rcp_f32_e32 v81, v81
	s_nop 0
	s_nop 0
	v_mov_b32_e32 v72, v71
	v_rcp_f32_e32 v80, v80
	s_nop 0
	v_pk_mul_f32 v[70:71], v[72:73], v[0:1] op_sel_hi:[1,0]
	v_pk_add_f32 v[72:73], v[88:89], 1.0 op_sel_hi:[1,0]
	v_mov_b32_e32 v84, v83
	v_pk_mul_f32 v[70:71], v[84:85], v[70:71]
	v_pk_mul_f32 v[80:81], v[108:109], v[80:81]
	v_rcp_f32_e32 v73, v73
	s_nop 0
	v_pk_mul_f32 v[80:81], v[106:107], v[80:81]
	v_rcp_f32_e32 v72, v72
	s_nop 0
	v_mov_b32_e32 v76, v75
	v_pk_mul_f32 v[72:73], v[76:77], v[72:73]
	v_mov_b32_e32 v82, v66
	v_pk_mul_f32 v[70:71], v[70:71], v[72:73]
	v_cvt_pk_bf16_f32 v71, v81, v71
	v_cvt_pk_bf16_f32 v70, v80, v70
	v_lshlrev_b64 v[74:75], 2, v[96:97]
	flat_store_dwordx2 v[78:79], v[70:71] offset:64
	v_lshl_add_u64 v[70:71], s[84:85], 0, v[74:75]
	v_lshl_add_u64 v[74:75], v[104:105], 0, v[74:75]
	flat_load_dwordx4 v[74:77], v[74:75]
	v_mov_b32_e32 v83, v68
	global_load_dwordx4 v[70:73], v[70:71], off
	v_pk_mul_f32 v[82:83], v[82:83], v[0:1] op_sel_hi:[1,0]
	s_waitcnt vmcnt(0) lgkmcnt(0)
	v_mul_f32_e32 v79, 0xbfb8aa3b, v75
	v_mul_f32_e32 v78, 0xbfb8aa3b, v74
	v_exp_f32_e32 v80, v79
	v_mul_f32_e32 v79, 0xbfb8aa3b, v76
	v_exp_f32_e32 v78, v78
	v_exp_f32_e32 v79, v79
	v_mov_b32_e32 v84, v70
	v_mov_b32_e32 v85, v72
	v_pk_mul_f32 v[82:83], v[82:83], v[84:85]
	v_pk_add_f32 v[78:79], v[78:79], 1.0 op_sel_hi:[1,0]
	v_mul_f32_e32 v81, 0xbfb8aa3b, v77
	v_exp_f32_e32 v81, v81
	v_mov_b32_e32 v85, v76
	v_mov_b32_e32 v76, v75
	v_rcp_f32_e32 v79, v79
	s_nop 0
	s_nop 0
	v_mov_b32_e32 v68, v67
	v_rcp_f32_e32 v78, v78
	s_nop 0
	v_pk_mul_f32 v[66:67], v[68:69], v[0:1] op_sel_hi:[1,0]
	v_pk_add_f32 v[68:69], v[80:81], 1.0 op_sel_hi:[1,0]
	v_mov_b32_e32 v72, v71
	v_pk_mul_f32 v[66:67], v[66:67], v[72:73]
	v_mov_b32_e32 v84, v74
	v_pk_mul_f32 v[78:79], v[84:85], v[78:79]
	v_rcp_f32_e32 v69, v69
	s_nop 0
	v_pk_mul_f32 v[78:79], v[82:83], v[78:79]
	v_rcp_f32_e32 v68, v68
	s_nop 0
	v_pk_mul_f32 v[68:69], v[76:77], v[68:69]
	v_pk_mul_f32 v[66:67], v[66:67], v[68:69]
	v_cvt_pk_bf16_f32 v67, v79, v67
	v_cvt_pk_bf16_f32 v66, v78, v66
	v_lshl_add_u64 v[68:69], v[96:97], 1, v[86:87]
	s_andn2_b64 vcc, exec, s[82:83]
	flat_store_dwordx2 v[68:69], v[66:67]
	s_cbranch_vccnz .LBB0_1206
	v_sub_f32_e32 v0, v2, v10
	v_mul_f32_e32 v66, 0x3fb8aa3b, v0
	v_mul_f32_e32 v0, 0xbfb8aa3b, v0
	v_exp_f32_e32 v70, v0
	v_sub_f32_e32 v0, v3, v11
	v_mul_f32_e32 v67, 0x3fb8aa3b, v0
	v_mul_f32_e32 v0, 0xbfb8aa3b, v0
	v_exp_f32_e32 v72, v0
	v_sub_f32_e32 v0, v4, v12
	v_exp_f32_e32 v68, v67
	v_mul_f32_e32 v67, 0x3fb8aa3b, v0
	v_mul_f32_e32 v0, 0xbfb8aa3b, v0
	v_exp_f32_e32 v71, v0
	v_sub_f32_e32 v0, v5, v13
	v_mul_f32_e32 v69, 0x3fb8aa3b, v0
	v_mul_f32_e32 v0, 0xbfb8aa3b, v0
	v_exp_f32_e32 v73, v0
	v_sub_f32_e32 v0, v6, v14
	v_mul_f32_e32 v74, 0x3fb8aa3b, v0
	v_mul_f32_e32 v0, 0xbfb8aa3b, v0
	v_exp_f32_e32 v66, v66
	v_exp_f32_e32 v67, v67
	v_exp_f32_e32 v76, v0
	v_sub_f32_e32 v0, v7, v15
	v_mul_f32_e32 v75, 0x3fb8aa3b, v0
	v_mul_f32_e32 v0, 0xbfb8aa3b, v0
	v_exp_f32_e32 v69, v69
	v_exp_f32_e32 v80, v0
	v_sub_f32_e32 v0, v8, v16
	v_mov_b32_e32 v82, v18
	v_mov_b32_e32 v83, v20
	v_exp_f32_e32 v78, v75
	v_mul_f32_e32 v75, 0x3fb8aa3b, v0
	v_mul_f32_e32 v0, 0xbfb8aa3b, v0
	v_pk_mul_f32 v[82:83], v[82:83], s[36:37] op_sel_hi:[1,0]
	v_exp_f32_e32 v74, v74
	v_exp_f32_e32 v75, v75
	v_exp_f32_e32 v77, v0
	v_sub_f32_e32 v0, v9, v17
	v_pk_mul_f32 v[66:67], v[82:83], v[66:67]
	v_mov_b32_e32 v82, v19
	v_mov_b32_e32 v83, v21
	v_mul_f32_e32 v79, 0x3fb8aa3b, v0
	v_pk_mul_f32 v[82:83], v[82:83], s[36:37] op_sel_hi:[1,0]
	v_exp_f32_e32 v79, v79
	v_pk_mul_f32 v[68:69], v[82:83], v[68:69]
	v_mov_b32_e32 v82, v22
	v_mov_b32_e32 v83, v24
	v_pk_mul_f32 v[82:83], v[82:83], s[36:37] op_sel_hi:[1,0]
	v_mul_f32_e32 v0, 0xbfb8aa3b, v0
	v_pk_mul_f32 v[74:75], v[82:83], v[74:75]
	v_mov_b32_e32 v82, v23
	v_mov_b32_e32 v83, v25
	v_pk_mul_f32 v[82:83], v[82:83], s[36:37] op_sel_hi:[1,0]
	v_bfe_u32 v84, v68, 16, 1
	v_pk_mul_f32 v[78:79], v[82:83], v[78:79]
	v_exp_f32_e32 v81, v0
	v_bfe_u32 v82, v78, 16, 1
	v_bfe_u32 v0, v79, 16, 1
	v_bfe_u32 v83, v69, 16, 1
	v_add3_u32 v84, v68, v84, s23
	v_add3_u32 v68, v78, v82, s23
	v_bfe_u32 v82, v75, 16, 1
	v_add3_u32 v83, v69, v83, s23
	v_add3_u32 v0, v79, v0, s23
	v_bfe_u32 v69, v66, 16, 1
	v_bfe_u32 v78, v67, 16, 1
	v_bfe_u32 v79, v74, 16, 1
	v_add3_u32 v75, v75, v82, s23
	s_mul_i32 s10, s34, 0xd800
	v_add3_u32 v74, v74, v79, s23
	v_add3_u32 v67, v67, v78, s23
	v_add3_u32 v66, v66, v69, s23
	v_lshrrev_b32_e32 v69, 16, v75
	s_add_i32 s10, s10, 0
	v_lshrrev_b32_e32 v66, 16, v66
	v_lshrrev_b32_e32 v67, 16, v67
	v_lshrrev_b32_e32 v74, 16, v74
	v_and_or_b32 v69, v0, s15, v69
	v_lshlrev_b32_e32 v0, 1, v92
	v_and_or_b32 v68, v68, s15, v74
	v_and_or_b32 v67, v83, s15, v67
	v_and_or_b32 v66, v84, s15, v66
	v_add3_u32 v0, s10, v113, v0
	ds_write_b128 v0, v[66:69]
	v_mov_b32_e32 v68, v27
	v_mov_b32_e32 v69, v29
	v_mov_b32_e32 v66, v26
	v_mov_b32_e32 v67, v28
	v_pk_mul_f32 v[68:69], v[68:69], v[72:73]
	v_mov_b32_e32 v72, v51
	v_mov_b32_e32 v73, v53
	v_pk_mul_f32 v[66:67], v[66:67], v[70:71]
	v_mov_b32_e32 v70, v50
	v_mov_b32_e32 v71, v52
	v_pk_mul_f32 v[72:73], v[72:73], v[80:81]
	v_pk_mul_f32 v[70:71], v[70:71], v[76:77]
	v_bfe_u32 v74, v73, 16, 1
	v_bfe_u32 v75, v72, 16, 1
	v_bfe_u32 v76, v69, 16, 1
	v_bfe_u32 v77, v68, 16, 1
	v_add3_u32 v77, v68, v77, s23
	v_add3_u32 v76, v69, v76, s23
	v_add3_u32 v68, v72, v75, s23
	v_add3_u32 v69, v73, v74, s23
	v_bfe_u32 v72, v66, 16, 1
	v_bfe_u32 v73, v67, 16, 1
	v_bfe_u32 v74, v70, 16, 1
	v_bfe_u32 v75, v71, 16, 1
	v_add3_u32 v71, v71, v75, s23
	v_add3_u32 v70, v70, v74, s23
	v_add3_u32 v67, v67, v73, s23
	v_add3_u32 v66, v66, v72, s23
	v_lshrrev_b32_e32 v66, 16, v66
	v_lshrrev_b32_e32 v67, 16, v67
	v_lshrrev_b32_e32 v70, 16, v70
	v_lshrrev_b32_e32 v71, 16, v71
	v_and_or_b32 v69, v69, s15, v71
	v_and_or_b32 v68, v68, s15, v70
	v_and_or_b32 v67, v76, s15, v67
	v_and_or_b32 v66, v77, s15, v66
	ds_write_b128 v0, v[66:69] offset:9216
	v_mul_f32_e32 v0, 0x3fb8aa3b, v112
	v_exp_f32_e32 v0, v0
	v_bfe_u32 v66, v30, 16, 1
	v_add3_u32 v66, v30, v66, s23
	v_lshl_add_u32 v67, v114, 1, s10
	ds_write_b16_d16_hi v67, v66 offset:18432
	v_mul_f32_e32 v66, v0, v46
	v_bfe_u32 v68, v66, 16, 1
	v_add3_u32 v66, v66, v68, s23
	ds_write_b16_d16_hi v67, v66 offset:36864
	v_bfe_u32 v66, v31, 16, 1
	v_add3_u32 v66, v31, v66, s23
	ds_write_b16_d16_hi v67, v66 offset:18576
	v_mul_f32_e32 v66, v0, v47
	v_bfe_u32 v68, v66, 16, 1
	v_add3_u32 v66, v66, v68, s23
	ds_write_b16_d16_hi v67, v66 offset:37008
	v_bfe_u32 v66, v32, 16, 1
	v_add3_u32 v66, v32, v66, s23
	ds_write_b16_d16_hi v67, v66 offset:18720
	v_mul_f32_e32 v66, v0, v48
	v_bfe_u32 v68, v66, 16, 1
	v_add3_u32 v66, v66, v68, s23
	ds_write_b16_d16_hi v67, v66 offset:37152
	v_bfe_u32 v66, v33, 16, 1
	v_add3_u32 v66, v33, v66, s23
	ds_write_b16_d16_hi v67, v66 offset:18864
	v_mul_f32_e32 v66, v0, v49
	v_bfe_u32 v68, v66, 16, 1
	v_add3_u32 v66, v66, v68, s23
	ds_write_b16_d16_hi v67, v66 offset:37296
	v_bfe_u32 v66, v34, 16, 1
	v_add3_u32 v66, v34, v66, s23
	ds_write_b16_d16_hi v67, v66 offset:19008
	v_mul_f32_e32 v66, v0, v54
	v_bfe_u32 v68, v66, 16, 1
	v_add3_u32 v66, v66, v68, s23
	ds_write_b16_d16_hi v67, v66 offset:37440
	v_bfe_u32 v66, v35, 16, 1
	v_add3_u32 v66, v35, v66, s23
	ds_write_b16_d16_hi v67, v66 offset:19152
	v_mul_f32_e32 v66, v0, v55
	v_bfe_u32 v68, v66, 16, 1
	v_add3_u32 v66, v66, v68, s23
	ds_write_b16_d16_hi v67, v66 offset:37584
	v_bfe_u32 v66, v36, 16, 1
	v_add3_u32 v66, v36, v66, s23
	ds_write_b16_d16_hi v67, v66 offset:19296
	v_mul_f32_e32 v66, v0, v56
	v_bfe_u32 v68, v66, 16, 1
	v_add3_u32 v66, v66, v68, s23
	ds_write_b16_d16_hi v67, v66 offset:37728
	v_bfe_u32 v66, v37, 16, 1
	v_add3_u32 v66, v37, v66, s23
	ds_write_b16_d16_hi v67, v66 offset:19440
	v_mul_f32_e32 v66, v0, v57
	v_bfe_u32 v68, v66, 16, 1
	v_add3_u32 v66, v66, v68, s23
	ds_write_b16_d16_hi v67, v66 offset:37872
	v_bfe_u32 v66, v38, 16, 1
	v_add3_u32 v66, v38, v66, s23
	ds_write_b16_d16_hi v67, v66 offset:19584
	v_mul_f32_e32 v66, v0, v58
	v_bfe_u32 v68, v66, 16, 1
	v_add3_u32 v66, v66, v68, s23
	ds_write_b16_d16_hi v67, v66 offset:38016
	v_bfe_u32 v66, v39, 16, 1
	v_add3_u32 v66, v39, v66, s23
	ds_write_b16_d16_hi v67, v66 offset:19728
	v_mul_f32_e32 v66, v0, v59
	v_bfe_u32 v68, v66, 16, 1
	v_add3_u32 v66, v66, v68, s23
	ds_write_b16_d16_hi v67, v66 offset:38160
	v_bfe_u32 v66, v40, 16, 1
	v_add3_u32 v66, v40, v66, s23
	ds_write_b16_d16_hi v67, v66 offset:19872
	v_mul_f32_e32 v66, v0, v60
	v_bfe_u32 v68, v66, 16, 1
	v_add3_u32 v66, v66, v68, s23
	ds_write_b16_d16_hi v67, v66 offset:38304
	v_bfe_u32 v66, v41, 16, 1
	v_add3_u32 v66, v41, v66, s23
	ds_write_b16_d16_hi v67, v66 offset:20016
	v_mul_f32_e32 v66, v0, v61
	v_bfe_u32 v68, v66, 16, 1
	v_add3_u32 v66, v66, v68, s23
	ds_write_b16_d16_hi v67, v66 offset:38448
	v_bfe_u32 v66, v42, 16, 1
	v_add3_u32 v66, v42, v66, s23
	ds_write_b16_d16_hi v67, v66 offset:20160
	v_mul_f32_e32 v66, v0, v62
	v_bfe_u32 v68, v66, 16, 1
	v_add3_u32 v66, v66, v68, s23
	ds_write_b16_d16_hi v67, v66 offset:38592
	v_bfe_u32 v66, v43, 16, 1
	v_add3_u32 v66, v43, v66, s23
	ds_write_b16_d16_hi v67, v66 offset:20304
	v_mul_f32_e32 v66, v0, v63
	v_bfe_u32 v68, v66, 16, 1
	v_add3_u32 v66, v66, v68, s23
	ds_write_b16_d16_hi v67, v66 offset:38736
	v_bfe_u32 v66, v44, 16, 1
	v_add3_u32 v66, v44, v66, s23
	ds_write_b16_d16_hi v67, v66 offset:20448
	v_mul_f32_e32 v66, v0, v64
	v_bfe_u32 v68, v66, 16, 1
	v_add3_u32 v66, v66, v68, s23
	ds_write_b16_d16_hi v67, v66 offset:38880
	v_bfe_u32 v66, v45, 16, 1
	v_add3_u32 v66, v45, v66, s23
	v_mul_f32_e32 v0, v0, v65
	ds_write_b16_d16_hi v67, v66 offset:20592
	v_bfe_u32 v66, v0, 16, 1
	v_add3_u32 v0, v0, v66, s23
	ds_write_b16_d16_hi v67, v0 offset:39024
	s_branch .LBB0_1206

.LBB0_1222:
	v_ashrrev_i32_e32 v2, 6, v4
	v_ashrrev_i32_e32 v3, 31, v2
	v_lshlrev_b64 v[6:7], 6, v[2:3]
	v_and_b32_e32 v0, 56, v4
	v_lshl_add_u64 v[8:9], s[38:39], 0, v[6:7]
	v_lshl_add_u64 v[10:11], s[40:41], 0, v[6:7]
	v_lshl_add_u64 v[6:7], s[42:43], 0, v[6:7]
	v_lshl_add_u64 v[8:9], v[8:9], 0, v[0:1]
	v_lshl_add_u64 v[10:11], v[10:11], 0, v[0:1]
	v_lshl_add_u64 v[6:7], v[6:7], 0, v[0:1]
	flat_load_dwordx2 v[8:9], v[8:9]
	s_mov_b32 s8, 0x1000000
	flat_load_dwordx2 v[10:11], v[10:11]
	v_add_u32_e32 v4, s84, v4
	flat_load_dwordx2 v[6:7], v[6:7]
	s_waitcnt vmcnt(0) lgkmcnt(0)
	v_max3_f32 v0, v8, v10, v6
	v_sub_f32_e32 v8, v8, v0
	v_mul_f32_e32 v8, 0x3fb8aa3b, v8
	v_exp_f32_e32 v14, v8
	v_sub_f32_e32 v8, v10, v0
	v_sub_f32_e32 v0, v6, v0
	v_mul_f32_e32 v8, 0x3fb8aa3b, v8
	v_mul_f32_e32 v0, 0x3fb8aa3b, v0
	v_exp_f32_e32 v17, v8
	v_exp_f32_e32 v16, v0
	v_mov_b32_e32 v10, v7
	v_fma_f32 v0, v9, v14, 0
	v_pk_mul_f32 v[6:7], v[10:11], v[16:17]
	s_nop 0
	v_add_f32_e32 v0, v7, v0
	v_add_f32_e32 v15, v6, v0
	v_lshlrev_b64 v[6:7], 10, v[2:3]
	v_and_b32_e32 v0, 0x1f8, v5
	v_lshl_add_u64 v[6:7], s[6:7], 0, v[6:7]
	v_lshlrev_b32_e32 v0, 1, v0
	v_lshl_add_u64 v[10:11], v[6:7], 0, v[0:1]
	flat_load_dwordx4 v[6:9], v[10:11]
	v_lshlrev_b64 v[2:3], 12, v[2:3]
	v_lshl_add_u64 v[2:3], s[0:1], 0, v[2:3]
	v_lshl_add_u64 v[2:3], v[2:3], 0, v[0:1]
	v_add_u32_e32 v5, s12, v5
	s_waitcnt vmcnt(0) lgkmcnt(0)
	v_lshlrev_b32_e32 v18, 16, v6
	v_and_b32_e32 v20, 0xffff0000, v6
	v_add_co_u32_e32 v6, vcc, s19, v10
	v_lshlrev_b32_e32 v19, 16, v7
	v_and_b32_e32 v21, 0xffff0000, v7
	v_addc_co_u32_e32 v7, vcc, 0, v11, vcc
	v_add_co_u32_e32 v10, vcc, s8, v10
	v_lshlrev_b32_e32 v22, 16, v8
	v_and_b32_e32 v24, 0xffff0000, v8
	v_lshlrev_b32_e32 v23, 16, v9
	v_and_b32_e32 v25, 0xffff0000, v9
	flat_load_dwordx4 v[6:9], v[6:7]
	v_addc_co_u32_e32 v11, vcc, 0, v11, vcc
	flat_load_dwordx4 v[10:13], v[10:11]
	v_pk_fma_f32 v[18:19], v[14:15], v[18:19], 0 op_sel_hi:[0,1,0]
	v_pk_fma_f32 v[20:21], v[14:15], v[20:21], 0 op_sel_hi:[0,1,0]
	v_mov_b32_e32 v30, v17
	v_rcp_f32_e32 v26, v15
	s_nop 0
	v_add_co_u32_e32 v2, vcc, 0x23c00000, v2
	s_mov_b32 s8, 0x7ffff
	s_nop 0
	v_addc_co_u32_e32 v3, vcc, 0, v3, vcc
	v_cmp_lt_i32_e32 vcc, s8, v4
	s_or_b64 s[44:45], vcc, s[44:45]
	s_waitcnt vmcnt(0) lgkmcnt(0)
	v_lshlrev_b32_e32 v29, 16, v7
	v_lshlrev_b32_e32 v28, 16, v6
	v_and_b32_e32 v7, 0xffff0000, v7
	v_and_b32_e32 v6, 0xffff0000, v6
	v_pk_fma_f32 v[18:19], v[30:31], v[28:29], v[18:19] op_sel_hi:[0,1,1]
	v_pk_fma_f32 v[6:7], v[30:31], v[6:7], v[20:21] op_sel_hi:[0,1,1]
	v_lshlrev_b32_e32 v21, 16, v11
	v_lshlrev_b32_e32 v20, 16, v10
	v_pk_fma_f32 v[18:19], v[16:17], v[20:21], v[18:19] op_sel_hi:[0,1,1]
	v_and_b32_e32 v11, 0xffff0000, v11
	v_and_b32_e32 v10, 0xffff0000, v10
	v_pk_fma_f32 v[6:7], v[16:17], v[10:11], v[6:7] op_sel_hi:[0,1,1]
	v_pk_mul_f32 v[10:11], v[18:19], v[26:27] op_sel_hi:[1,0]
	v_pk_fma_f32 v[18:19], v[14:15], v[22:23], 0 op_sel_hi:[0,1,0]
	v_pk_fma_f32 v[14:15], v[14:15], v[24:25], 0 op_sel_hi:[0,1,0]
	v_lshlrev_b32_e32 v21, 16, v9
	v_lshlrev_b32_e32 v20, 16, v8
	v_and_b32_e32 v9, 0xffff0000, v9
	v_and_b32_e32 v8, 0xffff0000, v8
	v_pk_fma_f32 v[8:9], v[30:31], v[8:9], v[14:15] op_sel_hi:[0,1,1]
	v_lshlrev_b32_e32 v15, 16, v13
	v_lshlrev_b32_e32 v14, 16, v12
	v_and_b32_e32 v13, 0xffff0000, v13
	v_and_b32_e32 v12, 0xffff0000, v12
	v_pk_fma_f32 v[18:19], v[30:31], v[20:21], v[18:19] op_sel_hi:[0,1,1]
	v_pk_fma_f32 v[8:9], v[16:17], v[12:13], v[8:9] op_sel_hi:[0,1,1]
	v_pk_mul_f32 v[6:7], v[6:7], v[26:27] op_sel_hi:[1,0]
	v_pk_fma_f32 v[14:15], v[16:17], v[14:15], v[18:19] op_sel_hi:[0,1,1]
	v_pk_mul_f32 v[8:9], v[8:9], v[26:27] op_sel_hi:[1,0]
	v_pk_mul_f32 v[12:13], v[14:15], v[26:27] op_sel_hi:[1,0]
	v_cvt_pk_bf16_f32 v9, v13, v9
	v_cvt_pk_bf16_f32 v8, v12, v8
	v_cvt_pk_bf16_f32 v7, v11, v7
	v_cvt_pk_bf16_f32 v6, v10, v6
	flat_store_dwordx4 v[2:3], v[6:9] offset:2048
	s_andn2_b64 exec, exec, s[44:45]
	s_cbranch_execnz .LBB0_1222
	s_or_b64 exec, exec, s[44:45]

.LBB0_1549:
	ds_write_b32 v47, v0 offset:16380
	s_waitcnt lgkmcnt(0)
	ds_read_b32 v0, v49
	ds_read_b32 v11, v49 offset:260
	v_lshl_add_u64 v[12:13], s[0:1], 1, v[8:9]
	s_waitcnt lgkmcnt(0)
	v_cvt_pk_bf16_f32 v16, v0, v11
	ds_read_b32 v0, v49 offset:520
	ds_read_b32 v11, v49 offset:780
	s_waitcnt lgkmcnt(1)
	s_waitcnt lgkmcnt(0)
	v_cvt_pk_bf16_f32 v17, v0, v11
	ds_read_b32 v0, v49 offset:1040
	ds_read_b32 v11, v49 offset:1300
	s_waitcnt lgkmcnt(1)
	s_waitcnt lgkmcnt(0)
	v_cvt_pk_bf16_f32 v18, v0, v11
	ds_read_b32 v0, v49 offset:1560
	ds_read_b32 v11, v49 offset:1820
	s_waitcnt lgkmcnt(1)
	s_waitcnt lgkmcnt(0)
	v_add_u32_e32 v14, s8, v48
	v_ashrrev_i32_e32 v15, 31, v14
	v_lshlrev_b64 v[20:21], 12, v[14:15]
	v_cvt_pk_bf16_f32 v19, v0, v11
	v_lshl_add_u64 v[20:21], v[12:13], 0, v[20:21]
	flat_store_dwordx4 v[20:21], v[16:19]
	ds_read_b32 v0, v49 offset:32
	ds_read_b32 v11, v49 offset:292
	v_add_u32_e32 v20, 8, v14
	v_ashrrev_i32_e32 v21, 31, v20
	v_lshlrev_b64 v[20:21], 12, v[20:21]
	s_waitcnt lgkmcnt(0)
	v_cvt_pk_bf16_f32 v16, v0, v11
	ds_read_b32 v0, v49 offset:552
	ds_read_b32 v11, v49 offset:812
	v_lshl_add_u64 v[20:21], v[12:13], 0, v[20:21]
	s_waitcnt lgkmcnt(0)
	v_cvt_pk_bf16_f32 v17, v0, v11
	ds_read_b32 v0, v49 offset:1072
	ds_read_b32 v11, v49 offset:1332
	s_waitcnt lgkmcnt(0)
	v_cvt_pk_bf16_f32 v18, v0, v11
	ds_read_b32 v0, v49 offset:1592
	ds_read_b32 v11, v49 offset:1852
	s_waitcnt lgkmcnt(0)
	v_cvt_pk_bf16_f32 v19, v0, v11
	flat_store_dwordx4 v[20:21], v[16:19]
	ds_read_b32 v0, v49 offset:64
	ds_read_b32 v11, v49 offset:324
	v_add_u32_e32 v20, 16, v14
	v_ashrrev_i32_e32 v21, 31, v20
	v_lshlrev_b64 v[20:21], 12, v[20:21]
	s_waitcnt lgkmcnt(0)
	v_cvt_pk_bf16_f32 v16, v0, v11
	ds_read_b32 v0, v49 offset:584
	ds_read_b32 v11, v49 offset:844
	v_lshl_add_u64 v[20:21], v[12:13], 0, v[20:21]
	s_waitcnt lgkmcnt(0)
	v_cvt_pk_bf16_f32 v17, v0, v11
	ds_read_b32 v0, v49 offset:1104
	ds_read_b32 v11, v49 offset:1364
	s_waitcnt lgkmcnt(0)
	v_cvt_pk_bf16_f32 v18, v0, v11
	ds_read_b32 v0, v49 offset:1624
	ds_read_b32 v11, v49 offset:1884
	s_waitcnt lgkmcnt(0)
	v_cvt_pk_bf16_f32 v19, v0, v11
	flat_store_dwordx4 v[20:21], v[16:19]
	ds_read_b32 v0, v49 offset:96
	ds_read_b32 v11, v49 offset:356
	v_add_u32_e32 v20, 24, v14
	v_ashrrev_i32_e32 v21, 31, v20
	v_lshlrev_b64 v[20:21], 12, v[20:21]
	s_waitcnt lgkmcnt(0)
	v_cvt_pk_bf16_f32 v16, v0, v11
	ds_read_b32 v0, v49 offset:616
	ds_read_b32 v11, v49 offset:876
	v_lshl_add_u64 v[20:21], v[12:13], 0, v[20:21]
	s_waitcnt lgkmcnt(0)
	v_cvt_pk_bf16_f32 v17, v0, v11
	ds_read_b32 v0, v49 offset:1136
	ds_read_b32 v11, v49 offset:1396
	s_waitcnt lgkmcnt(0)
	v_cvt_pk_bf16_f32 v18, v0, v11
	ds_read_b32 v0, v49 offset:1656
	ds_read_b32 v11, v49 offset:1916
	s_waitcnt lgkmcnt(0)
	v_cvt_pk_bf16_f32 v19, v0, v11
	flat_store_dwordx4 v[20:21], v[16:19]
	ds_read_b32 v0, v49 offset:128
	ds_read_b32 v11, v49 offset:388
	v_add_u32_e32 v20, 32, v14
	v_ashrrev_i32_e32 v21, 31, v20
	v_lshlrev_b64 v[20:21], 12, v[20:21]
	s_waitcnt lgkmcnt(0)
	v_cvt_pk_bf16_f32 v16, v0, v11
	ds_read_b32 v0, v49 offset:648
	ds_read_b32 v11, v49 offset:908
	v_lshl_add_u64 v[20:21], v[12:13], 0, v[20:21]
	s_waitcnt lgkmcnt(0)
	v_cvt_pk_bf16_f32 v17, v0, v11
	ds_read_b32 v0, v49 offset:1168
	ds_read_b32 v11, v49 offset:1428
	s_waitcnt lgkmcnt(0)
	v_cvt_pk_bf16_f32 v18, v0, v11
	ds_read_b32 v0, v49 offset:1688
	ds_read_b32 v11, v49 offset:1948
	s_waitcnt lgkmcnt(0)
	v_cvt_pk_bf16_f32 v19, v0, v11
	flat_store_dwordx4 v[20:21], v[16:19]
	ds_read_b32 v0, v49 offset:160
	ds_read_b32 v11, v49 offset:420
	v_add_u32_e32 v20, 40, v14
	v_ashrrev_i32_e32 v21, 31, v20
	v_lshlrev_b64 v[20:21], 12, v[20:21]
	s_waitcnt lgkmcnt(0)
	v_cvt_pk_bf16_f32 v16, v0, v11
	ds_read_b32 v0, v49 offset:680
	ds_read_b32 v11, v49 offset:940
	v_lshl_add_u64 v[20:21], v[12:13], 0, v[20:21]
	s_waitcnt lgkmcnt(0)
	v_cvt_pk_bf16_f32 v17, v0, v11
	ds_read_b32 v0, v49 offset:1200
	ds_read_b32 v11, v49 offset:1460
	s_waitcnt lgkmcnt(0)
	v_cvt_pk_bf16_f32 v18, v0, v11
	ds_read_b32 v0, v49 offset:1720
	ds_read_b32 v11, v49 offset:1980
	s_waitcnt lgkmcnt(0)
	v_cvt_pk_bf16_f32 v19, v0, v11
	flat_store_dwordx4 v[20:21], v[16:19]
	ds_read_b32 v0, v49 offset:192
	ds_read_b32 v11, v49 offset:452
	v_add_u32_e32 v20, 48, v14
	v_ashrrev_i32_e32 v21, 31, v20
	v_lshlrev_b64 v[20:21], 12, v[20:21]
	s_waitcnt lgkmcnt(0)
	v_cvt_pk_bf16_f32 v16, v0, v11
	ds_read_b32 v0, v49 offset:712
	ds_read_b32 v11, v49 offset:972
	v_lshl_add_u64 v[20:21], v[12:13], 0, v[20:21]
	v_add_u32_e32 v14, 56, v14
	s_waitcnt lgkmcnt(0)
	v_cvt_pk_bf16_f32 v17, v0, v11
	ds_read_b32 v0, v49 offset:1232
	ds_read_b32 v11, v49 offset:1492
	s_waitcnt lgkmcnt(0)
	v_cvt_pk_bf16_f32 v18, v0, v11
	ds_read_b32 v0, v49 offset:1752
	ds_read_b32 v11, v49 offset:2012
	s_waitcnt lgkmcnt(0)
	v_cvt_pk_bf16_f32 v19, v0, v11
	flat_store_dwordx4 v[20:21], v[16:19]
	ds_read_b32 v0, v49 offset:224
	ds_read_b32 v11, v49 offset:484
	s_waitcnt lgkmcnt(0)
	v_cvt_pk_bf16_f32 v16, v0, v11
	ds_read_b32 v0, v49 offset:744
	ds_read_b32 v11, v49 offset:1004
	s_waitcnt lgkmcnt(0)
	v_cvt_pk_bf16_f32 v17, v0, v11
	ds_read_b32 v0, v49 offset:1264
	ds_read_b32 v11, v49 offset:1524
	s_waitcnt lgkmcnt(0)
	v_cvt_pk_bf16_f32 v18, v0, v11
	ds_read_b32 v0, v49 offset:1784
	ds_read_b32 v11, v49 offset:2044
	s_waitcnt lgkmcnt(0)
	v_ashrrev_i32_e32 v15, 31, v14
	v_lshlrev_b64 v[14:15], 12, v[14:15]
	v_cvt_pk_bf16_f32 v19, v0, v11
	v_lshl_add_u64 v[12:13], v[12:13], 0, v[14:15]
	flat_store_dwordx4 v[12:13], v[16:19]
	s_waitcnt lgkmcnt(0)

.LBB0_1551:
	s_cmpk_gt_i32 s7, 0x18ff
	s_mov_b64 s[0:1], -1
	s_cbranch_scc0 .LBB0_1615
	s_cmpk_gt_u32 s7, 0x1cff
	s_cbranch_scc0 .LBB0_1612
	s_cmpk_gt_u32 s7, 0x20ff
	s_cbranch_scc0 .LBB0_1609
	s_cmpk_gt_u32 s7, 0x36ff
	s_cbranch_scc0 .LBB0_1556
	s_add_i32 s0, s7, 0xc900
	s_bfe_u32 s1, s0, 0xb0005
	s_and_b32 s0, s44, 0x7c0
	v_or_b32_e32 v0, s0, v46
	v_readlane_b32 s4, v254, 6
	v_lshlrev_b32_e32 v0, 2, v0
	v_readlane_b32 s5, v254, 7
	s_lshl_b32 s90, s1, 19
	s_nop 0
	v_lshl_add_u64 v[12:13], s[4:5], 0, v[0:1]
	v_lshl_add_u64 v[12:13], v[12:13], 0, s[90:91]
	v_add_co_u32_e32 v14, vcc, 0x2000, v12
	global_load_dword v0, v[12:13], off
	s_nop 0
	v_addc_co_u32_e32 v15, vcc, 0, v13, vcc
	global_load_dword v11, v[14:15], off
	v_add_co_u32_e32 v14, vcc, 0x4000, v12
	s_mov_b32 s4, 0x10000
	s_nop 0
	v_addc_co_u32_e32 v15, vcc, 0, v13, vcc
	v_add_co_u32_e32 v16, vcc, 0x6000, v12
	global_load_dword v14, v[14:15], off
	s_nop 0
	v_addc_co_u32_e32 v17, vcc, 0, v13, vcc
	global_load_dword v15, v[16:17], off
	v_add_co_u32_e32 v16, vcc, 0x8000, v12
	s_lshl_b32 s90, s1, 7
	s_nop 0
	v_addc_co_u32_e32 v17, vcc, 0, v13, vcc
	v_add_co_u32_e32 v18, vcc, 0xa000, v12
	global_load_dword v16, v[16:17], off
	s_nop 0
	v_addc_co_u32_e32 v19, vcc, 0, v13, vcc
	global_load_dword v17, v[18:19], off
	v_add_co_u32_e32 v18, vcc, 0xc000, v12
	s_nop 1
	v_addc_co_u32_e32 v19, vcc, 0, v13, vcc
	v_add_co_u32_e32 v20, vcc, 0xe000, v12
	global_load_dword v18, v[18:19], off
	s_nop 0
	v_addc_co_u32_e32 v21, vcc, 0, v13, vcc
	global_load_dword v19, v[20:21], off
	v_add_co_u32_e32 v20, vcc, s4, v12
	s_mov_b32 s4, 0x12000
	s_nop 0
	v_addc_co_u32_e32 v21, vcc, 0, v13, vcc
	v_add_co_u32_e32 v22, vcc, s4, v12
	s_mov_b32 s4, 0x14000
	s_nop 0
	v_addc_co_u32_e32 v23, vcc, 0, v13, vcc
	global_load_dword v20, v[20:21], off
	s_nop 0
	global_load_dword v21, v[22:23], off
	v_add_co_u32_e32 v22, vcc, s4, v12
	s_mov_b32 s4, 0x1a000
	s_nop 0
	v_addc_co_u32_e32 v23, vcc, 0, v13, vcc
	v_add_co_u32_e32 v24, vcc, s14, v12
	global_load_dword v22, v[22:23], off
	s_nop 0
	v_addc_co_u32_e32 v25, vcc, 0, v13, vcc
	global_load_dword v23, v[24:25], off
	v_add_co_u32_e32 v24, vcc, s9, v12
	s_nop 1
	v_addc_co_u32_e32 v25, vcc, 0, v13, vcc
	v_add_co_u32_e32 v26, vcc, s4, v12
	s_mov_b32 s4, 0x1c000
	s_nop 0
	v_addc_co_u32_e32 v27, vcc, 0, v13, vcc
	global_load_dword v24, v[24:25], off
	s_nop 0
	global_load_dword v25, v[26:27], off
	v_add_co_u32_e32 v26, vcc, s4, v12
	s_mov_b32 s4, 0x1e000
	s_nop 0
	v_addc_co_u32_e32 v27, vcc, 0, v13, vcc
	v_add_co_u32_e32 v28, vcc, s4, v12
	s_mov_b32 s4, 0x20000
	s_nop 0
	v_addc_co_u32_e32 v29, vcc, 0, v13, vcc
	global_load_dword v26, v[26:27], off
	s_nop 0
	global_load_dword v27, v[28:29], off
	v_add_co_u32_e32 v28, vcc, s4, v12
	s_mov_b32 s4, 0x22000
	s_nop 0
	v_addc_co_u32_e32 v29, vcc, 0, v13, vcc
	v_add_co_u32_e32 v30, vcc, s4, v12
	s_mov_b32 s4, 0x24000
	s_nop 0
	v_addc_co_u32_e32 v31, vcc, 0, v13, vcc
	global_load_dword v28, v[28:29], off
	s_nop 0
	global_load_dword v29, v[30:31], off
	v_add_co_u32_e32 v30, vcc, s4, v12
	s_mov_b32 s4, 0x26000
	s_nop 0
	v_addc_co_u32_e32 v31, vcc, 0, v13, vcc
	v_add_co_u32_e32 v32, vcc, s4, v12
	s_mov_b32 s4, 0x28000
	s_nop 0
	v_addc_co_u32_e32 v33, vcc, 0, v13, vcc
	global_load_dword v30, v[30:31], off
	s_nop 0
	global_load_dword v31, v[32:33], off
	v_add_co_u32_e32 v32, vcc, s4, v12
	s_mov_b32 s4, 0x2a000
	s_nop 0
	v_addc_co_u32_e32 v33, vcc, 0, v13, vcc
	v_add_co_u32_e32 v34, vcc, s4, v12
	s_mov_b32 s4, 0x2c000
	s_nop 0
	v_addc_co_u32_e32 v35, vcc, 0, v13, vcc
	global_load_dword v32, v[32:33], off
	s_nop 0
	global_load_dword v33, v[34:35], off
	v_add_co_u32_e32 v34, vcc, s4, v12
	s_mov_b32 s4, 0x2e000
	s_nop 0
	v_addc_co_u32_e32 v35, vcc, 0, v13, vcc
	v_add_co_u32_e32 v36, vcc, s4, v12
	s_mov_b32 s4, 0x30000
	s_nop 0
	v_addc_co_u32_e32 v37, vcc, 0, v13, vcc
	global_load_dword v34, v[34:35], off
	s_nop 0
	global_load_dword v35, v[36:37], off
	v_add_co_u32_e32 v36, vcc, s4, v12
	s_mov_b32 s4, 0x32000
	s_nop 0
	v_addc_co_u32_e32 v37, vcc, 0, v13, vcc
	v_add_co_u32_e32 v38, vcc, s4, v12
	s_mov_b32 s4, 0x34000
	s_nop 0
	v_addc_co_u32_e32 v39, vcc, 0, v13, vcc
	global_load_dword v36, v[36:37], off
	s_nop 0
	global_load_dword v37, v[38:39], off
	v_add_co_u32_e32 v38, vcc, s4, v12
	s_mov_b32 s4, 0x36000
	s_nop 0
	v_addc_co_u32_e32 v39, vcc, 0, v13, vcc
	v_add_co_u32_e32 v40, vcc, s4, v12
	s_mov_b32 s4, 0x38000
	s_nop 0
	v_addc_co_u32_e32 v41, vcc, 0, v13, vcc
	global_load_dword v38, v[38:39], off
	s_nop 0
	global_load_dword v39, v[40:41], off
	v_add_co_u32_e32 v40, vcc, s4, v12
	s_mov_b32 s4, 0x3a000
	s_nop 0
	v_addc_co_u32_e32 v41, vcc, 0, v13, vcc
	global_load_dword v42, v[40:41], off
	v_add_co_u32_e32 v40, vcc, s4, v12
	s_mov_b32 s4, 0x3c000
	s_nop 0
	v_addc_co_u32_e32 v41, vcc, 0, v13, vcc
	global_load_dword v43, v[40:41], off
	v_add_co_u32_e32 v40, vcc, s4, v12
	s_mov_b32 s4, 0x3e000
	s_nop 0
	v_addc_co_u32_e32 v41, vcc, 0, v13, vcc
	global_load_dword v44, v[40:41], off
	v_add_co_u32_e32 v40, vcc, s4, v12
	s_mov_b32 s4, 0x40000
	s_nop 0
	v_addc_co_u32_e32 v41, vcc, 0, v13, vcc
	global_load_dword v45, v[40:41], off
	v_add_co_u32_e32 v40, vcc, s4, v12
	s_mov_b32 s4, 0x42000
	s_nop 0
	v_addc_co_u32_e32 v41, vcc, 0, v13, vcc
	global_load_dword v57, v[40:41], off
	v_add_co_u32_e32 v40, vcc, s4, v12
	s_mov_b32 s4, 0x44000
	s_nop 0
	v_addc_co_u32_e32 v41, vcc, 0, v13, vcc
	global_load_dword v58, v[40:41], off
	v_add_co_u32_e32 v40, vcc, s4, v12
	s_mov_b32 s4, 0x46000
	s_nop 0
	v_addc_co_u32_e32 v41, vcc, 0, v13, vcc
	global_load_dword v59, v[40:41], off
	v_add_co_u32_e32 v40, vcc, s4, v12
	s_mov_b32 s4, 0x48000
	s_nop 0
	v_addc_co_u32_e32 v41, vcc, 0, v13, vcc
	global_load_dword v60, v[40:41], off
	v_add_co_u32_e32 v40, vcc, s4, v12
	s_mov_b32 s4, 0x4a000
	s_nop 0
	v_addc_co_u32_e32 v41, vcc, 0, v13, vcc
	global_load_dword v61, v[40:41], off
	v_add_co_u32_e32 v40, vcc, s4, v12
	s_mov_b32 s4, 0x4c000
	s_nop 0
	v_addc_co_u32_e32 v41, vcc, 0, v13, vcc
	global_load_dword v62, v[40:41], off
	v_add_co_u32_e32 v40, vcc, s4, v12
	s_mov_b32 s4, 0x4e000
	s_nop 0
	v_addc_co_u32_e32 v41, vcc, 0, v13, vcc
	global_load_dword v63, v[40:41], off
	v_add_co_u32_e32 v40, vcc, s4, v12
	s_mov_b32 s4, 0x50000
	s_nop 0
	v_addc_co_u32_e32 v41, vcc, 0, v13, vcc
	global_load_dword v64, v[40:41], off
	v_add_co_u32_e32 v40, vcc, s4, v12
	s_mov_b32 s4, 0x52000
	s_nop 0
	v_addc_co_u32_e32 v41, vcc, 0, v13, vcc
	global_load_dword v65, v[40:41], off
	v_add_co_u32_e32 v40, vcc, s4, v12
	s_mov_b32 s4, 0x54000
	s_nop 0
	v_addc_co_u32_e32 v41, vcc, 0, v13, vcc
	global_load_dword v66, v[40:41], off
	v_add_co_u32_e32 v40, vcc, s4, v12
	s_mov_b32 s4, 0x56000
	s_nop 0
	v_addc_co_u32_e32 v41, vcc, 0, v13, vcc
	global_load_dword v67, v[40:41], off
	v_add_co_u32_e32 v40, vcc, s4, v12
	s_mov_b32 s4, 0x58000
	s_nop 0
	v_addc_co_u32_e32 v41, vcc, 0, v13, vcc
	global_load_dword v68, v[40:41], off
	v_add_co_u32_e32 v40, vcc, s4, v12
	s_mov_b32 s4, 0x5a000
	s_nop 0
	v_addc_co_u32_e32 v41, vcc, 0, v13, vcc
	global_load_dword v69, v[40:41], off
	v_add_co_u32_e32 v40, vcc, s4, v12
	s_mov_b32 s4, 0x5c000
	s_nop 0
	v_addc_co_u32_e32 v41, vcc, 0, v13, vcc
	global_load_dword v70, v[40:41], off
	v_add_co_u32_e32 v40, vcc, s4, v12
	s_mov_b32 s4, 0x5e000
	s_nop 0
	v_addc_co_u32_e32 v41, vcc, 0, v13, vcc
	global_load_dword v71, v[40:41], off
	v_add_co_u32_e32 v40, vcc, s4, v12
	s_mov_b32 s4, 0x60000
	s_nop 0
	v_addc_co_u32_e32 v41, vcc, 0, v13, vcc
	global_load_dword v72, v[40:41], off
	v_add_co_u32_e32 v40, vcc, s4, v12
	s_mov_b32 s4, 0x64000
	s_nop 0
	v_addc_co_u32_e32 v41, vcc, 0, v13, vcc
	global_load_dword v73, v[40:41], off
	v_add_co_u32_e32 v40, vcc, s21, v12
	s_nop 1
	v_addc_co_u32_e32 v41, vcc, 0, v13, vcc
	global_load_dword v74, v[40:41], off
	v_add_co_u32_e32 v40, vcc, s4, v12
	s_mov_b32 s4, 0x66000
	s_nop 0
	v_addc_co_u32_e32 v41, vcc, 0, v13, vcc
	global_load_dword v75, v[40:41], off
	v_add_co_u32_e32 v40, vcc, s4, v12
	s_mov_b32 s4, 0x68000
	s_nop 0
	v_addc_co_u32_e32 v41, vcc, 0, v13, vcc
	global_load_dword v76, v[40:41], off
	v_add_co_u32_e32 v40, vcc, s4, v12
	s_mov_b32 s4, 0x6a000
	s_nop 0
	v_addc_co_u32_e32 v41, vcc, 0, v13, vcc
	global_load_dword v77, v[40:41], off
	v_add_co_u32_e32 v40, vcc, s4, v12
	s_mov_b32 s4, 0x6c000
	s_nop 0
	v_addc_co_u32_e32 v41, vcc, 0, v13, vcc
	global_load_dword v78, v[40:41], off
	v_add_co_u32_e32 v40, vcc, s4, v12
	s_mov_b32 s4, 0x70000
	s_nop 0
	v_addc_co_u32_e32 v41, vcc, 0, v13, vcc
	global_load_dword v79, v[40:41], off
	v_add_co_u32_e32 v40, vcc, s16, v12
	s_nop 1
	v_addc_co_u32_e32 v41, vcc, 0, v13, vcc
	global_load_dword v80, v[40:41], off
	v_add_co_u32_e32 v40, vcc, s4, v12
	s_mov_b32 s4, 0x72000
	s_nop 0
	v_addc_co_u32_e32 v41, vcc, 0, v13, vcc
	global_load_dword v81, v[40:41], off
	v_add_co_u32_e32 v40, vcc, s4, v12
	s_mov_b32 s4, 0x74000
	s_nop 0
	v_addc_co_u32_e32 v41, vcc, 0, v13, vcc
	global_load_dword v82, v[40:41], off
	v_add_co_u32_e32 v40, vcc, s4, v12
	s_mov_b32 s4, 0x76000
	s_nop 0
	v_addc_co_u32_e32 v41, vcc, 0, v13, vcc
	global_load_dword v83, v[40:41], off
	v_add_co_u32_e32 v40, vcc, s4, v12
	s_mov_b32 s4, 0x78000
	s_nop 0
	v_addc_co_u32_e32 v41, vcc, 0, v13, vcc
	global_load_dword v84, v[40:41], off
	v_add_co_u32_e32 v40, vcc, s4, v12
	s_mov_b32 s4, 0x7c000
	s_nop 0
	v_addc_co_u32_e32 v41, vcc, 0, v13, vcc
	global_load_dword v85, v[40:41], off
	v_add_co_u32_e32 v40, vcc, s89, v12
	s_nop 1
	v_addc_co_u32_e32 v41, vcc, 0, v13, vcc
	global_load_dword v86, v[40:41], off
	v_add_co_u32_e32 v40, vcc, s4, v12
	s_mov_b32 s4, 0x7e000
	s_nop 0
	v_addc_co_u32_e32 v41, vcc, 0, v13, vcc
	v_add_co_u32_e32 v12, vcc, s4, v12
	global_load_dword v40, v[40:41], off
	s_nop 0
	v_addc_co_u32_e32 v13, vcc, 0, v13, vcc
	global_load_dword v12, v[12:13], off
	s_waitcnt vmcnt(0)
	ds_write2_b32 v47, v0, v11 offset1:65
	ds_write2_b32 v47, v14, v15 offset0:130 offset1:195
	v_add_u32_e32 v0, 0x400, v47
	ds_write2_b32 v0, v16, v17 offset0:4 offset1:69
	ds_write2_b32 v0, v18, v19 offset0:134 offset1:199
	v_add_u32_e32 v0, 0x800, v47
	ds_write2_b32 v0, v20, v21 offset0:8 offset1:73
	ds_write2_b32 v0, v22, v23 offset0:138 offset1:203
	v_add_u32_e32 v0, 0xc00, v47
	ds_write2_b32 v0, v24, v25 offset0:12 offset1:77
	ds_write2_b32 v0, v26, v27 offset0:142 offset1:207
	v_add_u32_e32 v0, 0x1000, v47
	ds_write2_b32 v0, v28, v29 offset0:16 offset1:81
	ds_write2_b32 v0, v30, v31 offset0:146 offset1:211
	v_add_u32_e32 v0, 0x1400, v47
	ds_write2_b32 v0, v32, v33 offset0:20 offset1:85
	ds_write2_b32 v0, v34, v35 offset0:150 offset1:215
	v_add_u32_e32 v0, 0x1800, v47
	ds_write2_b32 v0, v36, v37 offset0:24 offset1:89
	ds_write2_b32 v0, v38, v39 offset0:154 offset1:219
	v_add_u32_e32 v0, 0x1c00, v47
	ds_write2_b32 v0, v42, v43 offset0:28 offset1:93
	ds_write2_b32 v0, v44, v45 offset0:158 offset1:223
	v_add_u32_e32 v0, 0x2000, v47
	ds_write2_b32 v0, v57, v58 offset0:32 offset1:97
	ds_write2_b32 v0, v59, v60 offset0:162 offset1:227
	v_add_u32_e32 v0, 0x2400, v47
	ds_write2_b32 v0, v61, v62 offset0:36 offset1:101
	ds_write2_b32 v0, v63, v64 offset0:166 offset1:231
	v_add_u32_e32 v0, 0x2800, v47
	ds_write2_b32 v0, v65, v66 offset0:40 offset1:105
	ds_write2_b32 v0, v67, v68 offset0:170 offset1:235
	v_add_u32_e32 v0, 0x2c00, v47
	ds_write2_b32 v0, v69, v70 offset0:44 offset1:109
	ds_write2_b32 v0, v71, v72 offset0:174 offset1:239
	v_add_u32_e32 v0, 0x3000, v47
	ds_write2_b32 v0, v73, v74 offset0:48 offset1:113
	ds_write2_b32 v0, v75, v76 offset0:178 offset1:243
	v_add_u32_e32 v0, 0x3400, v47
	ds_write2_b32 v0, v77, v78 offset0:52 offset1:117
	ds_write2_b32 v0, v79, v80 offset0:182 offset1:247
	v_add_u32_e32 v0, 0x3800, v47
	ds_write2_b32 v0, v81, v82 offset0:56 offset1:121
	ds_write2_b32 v0, v83, v84 offset0:186 offset1:251
	v_add_u32_e32 v0, 0x3c00, v47
	ds_write2_b32 v0, v85, v86 offset0:60 offset1:125
	ds_write2_b32 v0, v40, v12 offset0:190 offset1:255
	s_waitcnt lgkmcnt(0)
	ds_read_b32 v0, v49
	ds_read_b32 v11, v49 offset:260
	v_lshl_add_u64 v[12:13], v[2:3], 0, s[90:91]
	s_waitcnt lgkmcnt(0)
	v_cvt_pk_bf16_f32 v14, v0, v11
	ds_read_b32 v0, v49 offset:520
	ds_read_b32 v11, v49 offset:780
	s_waitcnt lgkmcnt(1)
	s_waitcnt lgkmcnt(0)
	v_cvt_pk_bf16_f32 v15, v0, v11
	ds_read_b32 v0, v49 offset:1040
	ds_read_b32 v11, v49 offset:1300
	s_waitcnt lgkmcnt(1)
	s_waitcnt lgkmcnt(0)
	v_cvt_pk_bf16_f32 v16, v0, v11
	ds_read_b32 v0, v49 offset:1560
	ds_read_b32 v11, v49 offset:1820
	s_waitcnt lgkmcnt(1)
	s_waitcnt lgkmcnt(0)
	v_cvt_pk_bf16_f32 v17, v0, v11
	v_or_b32_e32 v0, s0, v48
	v_mul_u32_u24_e32 v0, 0x1600, v0
	v_lshlrev_b32_e32 v0, 1, v0
	v_lshl_add_u64 v[18:19], v[12:13], 0, v[0:1]
	flat_store_dwordx4 v[18:19], v[14:17]
	ds_read_b32 v0, v49 offset:32
	ds_read_b32 v11, v49 offset:292
	s_waitcnt lgkmcnt(0)
	v_cvt_pk_bf16_f32 v14, v0, v11
	ds_read_b32 v0, v49 offset:552
	ds_read_b32 v11, v49 offset:812
	s_waitcnt lgkmcnt(0)
	v_cvt_pk_bf16_f32 v15, v0, v11
	ds_read_b32 v0, v49 offset:1072
	ds_read_b32 v11, v49 offset:1332
	s_waitcnt lgkmcnt(0)
	v_cvt_pk_bf16_f32 v16, v0, v11
	ds_read_b32 v0, v49 offset:1592
	ds_read_b32 v11, v49 offset:1852
	s_waitcnt lgkmcnt(0)
	v_cvt_pk_bf16_f32 v17, v0, v11
	v_or_b32_e32 v0, s0, v50
	v_mul_u32_u24_e32 v0, 0x1600, v0
	v_lshlrev_b32_e32 v0, 1, v0
	v_lshl_add_u64 v[18:19], v[12:13], 0, v[0:1]
	flat_store_dwordx4 v[18:19], v[14:17]
	ds_read_b32 v0, v49 offset:64
	ds_read_b32 v11, v49 offset:324
	s_waitcnt lgkmcnt(0)
	v_cvt_pk_bf16_f32 v14, v0, v11
	ds_read_b32 v0, v49 offset:584
	ds_read_b32 v11, v49 offset:844
	s_waitcnt lgkmcnt(0)
	v_cvt_pk_bf16_f32 v15, v0, v11
	ds_read_b32 v0, v49 offset:1104
	ds_read_b32 v11, v49 offset:1364
	s_waitcnt lgkmcnt(0)
	v_cvt_pk_bf16_f32 v16, v0, v11
	ds_read_b32 v0, v49 offset:1624
	ds_read_b32 v11, v49 offset:1884
	s_waitcnt lgkmcnt(0)
	v_cvt_pk_bf16_f32 v17, v0, v11
	v_or_b32_e32 v0, s0, v51
	v_mul_u32_u24_e32 v0, 0x1600, v0
	v_lshlrev_b32_e32 v0, 1, v0
	v_lshl_add_u64 v[18:19], v[12:13], 0, v[0:1]
	flat_store_dwordx4 v[18:19], v[14:17]
	ds_read_b32 v0, v49 offset:96
	ds_read_b32 v11, v49 offset:356
	s_waitcnt lgkmcnt(0)
	v_cvt_pk_bf16_f32 v14, v0, v11
	ds_read_b32 v0, v49 offset:616
	ds_read_b32 v11, v49 offset:876
	s_waitcnt lgkmcnt(0)
	v_cvt_pk_bf16_f32 v15, v0, v11
	ds_read_b32 v0, v49 offset:1136
	ds_read_b32 v11, v49 offset:1396
	s_waitcnt lgkmcnt(0)
	v_cvt_pk_bf16_f32 v16, v0, v11
	ds_read_b32 v0, v49 offset:1656
	ds_read_b32 v11, v49 offset:1916
	s_waitcnt lgkmcnt(0)
	v_cvt_pk_bf16_f32 v17, v0, v11
	v_or_b32_e32 v0, s0, v52
	v_mul_u32_u24_e32 v0, 0x1600, v0
	v_lshlrev_b32_e32 v0, 1, v0
	v_lshl_add_u64 v[18:19], v[12:13], 0, v[0:1]
	flat_store_dwordx4 v[18:19], v[14:17]
	ds_read_b32 v0, v49 offset:128
	ds_read_b32 v11, v49 offset:388
	s_waitcnt lgkmcnt(0)
	v_cvt_pk_bf16_f32 v14, v0, v11
	ds_read_b32 v0, v49 offset:648
	ds_read_b32 v11, v49 offset:908
	s_waitcnt lgkmcnt(0)
	v_cvt_pk_bf16_f32 v15, v0, v11
	ds_read_b32 v0, v49 offset:1168
	ds_read_b32 v11, v49 offset:1428
	s_waitcnt lgkmcnt(0)
	v_cvt_pk_bf16_f32 v16, v0, v11
	ds_read_b32 v0, v49 offset:1688
	ds_read_b32 v11, v49 offset:1948
	s_waitcnt lgkmcnt(0)
	v_cvt_pk_bf16_f32 v17, v0, v11
	v_or_b32_e32 v0, s0, v53
	v_mul_u32_u24_e32 v0, 0x1600, v0
	v_lshlrev_b32_e32 v0, 1, v0
	v_lshl_add_u64 v[18:19], v[12:13], 0, v[0:1]
	flat_store_dwordx4 v[18:19], v[14:17]
	ds_read_b32 v0, v49 offset:160
	ds_read_b32 v11, v49 offset:420
	s_waitcnt lgkmcnt(0)
	v_cvt_pk_bf16_f32 v14, v0, v11
	ds_read_b32 v0, v49 offset:680
	ds_read_b32 v11, v49 offset:940
	s_waitcnt lgkmcnt(0)
	v_cvt_pk_bf16_f32 v15, v0, v11
	ds_read_b32 v0, v49 offset:1200
	ds_read_b32 v11, v49 offset:1460
	s_waitcnt lgkmcnt(0)
	v_cvt_pk_bf16_f32 v16, v0, v11
	ds_read_b32 v0, v49 offset:1720
	ds_read_b32 v11, v49 offset:1980
	s_waitcnt lgkmcnt(0)
	v_cvt_pk_bf16_f32 v17, v0, v11
	v_or_b32_e32 v0, s0, v54
	v_mul_u32_u24_e32 v0, 0x1600, v0
	v_lshlrev_b32_e32 v0, 1, v0
	v_lshl_add_u64 v[18:19], v[12:13], 0, v[0:1]
	flat_store_dwordx4 v[18:19], v[14:17]
	ds_read_b32 v0, v49 offset:192
	ds_read_b32 v11, v49 offset:452
	s_waitcnt lgkmcnt(0)
	v_cvt_pk_bf16_f32 v14, v0, v11
	ds_read_b32 v0, v49 offset:712
	ds_read_b32 v11, v49 offset:972
	s_waitcnt lgkmcnt(0)
	v_cvt_pk_bf16_f32 v15, v0, v11
	ds_read_b32 v0, v49 offset:1232
	ds_read_b32 v11, v49 offset:1492
	s_waitcnt lgkmcnt(0)
	v_cvt_pk_bf16_f32 v16, v0, v11
	ds_read_b32 v0, v49 offset:1752
	ds_read_b32 v11, v49 offset:2012
	s_waitcnt lgkmcnt(0)
	v_cvt_pk_bf16_f32 v17, v0, v11
	v_or_b32_e32 v0, s0, v55
	v_mul_u32_u24_e32 v0, 0x1600, v0
	v_lshlrev_b32_e32 v0, 1, v0
	v_lshl_add_u64 v[18:19], v[12:13], 0, v[0:1]
	flat_store_dwordx4 v[18:19], v[14:17]
	ds_read_b32 v0, v49 offset:224
	ds_read_b32 v11, v49 offset:484
	s_waitcnt lgkmcnt(0)
	v_cvt_pk_bf16_f32 v14, v0, v11
	ds_read_b32 v0, v49 offset:744
	ds_read_b32 v11, v49 offset:1004
	s_waitcnt lgkmcnt(0)
	v_cvt_pk_bf16_f32 v15, v0, v11
	ds_read_b32 v0, v49 offset:1264
	ds_read_b32 v11, v49 offset:1524
	s_waitcnt lgkmcnt(0)
	v_cvt_pk_bf16_f32 v16, v0, v11
	ds_read_b32 v0, v49 offset:1784
	ds_read_b32 v11, v49 offset:2044
	s_waitcnt lgkmcnt(0)
	v_cvt_pk_bf16_f32 v17, v0, v11
	v_or_b32_e32 v0, s0, v56
	v_mul_u32_u24_e32 v0, 0x1600, v0
	v_lshlrev_b32_e32 v0, 1, v0
	v_lshl_add_u64 v[12:13], v[12:13], 0, v[0:1]
	flat_store_dwordx4 v[12:13], v[14:17]
	s_waitcnt lgkmcnt(0)
	s_mov_b64 s[0:1], 0

.LBB0_1607:
	v_add_u32_e32 v0, 0x3c00, v47
	ds_write2_b32 v0, v14, v15 offset0:190 offset1:255
	s_waitcnt lgkmcnt(0)
	ds_read_b32 v0, v49
	ds_read_b32 v11, v49 offset:260
	s_lshl_b32 s90, s5, 1
	v_lshl_add_u64 v[12:13], v[4:5], 0, s[90:91]
	s_waitcnt lgkmcnt(0)
	v_cvt_pk_bf16_f32 v14, v0, v11
	ds_read_b32 v0, v49 offset:520
	ds_read_b32 v11, v49 offset:780
	s_waitcnt lgkmcnt(1)
	s_waitcnt lgkmcnt(0)
	v_cvt_pk_bf16_f32 v15, v0, v11
	ds_read_b32 v0, v49 offset:1040
	ds_read_b32 v11, v49 offset:1300
	s_waitcnt lgkmcnt(1)
	s_waitcnt lgkmcnt(0)
	v_cvt_pk_bf16_f32 v16, v0, v11
	ds_read_b32 v0, v49 offset:1560
	ds_read_b32 v11, v49 offset:1820
	s_waitcnt lgkmcnt(1)
	s_waitcnt lgkmcnt(0)
	v_cvt_pk_bf16_f32 v17, v0, v11
	v_or_b32_e32 v0, s4, v48
	v_lshlrev_b32_e32 v0, 12, v0
	v_lshl_add_u64 v[18:19], v[12:13], 0, v[0:1]
	flat_store_dwordx4 v[18:19], v[14:17]
	ds_read_b32 v0, v49 offset:32
	ds_read_b32 v11, v49 offset:292
	s_waitcnt lgkmcnt(0)
	v_cvt_pk_bf16_f32 v14, v0, v11
	ds_read_b32 v0, v49 offset:552
	ds_read_b32 v11, v49 offset:812
	s_waitcnt lgkmcnt(0)
	v_cvt_pk_bf16_f32 v15, v0, v11
	ds_read_b32 v0, v49 offset:1072
	ds_read_b32 v11, v49 offset:1332
	s_waitcnt lgkmcnt(0)
	v_cvt_pk_bf16_f32 v16, v0, v11
	ds_read_b32 v0, v49 offset:1592
	ds_read_b32 v11, v49 offset:1852
	s_waitcnt lgkmcnt(0)
	v_cvt_pk_bf16_f32 v17, v0, v11
	v_or_b32_e32 v0, s4, v50
	v_lshlrev_b32_e32 v0, 12, v0
	v_lshl_add_u64 v[18:19], v[12:13], 0, v[0:1]
	flat_store_dwordx4 v[18:19], v[14:17]
	ds_read_b32 v0, v49 offset:64
	ds_read_b32 v11, v49 offset:324
	s_waitcnt lgkmcnt(0)
	v_cvt_pk_bf16_f32 v14, v0, v11
	ds_read_b32 v0, v49 offset:584
	ds_read_b32 v11, v49 offset:844
	s_waitcnt lgkmcnt(0)
	v_cvt_pk_bf16_f32 v15, v0, v11
	ds_read_b32 v0, v49 offset:1104
	ds_read_b32 v11, v49 offset:1364
	s_waitcnt lgkmcnt(0)
	v_cvt_pk_bf16_f32 v16, v0, v11
	ds_read_b32 v0, v49 offset:1624
	ds_read_b32 v11, v49 offset:1884
	s_waitcnt lgkmcnt(0)
	v_cvt_pk_bf16_f32 v17, v0, v11
	v_or_b32_e32 v0, s4, v51
	v_lshlrev_b32_e32 v0, 12, v0
	v_lshl_add_u64 v[18:19], v[12:13], 0, v[0:1]
	flat_store_dwordx4 v[18:19], v[14:17]
	ds_read_b32 v0, v49 offset:96
	ds_read_b32 v11, v49 offset:356
	s_waitcnt lgkmcnt(0)
	v_cvt_pk_bf16_f32 v14, v0, v11
	ds_read_b32 v0, v49 offset:616
	ds_read_b32 v11, v49 offset:876
	s_waitcnt lgkmcnt(0)
	v_cvt_pk_bf16_f32 v15, v0, v11
	ds_read_b32 v0, v49 offset:1136
	ds_read_b32 v11, v49 offset:1396
	s_waitcnt lgkmcnt(0)
	v_cvt_pk_bf16_f32 v16, v0, v11
	ds_read_b32 v0, v49 offset:1656
	ds_read_b32 v11, v49 offset:1916
	s_waitcnt lgkmcnt(0)
	v_cvt_pk_bf16_f32 v17, v0, v11
	v_or_b32_e32 v0, s4, v52
	v_lshlrev_b32_e32 v0, 12, v0
	v_lshl_add_u64 v[18:19], v[12:13], 0, v[0:1]
	flat_store_dwordx4 v[18:19], v[14:17]
	ds_read_b32 v0, v49 offset:128
	ds_read_b32 v11, v49 offset:388
	s_waitcnt lgkmcnt(0)
	v_cvt_pk_bf16_f32 v14, v0, v11
	ds_read_b32 v0, v49 offset:648
	ds_read_b32 v11, v49 offset:908
	s_waitcnt lgkmcnt(0)
	v_cvt_pk_bf16_f32 v15, v0, v11
	ds_read_b32 v0, v49 offset:1168
	ds_read_b32 v11, v49 offset:1428
	s_waitcnt lgkmcnt(0)
	v_cvt_pk_bf16_f32 v16, v0, v11
	ds_read_b32 v0, v49 offset:1688
	ds_read_b32 v11, v49 offset:1948
	s_waitcnt lgkmcnt(0)
	v_cvt_pk_bf16_f32 v17, v0, v11
	v_or_b32_e32 v0, s4, v53
	v_lshlrev_b32_e32 v0, 12, v0
	v_lshl_add_u64 v[18:19], v[12:13], 0, v[0:1]
	flat_store_dwordx4 v[18:19], v[14:17]
	ds_read_b32 v0, v49 offset:160
	ds_read_b32 v11, v49 offset:420
	s_waitcnt lgkmcnt(0)
	v_cvt_pk_bf16_f32 v14, v0, v11
	ds_read_b32 v0, v49 offset:680
	ds_read_b32 v11, v49 offset:940
	s_waitcnt lgkmcnt(0)
	v_cvt_pk_bf16_f32 v15, v0, v11
	ds_read_b32 v0, v49 offset:1200
	ds_read_b32 v11, v49 offset:1460
	s_waitcnt lgkmcnt(0)
	v_cvt_pk_bf16_f32 v16, v0, v11
	ds_read_b32 v0, v49 offset:1720
	ds_read_b32 v11, v49 offset:1980
	s_waitcnt lgkmcnt(0)
	v_cvt_pk_bf16_f32 v17, v0, v11
	v_or_b32_e32 v0, s4, v54
	v_lshlrev_b32_e32 v0, 12, v0
	v_lshl_add_u64 v[18:19], v[12:13], 0, v[0:1]
	flat_store_dwordx4 v[18:19], v[14:17]
	ds_read_b32 v0, v49 offset:192
	ds_read_b32 v11, v49 offset:452
	s_waitcnt lgkmcnt(0)
	v_cvt_pk_bf16_f32 v14, v0, v11
	ds_read_b32 v0, v49 offset:712
	ds_read_b32 v11, v49 offset:972
	s_waitcnt lgkmcnt(0)
	v_cvt_pk_bf16_f32 v15, v0, v11
	ds_read_b32 v0, v49 offset:1232
	ds_read_b32 v11, v49 offset:1492
	s_waitcnt lgkmcnt(0)
	v_cvt_pk_bf16_f32 v16, v0, v11
	ds_read_b32 v0, v49 offset:1752
	ds_read_b32 v11, v49 offset:2012
	s_waitcnt lgkmcnt(0)
	v_cvt_pk_bf16_f32 v17, v0, v11
	v_or_b32_e32 v0, s4, v55
	v_lshlrev_b32_e32 v0, 12, v0
	v_lshl_add_u64 v[18:19], v[12:13], 0, v[0:1]
	flat_store_dwordx4 v[18:19], v[14:17]
	ds_read_b32 v0, v49 offset:224
	ds_read_b32 v11, v49 offset:484
	s_waitcnt lgkmcnt(0)
	v_cvt_pk_bf16_f32 v14, v0, v11
	ds_read_b32 v0, v49 offset:744
	ds_read_b32 v11, v49 offset:1004
	s_waitcnt lgkmcnt(0)
	v_cvt_pk_bf16_f32 v15, v0, v11
	ds_read_b32 v0, v49 offset:1264
	ds_read_b32 v11, v49 offset:1524
	s_waitcnt lgkmcnt(0)
	v_cvt_pk_bf16_f32 v16, v0, v11
	ds_read_b32 v0, v49 offset:1784
	ds_read_b32 v11, v49 offset:2044
	s_waitcnt lgkmcnt(0)
	v_cvt_pk_bf16_f32 v17, v0, v11
	v_or_b32_e32 v0, s4, v56
	v_lshlrev_b32_e32 v0, 12, v0
	v_lshl_add_u64 v[12:13], v[12:13], 0, v[0:1]
	flat_store_dwordx4 v[12:13], v[14:17]
	s_waitcnt lgkmcnt(0)

.LBB0_1609:
	s_andn2_b64 vcc, exec, s[0:1]
	s_cbranch_vccnz .LBB0_1611
	s_add_i32 s0, s7, 0xe300
	s_bfe_u32 s1, s0, 0xb0005
	s_and_b32 s0, s44, 0x7c0
	v_or_b32_e32 v0, s0, v46
	v_readlane_b32 s4, v254, 10
	v_lshlrev_b32_e32 v0, 2, v0
	v_readlane_b32 s5, v254, 11
	s_lshl_b32 s90, s1, 19
	s_nop 0
	v_lshl_add_u64 v[12:13], s[4:5], 0, v[0:1]
	v_lshl_add_u64 v[12:13], v[12:13], 0, s[90:91]
	v_add_co_u32_e32 v14, vcc, 0x2000, v12
	global_load_dword v0, v[12:13], off
	s_nop 0
	v_addc_co_u32_e32 v15, vcc, 0, v13, vcc
	global_load_dword v11, v[14:15], off
	v_add_co_u32_e32 v14, vcc, 0x4000, v12
	s_mov_b32 s4, 0x10000
	s_nop 0
	v_addc_co_u32_e32 v15, vcc, 0, v13, vcc
	v_add_co_u32_e32 v16, vcc, 0x6000, v12
	global_load_dword v14, v[14:15], off
	s_nop 0
	v_addc_co_u32_e32 v17, vcc, 0, v13, vcc
	global_load_dword v15, v[16:17], off
	v_add_co_u32_e32 v16, vcc, 0x8000, v12
	s_lshl_b32 s90, s1, 7
	s_nop 0
	v_addc_co_u32_e32 v17, vcc, 0, v13, vcc
	v_add_co_u32_e32 v18, vcc, 0xa000, v12
	global_load_dword v16, v[16:17], off
	s_nop 0
	v_addc_co_u32_e32 v19, vcc, 0, v13, vcc
	global_load_dword v17, v[18:19], off
	v_add_co_u32_e32 v18, vcc, 0xc000, v12
	s_nop 1
	v_addc_co_u32_e32 v19, vcc, 0, v13, vcc
	v_add_co_u32_e32 v20, vcc, 0xe000, v12
	global_load_dword v18, v[18:19], off
	s_nop 0
	v_addc_co_u32_e32 v21, vcc, 0, v13, vcc
	global_load_dword v19, v[20:21], off
	v_add_co_u32_e32 v20, vcc, s4, v12
	s_mov_b32 s4, 0x12000
	s_nop 0
	v_addc_co_u32_e32 v21, vcc, 0, v13, vcc
	v_add_co_u32_e32 v22, vcc, s4, v12
	s_mov_b32 s4, 0x14000
	s_nop 0
	v_addc_co_u32_e32 v23, vcc, 0, v13, vcc
	global_load_dword v20, v[20:21], off
	s_nop 0
	global_load_dword v21, v[22:23], off
	v_add_co_u32_e32 v22, vcc, s4, v12
	s_mov_b32 s4, 0x1a000
	s_nop 0
	v_addc_co_u32_e32 v23, vcc, 0, v13, vcc
	v_add_co_u32_e32 v24, vcc, s14, v12
	global_load_dword v22, v[22:23], off
	s_nop 0
	v_addc_co_u32_e32 v25, vcc, 0, v13, vcc
	global_load_dword v23, v[24:25], off
	v_add_co_u32_e32 v24, vcc, s9, v12
	s_nop 1
	v_addc_co_u32_e32 v25, vcc, 0, v13, vcc
	v_add_co_u32_e32 v26, vcc, s4, v12
	s_mov_b32 s4, 0x1c000
	s_nop 0
	v_addc_co_u32_e32 v27, vcc, 0, v13, vcc
	global_load_dword v24, v[24:25], off
	s_nop 0
	global_load_dword v25, v[26:27], off
	v_add_co_u32_e32 v26, vcc, s4, v12
	s_mov_b32 s4, 0x1e000
	s_nop 0
	v_addc_co_u32_e32 v27, vcc, 0, v13, vcc
	v_add_co_u32_e32 v28, vcc, s4, v12
	s_mov_b32 s4, 0x20000
	s_nop 0
	v_addc_co_u32_e32 v29, vcc, 0, v13, vcc
	global_load_dword v26, v[26:27], off
	s_nop 0
	global_load_dword v27, v[28:29], off
	v_add_co_u32_e32 v28, vcc, s4, v12
	s_mov_b32 s4, 0x22000
	s_nop 0
	v_addc_co_u32_e32 v29, vcc, 0, v13, vcc
	v_add_co_u32_e32 v30, vcc, s4, v12
	s_mov_b32 s4, 0x24000
	s_nop 0
	v_addc_co_u32_e32 v31, vcc, 0, v13, vcc
	global_load_dword v28, v[28:29], off
	s_nop 0
	global_load_dword v29, v[30:31], off
	v_add_co_u32_e32 v30, vcc, s4, v12
	s_mov_b32 s4, 0x26000
	s_nop 0
	v_addc_co_u32_e32 v31, vcc, 0, v13, vcc
	v_add_co_u32_e32 v32, vcc, s4, v12
	s_mov_b32 s4, 0x28000
	s_nop 0
	v_addc_co_u32_e32 v33, vcc, 0, v13, vcc
	global_load_dword v30, v[30:31], off
	s_nop 0
	global_load_dword v31, v[32:33], off
	v_add_co_u32_e32 v32, vcc, s4, v12
	s_mov_b32 s4, 0x2a000
	s_nop 0
	v_addc_co_u32_e32 v33, vcc, 0, v13, vcc
	v_add_co_u32_e32 v34, vcc, s4, v12
	s_mov_b32 s4, 0x2c000
	s_nop 0
	v_addc_co_u32_e32 v35, vcc, 0, v13, vcc
	global_load_dword v32, v[32:33], off
	s_nop 0
	global_load_dword v33, v[34:35], off
	v_add_co_u32_e32 v34, vcc, s4, v12
	s_mov_b32 s4, 0x2e000
	s_nop 0
	v_addc_co_u32_e32 v35, vcc, 0, v13, vcc
	v_add_co_u32_e32 v36, vcc, s4, v12
	s_mov_b32 s4, 0x30000
	s_nop 0
	v_addc_co_u32_e32 v37, vcc, 0, v13, vcc
	global_load_dword v34, v[34:35], off
	s_nop 0
	global_load_dword v35, v[36:37], off
	v_add_co_u32_e32 v36, vcc, s4, v12
	s_mov_b32 s4, 0x32000
	s_nop 0
	v_addc_co_u32_e32 v37, vcc, 0, v13, vcc
	v_add_co_u32_e32 v38, vcc, s4, v12
	s_mov_b32 s4, 0x34000
	s_nop 0
	v_addc_co_u32_e32 v39, vcc, 0, v13, vcc
	global_load_dword v36, v[36:37], off
	s_nop 0
	global_load_dword v37, v[38:39], off
	v_add_co_u32_e32 v38, vcc, s4, v12
	s_mov_b32 s4, 0x36000
	s_nop 0
	v_addc_co_u32_e32 v39, vcc, 0, v13, vcc
	v_add_co_u32_e32 v40, vcc, s4, v12
	s_mov_b32 s4, 0x38000
	s_nop 0
	v_addc_co_u32_e32 v41, vcc, 0, v13, vcc
	global_load_dword v38, v[38:39], off
	s_nop 0
	global_load_dword v39, v[40:41], off
	v_add_co_u32_e32 v40, vcc, s4, v12
	s_mov_b32 s4, 0x3a000
	s_nop 0
	v_addc_co_u32_e32 v41, vcc, 0, v13, vcc
	global_load_dword v42, v[40:41], off
	v_add_co_u32_e32 v40, vcc, s4, v12
	s_mov_b32 s4, 0x3c000
	s_nop 0
	v_addc_co_u32_e32 v41, vcc, 0, v13, vcc
	global_load_dword v43, v[40:41], off
	v_add_co_u32_e32 v40, vcc, s4, v12
	s_mov_b32 s4, 0x3e000
	s_nop 0
	v_addc_co_u32_e32 v41, vcc, 0, v13, vcc
	global_load_dword v44, v[40:41], off
	v_add_co_u32_e32 v40, vcc, s4, v12
	s_mov_b32 s4, 0x40000
	s_nop 0
	v_addc_co_u32_e32 v41, vcc, 0, v13, vcc
	global_load_dword v45, v[40:41], off
	v_add_co_u32_e32 v40, vcc, s4, v12
	s_mov_b32 s4, 0x42000
	s_nop 0
	v_addc_co_u32_e32 v41, vcc, 0, v13, vcc
	global_load_dword v57, v[40:41], off
	v_add_co_u32_e32 v40, vcc, s4, v12
	s_mov_b32 s4, 0x44000
	s_nop 0
	v_addc_co_u32_e32 v41, vcc, 0, v13, vcc
	global_load_dword v58, v[40:41], off
	v_add_co_u32_e32 v40, vcc, s4, v12
	s_mov_b32 s4, 0x46000
	s_nop 0
	v_addc_co_u32_e32 v41, vcc, 0, v13, vcc
	global_load_dword v59, v[40:41], off
	v_add_co_u32_e32 v40, vcc, s4, v12
	s_mov_b32 s4, 0x48000
	s_nop 0
	v_addc_co_u32_e32 v41, vcc, 0, v13, vcc
	global_load_dword v60, v[40:41], off
	v_add_co_u32_e32 v40, vcc, s4, v12
	s_mov_b32 s4, 0x4a000
	s_nop 0
	v_addc_co_u32_e32 v41, vcc, 0, v13, vcc
	global_load_dword v61, v[40:41], off
	v_add_co_u32_e32 v40, vcc, s4, v12
	s_mov_b32 s4, 0x4c000
	s_nop 0
	v_addc_co_u32_e32 v41, vcc, 0, v13, vcc
	global_load_dword v62, v[40:41], off
	v_add_co_u32_e32 v40, vcc, s4, v12
	s_mov_b32 s4, 0x4e000
	s_nop 0
	v_addc_co_u32_e32 v41, vcc, 0, v13, vcc
	global_load_dword v63, v[40:41], off
	v_add_co_u32_e32 v40, vcc, s4, v12
	s_mov_b32 s4, 0x50000
	s_nop 0
	v_addc_co_u32_e32 v41, vcc, 0, v13, vcc
	global_load_dword v64, v[40:41], off
	v_add_co_u32_e32 v40, vcc, s4, v12
	s_mov_b32 s4, 0x52000
	s_nop 0
	v_addc_co_u32_e32 v41, vcc, 0, v13, vcc
	global_load_dword v65, v[40:41], off
	v_add_co_u32_e32 v40, vcc, s4, v12
	s_mov_b32 s4, 0x54000
	s_nop 0
	v_addc_co_u32_e32 v41, vcc, 0, v13, vcc
	global_load_dword v66, v[40:41], off
	v_add_co_u32_e32 v40, vcc, s4, v12
	s_mov_b32 s4, 0x56000
	s_nop 0
	v_addc_co_u32_e32 v41, vcc, 0, v13, vcc
	global_load_dword v67, v[40:41], off
	v_add_co_u32_e32 v40, vcc, s4, v12
	s_mov_b32 s4, 0x58000
	s_nop 0
	v_addc_co_u32_e32 v41, vcc, 0, v13, vcc
	global_load_dword v68, v[40:41], off
	v_add_co_u32_e32 v40, vcc, s4, v12
	s_mov_b32 s4, 0x5a000
	s_nop 0
	v_addc_co_u32_e32 v41, vcc, 0, v13, vcc
	global_load_dword v69, v[40:41], off
	v_add_co_u32_e32 v40, vcc, s4, v12
	s_mov_b32 s4, 0x5c000
	s_nop 0
	v_addc_co_u32_e32 v41, vcc, 0, v13, vcc
	global_load_dword v70, v[40:41], off
	v_add_co_u32_e32 v40, vcc, s4, v12
	s_mov_b32 s4, 0x5e000
	s_nop 0
	v_addc_co_u32_e32 v41, vcc, 0, v13, vcc
	global_load_dword v71, v[40:41], off
	v_add_co_u32_e32 v40, vcc, s4, v12
	s_mov_b32 s4, 0x60000
	s_nop 0
	v_addc_co_u32_e32 v41, vcc, 0, v13, vcc
	global_load_dword v72, v[40:41], off
	v_add_co_u32_e32 v40, vcc, s4, v12
	s_mov_b32 s4, 0x64000
	s_nop 0
	v_addc_co_u32_e32 v41, vcc, 0, v13, vcc
	global_load_dword v73, v[40:41], off
	v_add_co_u32_e32 v40, vcc, s21, v12
	s_nop 1
	v_addc_co_u32_e32 v41, vcc, 0, v13, vcc
	global_load_dword v74, v[40:41], off
	v_add_co_u32_e32 v40, vcc, s4, v12
	s_mov_b32 s4, 0x66000
	s_nop 0
	v_addc_co_u32_e32 v41, vcc, 0, v13, vcc
	global_load_dword v75, v[40:41], off
	v_add_co_u32_e32 v40, vcc, s4, v12
	s_mov_b32 s4, 0x68000
	s_nop 0
	v_addc_co_u32_e32 v41, vcc, 0, v13, vcc
	global_load_dword v76, v[40:41], off
	v_add_co_u32_e32 v40, vcc, s4, v12
	s_mov_b32 s4, 0x6a000
	s_nop 0
	v_addc_co_u32_e32 v41, vcc, 0, v13, vcc
	global_load_dword v77, v[40:41], off
	v_add_co_u32_e32 v40, vcc, s4, v12
	s_mov_b32 s4, 0x6c000
	s_nop 0
	v_addc_co_u32_e32 v41, vcc, 0, v13, vcc
	global_load_dword v78, v[40:41], off
	v_add_co_u32_e32 v40, vcc, s4, v12
	s_mov_b32 s4, 0x70000
	s_nop 0
	v_addc_co_u32_e32 v41, vcc, 0, v13, vcc
	global_load_dword v79, v[40:41], off
	v_add_co_u32_e32 v40, vcc, s16, v12
	s_nop 1
	v_addc_co_u32_e32 v41, vcc, 0, v13, vcc
	global_load_dword v80, v[40:41], off
	v_add_co_u32_e32 v40, vcc, s4, v12
	s_mov_b32 s4, 0x72000
	s_nop 0
	v_addc_co_u32_e32 v41, vcc, 0, v13, vcc
	global_load_dword v81, v[40:41], off
	v_add_co_u32_e32 v40, vcc, s4, v12
	s_mov_b32 s4, 0x74000
	s_nop 0
	v_addc_co_u32_e32 v41, vcc, 0, v13, vcc
	global_load_dword v82, v[40:41], off
	v_add_co_u32_e32 v40, vcc, s4, v12
	s_mov_b32 s4, 0x76000
	s_nop 0
	v_addc_co_u32_e32 v41, vcc, 0, v13, vcc
	global_load_dword v83, v[40:41], off
	v_add_co_u32_e32 v40, vcc, s4, v12
	s_mov_b32 s4, 0x78000
	s_nop 0
	v_addc_co_u32_e32 v41, vcc, 0, v13, vcc
	global_load_dword v84, v[40:41], off
	v_add_co_u32_e32 v40, vcc, s4, v12
	s_mov_b32 s4, 0x7c000
	s_nop 0
	v_addc_co_u32_e32 v41, vcc, 0, v13, vcc
	global_load_dword v85, v[40:41], off
	v_add_co_u32_e32 v40, vcc, s89, v12
	s_nop 1
	v_addc_co_u32_e32 v41, vcc, 0, v13, vcc
	global_load_dword v86, v[40:41], off
	v_add_co_u32_e32 v40, vcc, s4, v12
	s_mov_b32 s4, 0x7e000
	s_nop 0
	v_addc_co_u32_e32 v41, vcc, 0, v13, vcc
	v_add_co_u32_e32 v12, vcc, s4, v12
	global_load_dword v40, v[40:41], off
	s_nop 0
	v_addc_co_u32_e32 v13, vcc, 0, v13, vcc
	global_load_dword v12, v[12:13], off
	s_waitcnt vmcnt(0)
	ds_write2_b32 v47, v0, v11 offset1:65
	ds_write2_b32 v47, v14, v15 offset0:130 offset1:195
	v_add_u32_e32 v0, 0x400, v47
	ds_write2_b32 v0, v16, v17 offset0:4 offset1:69
	ds_write2_b32 v0, v18, v19 offset0:134 offset1:199
	v_add_u32_e32 v0, 0x800, v47
	ds_write2_b32 v0, v20, v21 offset0:8 offset1:73
	ds_write2_b32 v0, v22, v23 offset0:138 offset1:203
	v_add_u32_e32 v0, 0xc00, v47
	ds_write2_b32 v0, v24, v25 offset0:12 offset1:77
	ds_write2_b32 v0, v26, v27 offset0:142 offset1:207
	v_add_u32_e32 v0, 0x1000, v47
	ds_write2_b32 v0, v28, v29 offset0:16 offset1:81
	ds_write2_b32 v0, v30, v31 offset0:146 offset1:211
	v_add_u32_e32 v0, 0x1400, v47
	ds_write2_b32 v0, v32, v33 offset0:20 offset1:85
	ds_write2_b32 v0, v34, v35 offset0:150 offset1:215
	v_add_u32_e32 v0, 0x1800, v47
	ds_write2_b32 v0, v36, v37 offset0:24 offset1:89
	ds_write2_b32 v0, v38, v39 offset0:154 offset1:219
	v_add_u32_e32 v0, 0x1c00, v47
	ds_write2_b32 v0, v42, v43 offset0:28 offset1:93
	ds_write2_b32 v0, v44, v45 offset0:158 offset1:223
	v_add_u32_e32 v0, 0x2000, v47
	ds_write2_b32 v0, v57, v58 offset0:32 offset1:97
	ds_write2_b32 v0, v59, v60 offset0:162 offset1:227
	v_add_u32_e32 v0, 0x2400, v47
	ds_write2_b32 v0, v61, v62 offset0:36 offset1:101
	ds_write2_b32 v0, v63, v64 offset0:166 offset1:231
	v_add_u32_e32 v0, 0x2800, v47
	ds_write2_b32 v0, v65, v66 offset0:40 offset1:105
	ds_write2_b32 v0, v67, v68 offset0:170 offset1:235
	v_add_u32_e32 v0, 0x2c00, v47
	ds_write2_b32 v0, v69, v70 offset0:44 offset1:109
	ds_write2_b32 v0, v71, v72 offset0:174 offset1:239
	v_add_u32_e32 v0, 0x3000, v47
	ds_write2_b32 v0, v73, v74 offset0:48 offset1:113
	ds_write2_b32 v0, v75, v76 offset0:178 offset1:243
	v_add_u32_e32 v0, 0x3400, v47
	ds_write2_b32 v0, v77, v78 offset0:52 offset1:117
	ds_write2_b32 v0, v79, v80 offset0:182 offset1:247
	v_add_u32_e32 v0, 0x3800, v47
	ds_write2_b32 v0, v81, v82 offset0:56 offset1:121
	ds_write2_b32 v0, v83, v84 offset0:186 offset1:251
	v_add_u32_e32 v0, 0x3c00, v47
	ds_write2_b32 v0, v85, v86 offset0:60 offset1:125
	ds_write2_b32 v0, v40, v12 offset0:190 offset1:255
	s_waitcnt lgkmcnt(0)
	ds_read_b32 v0, v49
	ds_read_b32 v11, v49 offset:260
	v_lshl_add_u64 v[12:13], v[6:7], 0, s[90:91]
	s_waitcnt lgkmcnt(0)
	v_cvt_pk_bf16_f32 v14, v0, v11
	ds_read_b32 v0, v49 offset:520
	ds_read_b32 v11, v49 offset:780
	s_waitcnt lgkmcnt(1)
	s_waitcnt lgkmcnt(0)
	v_cvt_pk_bf16_f32 v15, v0, v11
	ds_read_b32 v0, v49 offset:1040
	ds_read_b32 v11, v49 offset:1300
	s_waitcnt lgkmcnt(1)
	s_waitcnt lgkmcnt(0)
	v_cvt_pk_bf16_f32 v16, v0, v11
	ds_read_b32 v0, v49 offset:1560
	ds_read_b32 v11, v49 offset:1820
	s_waitcnt lgkmcnt(1)
	s_waitcnt lgkmcnt(0)
	v_cvt_pk_bf16_f32 v17, v0, v11
	v_or_b32_e32 v0, s0, v48
	v_lshlrev_b32_e32 v0, 12, v0
	v_lshl_add_u64 v[18:19], v[12:13], 0, v[0:1]
	flat_store_dwordx4 v[18:19], v[14:17]
	ds_read_b32 v0, v49 offset:32
	ds_read_b32 v11, v49 offset:292
	s_waitcnt lgkmcnt(0)
	v_cvt_pk_bf16_f32 v14, v0, v11
	ds_read_b32 v0, v49 offset:552
	ds_read_b32 v11, v49 offset:812
	s_waitcnt lgkmcnt(0)
	v_cvt_pk_bf16_f32 v15, v0, v11
	ds_read_b32 v0, v49 offset:1072
	ds_read_b32 v11, v49 offset:1332
	s_waitcnt lgkmcnt(0)
	v_cvt_pk_bf16_f32 v16, v0, v11
	ds_read_b32 v0, v49 offset:1592
	ds_read_b32 v11, v49 offset:1852
	s_waitcnt lgkmcnt(0)
	v_cvt_pk_bf16_f32 v17, v0, v11
	v_or_b32_e32 v0, s0, v50
	v_lshlrev_b32_e32 v0, 12, v0
	v_lshl_add_u64 v[18:19], v[12:13], 0, v[0:1]
	flat_store_dwordx4 v[18:19], v[14:17]
	ds_read_b32 v0, v49 offset:64
	ds_read_b32 v11, v49 offset:324
	s_waitcnt lgkmcnt(0)
	v_cvt_pk_bf16_f32 v14, v0, v11
	ds_read_b32 v0, v49 offset:584
	ds_read_b32 v11, v49 offset:844
	s_waitcnt lgkmcnt(0)
	v_cvt_pk_bf16_f32 v15, v0, v11
	ds_read_b32 v0, v49 offset:1104
	ds_read_b32 v11, v49 offset:1364
	s_waitcnt lgkmcnt(0)
	v_cvt_pk_bf16_f32 v16, v0, v11
	ds_read_b32 v0, v49 offset:1624
	ds_read_b32 v11, v49 offset:1884
	s_waitcnt lgkmcnt(0)
	v_cvt_pk_bf16_f32 v17, v0, v11
	v_or_b32_e32 v0, s0, v51
	v_lshlrev_b32_e32 v0, 12, v0
	v_lshl_add_u64 v[18:19], v[12:13], 0, v[0:1]
	flat_store_dwordx4 v[18:19], v[14:17]
	ds_read_b32 v0, v49 offset:96
	ds_read_b32 v11, v49 offset:356
	s_waitcnt lgkmcnt(0)
	v_cvt_pk_bf16_f32 v14, v0, v11
	ds_read_b32 v0, v49 offset:616
	ds_read_b32 v11, v49 offset:876
	s_waitcnt lgkmcnt(0)
	v_cvt_pk_bf16_f32 v15, v0, v11
	ds_read_b32 v0, v49 offset:1136
	ds_read_b32 v11, v49 offset:1396
	s_waitcnt lgkmcnt(0)
	v_cvt_pk_bf16_f32 v16, v0, v11
	ds_read_b32 v0, v49 offset:1656
	ds_read_b32 v11, v49 offset:1916
	s_waitcnt lgkmcnt(0)
	v_cvt_pk_bf16_f32 v17, v0, v11
	v_or_b32_e32 v0, s0, v52
	v_lshlrev_b32_e32 v0, 12, v0
	v_lshl_add_u64 v[18:19], v[12:13], 0, v[0:1]
	flat_store_dwordx4 v[18:19], v[14:17]
	ds_read_b32 v0, v49 offset:128
	ds_read_b32 v11, v49 offset:388
	s_waitcnt lgkmcnt(0)
	v_cvt_pk_bf16_f32 v14, v0, v11
	ds_read_b32 v0, v49 offset:648
	ds_read_b32 v11, v49 offset:908
	s_waitcnt lgkmcnt(0)
	v_cvt_pk_bf16_f32 v15, v0, v11
	ds_read_b32 v0, v49 offset:1168
	ds_read_b32 v11, v49 offset:1428
	s_waitcnt lgkmcnt(0)
	v_cvt_pk_bf16_f32 v16, v0, v11
	ds_read_b32 v0, v49 offset:1688
	ds_read_b32 v11, v49 offset:1948
	s_waitcnt lgkmcnt(0)
	v_cvt_pk_bf16_f32 v17, v0, v11
	v_or_b32_e32 v0, s0, v53
	v_lshlrev_b32_e32 v0, 12, v0
	v_lshl_add_u64 v[18:19], v[12:13], 0, v[0:1]
	flat_store_dwordx4 v[18:19], v[14:17]
	ds_read_b32 v0, v49 offset:160
	ds_read_b32 v11, v49 offset:420
	s_waitcnt lgkmcnt(0)
	v_cvt_pk_bf16_f32 v14, v0, v11
	ds_read_b32 v0, v49 offset:680
	ds_read_b32 v11, v49 offset:940
	s_waitcnt lgkmcnt(0)
	v_cvt_pk_bf16_f32 v15, v0, v11
	ds_read_b32 v0, v49 offset:1200
	ds_read_b32 v11, v49 offset:1460
	s_waitcnt lgkmcnt(0)
	v_cvt_pk_bf16_f32 v16, v0, v11
	ds_read_b32 v0, v49 offset:1720
	ds_read_b32 v11, v49 offset:1980
	s_waitcnt lgkmcnt(0)
	v_cvt_pk_bf16_f32 v17, v0, v11
	v_or_b32_e32 v0, s0, v54
	v_lshlrev_b32_e32 v0, 12, v0
	v_lshl_add_u64 v[18:19], v[12:13], 0, v[0:1]
	flat_store_dwordx4 v[18:19], v[14:17]
	ds_read_b32 v0, v49 offset:192
	ds_read_b32 v11, v49 offset:452
	s_waitcnt lgkmcnt(0)
	v_cvt_pk_bf16_f32 v14, v0, v11
	ds_read_b32 v0, v49 offset:712
	ds_read_b32 v11, v49 offset:972
	s_waitcnt lgkmcnt(0)
	v_cvt_pk_bf16_f32 v15, v0, v11
	ds_read_b32 v0, v49 offset:1232
	ds_read_b32 v11, v49 offset:1492
	s_waitcnt lgkmcnt(0)
	v_cvt_pk_bf16_f32 v16, v0, v11
	ds_read_b32 v0, v49 offset:1752
	ds_read_b32 v11, v49 offset:2012
	s_waitcnt lgkmcnt(0)
	v_cvt_pk_bf16_f32 v17, v0, v11
	v_or_b32_e32 v0, s0, v55
	v_lshlrev_b32_e32 v0, 12, v0
	v_lshl_add_u64 v[18:19], v[12:13], 0, v[0:1]
	flat_store_dwordx4 v[18:19], v[14:17]
	ds_read_b32 v0, v49 offset:224
	ds_read_b32 v11, v49 offset:484
	s_waitcnt lgkmcnt(0)
	v_cvt_pk_bf16_f32 v14, v0, v11
	ds_read_b32 v0, v49 offset:744
	ds_read_b32 v11, v49 offset:1004
	s_waitcnt lgkmcnt(0)
	v_cvt_pk_bf16_f32 v15, v0, v11
	ds_read_b32 v0, v49 offset:1264
	ds_read_b32 v11, v49 offset:1524
	s_waitcnt lgkmcnt(0)
	v_cvt_pk_bf16_f32 v16, v0, v11
	ds_read_b32 v0, v49 offset:1784
	ds_read_b32 v11, v49 offset:2044
	s_waitcnt lgkmcnt(0)
	v_cvt_pk_bf16_f32 v17, v0, v11
	v_or_b32_e32 v0, s0, v56
	v_lshlrev_b32_e32 v0, 12, v0
	v_lshl_add_u64 v[12:13], v[12:13], 0, v[0:1]
	flat_store_dwordx4 v[12:13], v[14:17]
	s_waitcnt lgkmcnt(0)

.LBB0_1612:
	s_andn2_b64 vcc, exec, s[0:1]
	s_cbranch_vccnz .LBB0_1614
	s_add_i32 s0, s7, 0xffffe700
	s_lshr_b32 s90, s0, 8
	s_lshl_b64 s[0:1], s[90:91], 22
	s_add_u32 s4, s12, s0
	s_addc_u32 s5, s18, s1
	s_and_b32 s0, s44, 0x7c0
	v_or_b32_e32 v0, s0, v46
	s_and_b32 s1, s46, 0x1c0
	v_lshlrev_b32_e32 v0, 2, v0
	v_lshl_add_u64 v[12:13], s[4:5], 0, v[0:1]
	s_lshl_b32 s4, s1, 13
	s_mov_b32 s5, s91
	v_lshl_add_u64 v[12:13], v[12:13], 0, s[4:5]
	v_add_co_u32_e32 v14, vcc, s28, v12
	global_load_dword v0, v[12:13], off
	s_nop 0
	v_addc_co_u32_e32 v15, vcc, 0, v13, vcc
	global_load_dword v11, v[14:15], off
	v_add_co_u32_e32 v14, vcc, s13, v12
	s_movk_i32 s4, 0x6000
	s_nop 0
	v_addc_co_u32_e32 v15, vcc, 0, v13, vcc
	v_add_co_u32_e32 v16, vcc, s4, v12
	s_mov_b32 s4, 0x8000
	s_nop 0
	v_addc_co_u32_e32 v17, vcc, 0, v13, vcc
	global_load_dword v14, v[14:15], off
	s_nop 0
	global_load_dword v15, v[16:17], off
	v_add_co_u32_e32 v16, vcc, s4, v12
	s_mov_b32 s4, 0xa000
	s_nop 0
	v_addc_co_u32_e32 v17, vcc, 0, v13, vcc
	v_add_co_u32_e32 v18, vcc, s4, v12
	s_mov_b32 s4, 0xc000
	s_nop 0
	v_addc_co_u32_e32 v19, vcc, 0, v13, vcc
	global_load_dword v16, v[16:17], off
	s_nop 0
	global_load_dword v17, v[18:19], off
	v_add_co_u32_e32 v18, vcc, s4, v12
	s_mov_b32 s4, 0xe000
	s_nop 0
	v_addc_co_u32_e32 v19, vcc, 0, v13, vcc
	v_add_co_u32_e32 v20, vcc, s4, v12
	s_mov_b32 s4, 0x10000
	s_nop 0
	v_addc_co_u32_e32 v21, vcc, 0, v13, vcc
	global_load_dword v18, v[18:19], off
	s_nop 0
	global_load_dword v19, v[20:21], off
	v_add_co_u32_e32 v20, vcc, s4, v12
	s_mov_b32 s4, 0x12000
	s_nop 0
	v_addc_co_u32_e32 v21, vcc, 0, v13, vcc
	v_add_co_u32_e32 v22, vcc, s4, v12
	s_mov_b32 s4, 0x14000
	s_nop 0
	v_addc_co_u32_e32 v23, vcc, 0, v13, vcc
	global_load_dword v20, v[20:21], off
	s_nop 0
	global_load_dword v21, v[22:23], off
	v_add_co_u32_e32 v22, vcc, s4, v12
	s_mov_b32 s4, 0x1a000
	s_nop 0
	v_addc_co_u32_e32 v23, vcc, 0, v13, vcc
	v_add_co_u32_e32 v24, vcc, s14, v12
	global_load_dword v22, v[22:23], off
	s_nop 0
	v_addc_co_u32_e32 v25, vcc, 0, v13, vcc
	global_load_dword v23, v[24:25], off
	v_add_co_u32_e32 v24, vcc, s9, v12
	s_nop 1
	v_addc_co_u32_e32 v25, vcc, 0, v13, vcc
	v_add_co_u32_e32 v26, vcc, s4, v12
	s_mov_b32 s4, 0x1c000
	s_nop 0
	v_addc_co_u32_e32 v27, vcc, 0, v13, vcc
	global_load_dword v24, v[24:25], off
	s_nop 0
	global_load_dword v25, v[26:27], off
	v_add_co_u32_e32 v26, vcc, s4, v12
	s_mov_b32 s4, 0x1e000
	s_nop 0
	v_addc_co_u32_e32 v27, vcc, 0, v13, vcc
	v_add_co_u32_e32 v28, vcc, s4, v12
	s_mov_b32 s4, 0x20000
	s_nop 0
	v_addc_co_u32_e32 v29, vcc, 0, v13, vcc
	global_load_dword v26, v[26:27], off
	s_nop 0
	global_load_dword v27, v[28:29], off
	v_add_co_u32_e32 v28, vcc, s4, v12
	s_mov_b32 s4, 0x22000
	s_nop 0
	v_addc_co_u32_e32 v29, vcc, 0, v13, vcc
	v_add_co_u32_e32 v30, vcc, s4, v12
	s_mov_b32 s4, 0x24000
	s_nop 0
	v_addc_co_u32_e32 v31, vcc, 0, v13, vcc
	global_load_dword v28, v[28:29], off
	s_nop 0
	global_load_dword v29, v[30:31], off
	v_add_co_u32_e32 v30, vcc, s4, v12
	s_mov_b32 s4, 0x26000
	s_nop 0
	v_addc_co_u32_e32 v31, vcc, 0, v13, vcc
	v_add_co_u32_e32 v32, vcc, s4, v12
	s_mov_b32 s4, 0x28000
	s_nop 0
	v_addc_co_u32_e32 v33, vcc, 0, v13, vcc
	global_load_dword v30, v[30:31], off
	s_nop 0
	global_load_dword v31, v[32:33], off
	v_add_co_u32_e32 v32, vcc, s4, v12
	s_mov_b32 s4, 0x2a000
	s_nop 0
	v_addc_co_u32_e32 v33, vcc, 0, v13, vcc
	v_add_co_u32_e32 v34, vcc, s4, v12
	s_mov_b32 s4, 0x2c000
	s_nop 0
	v_addc_co_u32_e32 v35, vcc, 0, v13, vcc
	global_load_dword v32, v[32:33], off
	s_nop 0
	global_load_dword v33, v[34:35], off
	v_add_co_u32_e32 v34, vcc, s4, v12
	s_mov_b32 s4, 0x2e000
	s_nop 0
	v_addc_co_u32_e32 v35, vcc, 0, v13, vcc
	global_load_dword v36, v[34:35], off
	v_add_co_u32_e32 v34, vcc, s4, v12
	s_mov_b32 s4, 0x30000
	s_nop 0
	v_addc_co_u32_e32 v35, vcc, 0, v13, vcc
	global_load_dword v37, v[34:35], off
	v_add_co_u32_e32 v34, vcc, s4, v12
	s_mov_b32 s4, 0x32000
	s_nop 0
	v_addc_co_u32_e32 v35, vcc, 0, v13, vcc
	global_load_dword v38, v[34:35], off
	v_add_co_u32_e32 v34, vcc, s4, v12
	s_mov_b32 s4, 0x34000
	s_nop 0
	v_addc_co_u32_e32 v35, vcc, 0, v13, vcc
	global_load_dword v39, v[34:35], off
	v_add_co_u32_e32 v34, vcc, s4, v12
	s_mov_b32 s4, 0x36000
	s_nop 0
	v_addc_co_u32_e32 v35, vcc, 0, v13, vcc
	global_load_dword v40, v[34:35], off
	v_add_co_u32_e32 v34, vcc, s4, v12
	s_mov_b32 s4, 0x38000
	s_nop 0
	v_addc_co_u32_e32 v35, vcc, 0, v13, vcc
	global_load_dword v41, v[34:35], off
	v_add_co_u32_e32 v34, vcc, s4, v12
	s_mov_b32 s4, 0x3a000
	s_nop 0
	v_addc_co_u32_e32 v35, vcc, 0, v13, vcc
	global_load_dword v42, v[34:35], off
	v_add_co_u32_e32 v34, vcc, s4, v12
	s_mov_b32 s4, 0x3c000
	s_nop 0
	v_addc_co_u32_e32 v35, vcc, 0, v13, vcc
	global_load_dword v43, v[34:35], off
	v_add_co_u32_e32 v34, vcc, s4, v12
	s_mov_b32 s4, 0x3e000
	s_nop 0
	v_addc_co_u32_e32 v35, vcc, 0, v13, vcc
	global_load_dword v44, v[34:35], off
	v_add_co_u32_e32 v34, vcc, s4, v12
	s_mov_b32 s4, 0x40000
	s_nop 0
	v_addc_co_u32_e32 v35, vcc, 0, v13, vcc
	global_load_dword v45, v[34:35], off
	v_add_co_u32_e32 v34, vcc, s4, v12
	s_mov_b32 s4, 0x42000
	s_nop 0
	v_addc_co_u32_e32 v35, vcc, 0, v13, vcc
	global_load_dword v57, v[34:35], off
	v_add_co_u32_e32 v34, vcc, s4, v12
	s_mov_b32 s4, 0x44000
	s_nop 0
	v_addc_co_u32_e32 v35, vcc, 0, v13, vcc
	global_load_dword v58, v[34:35], off
	v_add_co_u32_e32 v34, vcc, s4, v12
	s_mov_b32 s4, 0x46000
	s_nop 0
	v_addc_co_u32_e32 v35, vcc, 0, v13, vcc
	global_load_dword v59, v[34:35], off
	v_add_co_u32_e32 v34, vcc, s4, v12
	s_mov_b32 s4, 0x48000
	s_nop 0
	v_addc_co_u32_e32 v35, vcc, 0, v13, vcc
	global_load_dword v60, v[34:35], off
	v_add_co_u32_e32 v34, vcc, s4, v12
	s_mov_b32 s4, 0x4a000
	s_nop 0
	v_addc_co_u32_e32 v35, vcc, 0, v13, vcc
	global_load_dword v61, v[34:35], off
	v_add_co_u32_e32 v34, vcc, s4, v12
	s_mov_b32 s4, 0x4c000
	s_nop 0
	v_addc_co_u32_e32 v35, vcc, 0, v13, vcc
	global_load_dword v62, v[34:35], off
	v_add_co_u32_e32 v34, vcc, s4, v12
	s_mov_b32 s4, 0x4e000
	s_nop 0
	v_addc_co_u32_e32 v35, vcc, 0, v13, vcc
	global_load_dword v63, v[34:35], off
	v_add_co_u32_e32 v34, vcc, s4, v12
	s_mov_b32 s4, 0x50000
	s_nop 0
	v_addc_co_u32_e32 v35, vcc, 0, v13, vcc
	global_load_dword v64, v[34:35], off
	v_add_co_u32_e32 v34, vcc, s4, v12
	s_mov_b32 s4, 0x52000
	s_nop 0
	v_addc_co_u32_e32 v35, vcc, 0, v13, vcc
	global_load_dword v65, v[34:35], off
	v_add_co_u32_e32 v34, vcc, s4, v12
	s_mov_b32 s4, 0x54000
	s_nop 0
	v_addc_co_u32_e32 v35, vcc, 0, v13, vcc
	global_load_dword v66, v[34:35], off
	v_add_co_u32_e32 v34, vcc, s4, v12
	s_mov_b32 s4, 0x56000
	s_nop 0
	v_addc_co_u32_e32 v35, vcc, 0, v13, vcc
	global_load_dword v67, v[34:35], off
	v_add_co_u32_e32 v34, vcc, s4, v12
	s_mov_b32 s4, 0x58000
	s_nop 0
	v_addc_co_u32_e32 v35, vcc, 0, v13, vcc
	global_load_dword v68, v[34:35], off
	v_add_co_u32_e32 v34, vcc, s4, v12
	s_mov_b32 s4, 0x5a000
	s_nop 0
	v_addc_co_u32_e32 v35, vcc, 0, v13, vcc
	global_load_dword v69, v[34:35], off
	v_add_co_u32_e32 v34, vcc, s4, v12
	s_mov_b32 s4, 0x5c000
	s_nop 0
	v_addc_co_u32_e32 v35, vcc, 0, v13, vcc
	global_load_dword v70, v[34:35], off
	v_add_co_u32_e32 v34, vcc, s4, v12
	s_mov_b32 s4, 0x5e000
	s_nop 0
	v_addc_co_u32_e32 v35, vcc, 0, v13, vcc
	global_load_dword v71, v[34:35], off
	v_add_co_u32_e32 v34, vcc, s4, v12
	s_mov_b32 s4, 0x60000
	s_nop 0
	v_addc_co_u32_e32 v35, vcc, 0, v13, vcc
	global_load_dword v72, v[34:35], off
	v_add_co_u32_e32 v34, vcc, s4, v12
	s_mov_b32 s4, 0x64000
	s_nop 0
	v_addc_co_u32_e32 v35, vcc, 0, v13, vcc
	global_load_dword v73, v[34:35], off
	v_add_co_u32_e32 v34, vcc, s21, v12
	s_nop 1
	v_addc_co_u32_e32 v35, vcc, 0, v13, vcc
	global_load_dword v74, v[34:35], off
	v_add_co_u32_e32 v34, vcc, s4, v12
	s_mov_b32 s4, 0x66000
	s_nop 0
	v_addc_co_u32_e32 v35, vcc, 0, v13, vcc
	global_load_dword v75, v[34:35], off
	v_add_co_u32_e32 v34, vcc, s4, v12
	s_mov_b32 s4, 0x68000
	s_nop 0
	v_addc_co_u32_e32 v35, vcc, 0, v13, vcc
	global_load_dword v76, v[34:35], off
	v_add_co_u32_e32 v34, vcc, s4, v12
	s_mov_b32 s4, 0x6a000
	s_nop 0
	v_addc_co_u32_e32 v35, vcc, 0, v13, vcc
	global_load_dword v77, v[34:35], off
	v_add_co_u32_e32 v34, vcc, s4, v12
	s_mov_b32 s4, 0x6c000
	s_nop 0
	v_addc_co_u32_e32 v35, vcc, 0, v13, vcc
	global_load_dword v78, v[34:35], off
	v_add_co_u32_e32 v34, vcc, s4, v12
	s_mov_b32 s4, 0x70000
	s_nop 0
	v_addc_co_u32_e32 v35, vcc, 0, v13, vcc
	global_load_dword v79, v[34:35], off
	v_add_co_u32_e32 v34, vcc, s16, v12
	s_nop 1
	v_addc_co_u32_e32 v35, vcc, 0, v13, vcc
	global_load_dword v80, v[34:35], off
	v_add_co_u32_e32 v34, vcc, s4, v12
	s_mov_b32 s4, 0x72000
	s_nop 0
	v_addc_co_u32_e32 v35, vcc, 0, v13, vcc
	global_load_dword v81, v[34:35], off
	v_add_co_u32_e32 v34, vcc, s4, v12
	s_mov_b32 s4, 0x74000
	s_nop 0
	v_addc_co_u32_e32 v35, vcc, 0, v13, vcc
	global_load_dword v82, v[34:35], off
	v_add_co_u32_e32 v34, vcc, s4, v12
	s_mov_b32 s4, 0x76000
	s_nop 0
	v_addc_co_u32_e32 v35, vcc, 0, v13, vcc
	global_load_dword v83, v[34:35], off
	v_add_co_u32_e32 v34, vcc, s4, v12
	s_mov_b32 s4, 0x78000
	s_nop 0
	v_addc_co_u32_e32 v35, vcc, 0, v13, vcc
	global_load_dword v84, v[34:35], off
	v_add_co_u32_e32 v34, vcc, s4, v12
	s_mov_b32 s4, 0x7c000
	s_nop 0
	v_addc_co_u32_e32 v35, vcc, 0, v13, vcc
	global_load_dword v85, v[34:35], off
	v_add_co_u32_e32 v34, vcc, s89, v12
	s_nop 1
	v_addc_co_u32_e32 v35, vcc, 0, v13, vcc
	global_load_dword v86, v[34:35], off
	v_add_co_u32_e32 v34, vcc, s4, v12
	s_mov_b32 s4, 0x7e000
	s_nop 0
	v_addc_co_u32_e32 v35, vcc, 0, v13, vcc
	v_add_co_u32_e32 v12, vcc, s4, v12
	global_load_dword v34, v[34:35], off
	s_nop 0
	v_addc_co_u32_e32 v13, vcc, 0, v13, vcc
	global_load_dword v12, v[12:13], off
	s_waitcnt vmcnt(0)
	ds_write2_b32 v47, v0, v11 offset1:65
	ds_write2_b32 v47, v14, v15 offset0:130 offset1:195
	v_add_u32_e32 v0, 0x400, v47
	ds_write2_b32 v0, v16, v17 offset0:4 offset1:69
	ds_write2_b32 v0, v18, v19 offset0:134 offset1:199
	v_add_u32_e32 v0, 0x800, v47
	ds_write2_b32 v0, v20, v21 offset0:8 offset1:73
	ds_write2_b32 v0, v22, v23 offset0:138 offset1:203
	v_add_u32_e32 v0, 0xc00, v47
	ds_write2_b32 v0, v24, v25 offset0:12 offset1:77
	ds_write2_b32 v0, v26, v27 offset0:142 offset1:207
	v_add_u32_e32 v0, 0x1000, v47
	ds_write2_b32 v0, v28, v29 offset0:16 offset1:81
	ds_write2_b32 v0, v30, v31 offset0:146 offset1:211
	v_add_u32_e32 v0, 0x1400, v47
	ds_write2_b32 v0, v32, v33 offset0:20 offset1:85
	ds_write2_b32 v0, v36, v37 offset0:150 offset1:215
	v_add_u32_e32 v0, 0x1800, v47
	ds_write2_b32 v0, v38, v39 offset0:24 offset1:89
	ds_write2_b32 v0, v40, v41 offset0:154 offset1:219
	v_add_u32_e32 v0, 0x1c00, v47
	ds_write2_b32 v0, v42, v43 offset0:28 offset1:93
	ds_write2_b32 v0, v44, v45 offset0:158 offset1:223
	v_add_u32_e32 v0, 0x2000, v47
	ds_write2_b32 v0, v57, v58 offset0:32 offset1:97
	ds_write2_b32 v0, v59, v60 offset0:162 offset1:227
	v_add_u32_e32 v0, 0x2400, v47
	ds_write2_b32 v0, v61, v62 offset0:36 offset1:101
	ds_write2_b32 v0, v63, v64 offset0:166 offset1:231
	v_add_u32_e32 v0, 0x2800, v47
	ds_write2_b32 v0, v65, v66 offset0:40 offset1:105
	ds_write2_b32 v0, v67, v68 offset0:170 offset1:235
	v_add_u32_e32 v0, 0x2c00, v47
	ds_write2_b32 v0, v69, v70 offset0:44 offset1:109
	ds_write2_b32 v0, v71, v72 offset0:174 offset1:239
	v_add_u32_e32 v0, 0x3000, v47
	ds_write2_b32 v0, v73, v74 offset0:48 offset1:113
	ds_write2_b32 v0, v75, v76 offset0:178 offset1:243
	v_add_u32_e32 v0, 0x3400, v47
	ds_write2_b32 v0, v77, v78 offset0:52 offset1:117
	ds_write2_b32 v0, v79, v80 offset0:182 offset1:247
	v_add_u32_e32 v0, 0x3800, v47
	s_lshl_b32 s4, s90, 10
	ds_write2_b32 v0, v81, v82 offset0:56 offset1:121
	ds_write2_b32 v0, v83, v84 offset0:186 offset1:251
	v_add_u32_e32 v0, 0x3c00, v47
	s_add_u32 s4, s38, s4
	ds_write2_b32 v0, v85, v86 offset0:60 offset1:125
	ds_write2_b32 v0, v34, v12 offset0:190 offset1:255
	s_addc_u32 s5, s39, 0
	s_lshl_b32 s1, s1, 1
	s_waitcnt lgkmcnt(0)
	s_add_u32 s4, s4, s1
	s_addc_u32 s5, s5, 0
	v_mov_b32_e32 v11, v1
	v_lshl_add_u64 v[12:13], s[4:5], 0, v[10:11]
	ds_read_b32 v0, v49
	ds_read_b32 v11, v49 offset:260
	s_waitcnt lgkmcnt(0)
	v_cvt_pk_bf16_f32 v14, v0, v11
	ds_read_b32 v0, v49 offset:520
	ds_read_b32 v11, v49 offset:780
	s_waitcnt lgkmcnt(1)
	s_waitcnt lgkmcnt(0)
	v_cvt_pk_bf16_f32 v15, v0, v11
	ds_read_b32 v0, v49 offset:1040
	ds_read_b32 v11, v49 offset:1300
	s_waitcnt lgkmcnt(1)
	s_waitcnt lgkmcnt(0)
	v_cvt_pk_bf16_f32 v16, v0, v11
	ds_read_b32 v0, v49 offset:1560
	ds_read_b32 v11, v49 offset:1820
	s_waitcnt lgkmcnt(1)
	s_waitcnt lgkmcnt(0)
	v_cvt_pk_bf16_f32 v17, v0, v11
	v_or_b32_e32 v0, s0, v48
	v_lshlrev_b32_e32 v0, 12, v0
	v_lshl_add_u64 v[18:19], v[12:13], 0, v[0:1]
	flat_store_dwordx4 v[18:19], v[14:17]
	ds_read_b32 v0, v49 offset:32
	ds_read_b32 v11, v49 offset:292
	s_waitcnt lgkmcnt(0)
	v_cvt_pk_bf16_f32 v14, v0, v11
	ds_read_b32 v0, v49 offset:552
	ds_read_b32 v11, v49 offset:812
	s_waitcnt lgkmcnt(0)
	v_cvt_pk_bf16_f32 v15, v0, v11
	ds_read_b32 v0, v49 offset:1072
	ds_read_b32 v11, v49 offset:1332
	s_waitcnt lgkmcnt(0)
	v_cvt_pk_bf16_f32 v16, v0, v11
	ds_read_b32 v0, v49 offset:1592
	ds_read_b32 v11, v49 offset:1852
	s_waitcnt lgkmcnt(0)
	v_cvt_pk_bf16_f32 v17, v0, v11
	v_or_b32_e32 v0, s0, v50
	v_lshlrev_b32_e32 v0, 12, v0
	v_lshl_add_u64 v[18:19], v[12:13], 0, v[0:1]
	flat_store_dwordx4 v[18:19], v[14:17]
	ds_read_b32 v0, v49 offset:64
	ds_read_b32 v11, v49 offset:324
	s_waitcnt lgkmcnt(0)
	v_cvt_pk_bf16_f32 v14, v0, v11
	ds_read_b32 v0, v49 offset:584
	ds_read_b32 v11, v49 offset:844
	s_waitcnt lgkmcnt(0)
	v_cvt_pk_bf16_f32 v15, v0, v11
	ds_read_b32 v0, v49 offset:1104
	ds_read_b32 v11, v49 offset:1364
	s_waitcnt lgkmcnt(0)
	v_cvt_pk_bf16_f32 v16, v0, v11
	ds_read_b32 v0, v49 offset:1624
	ds_read_b32 v11, v49 offset:1884
	s_waitcnt lgkmcnt(0)
	v_cvt_pk_bf16_f32 v17, v0, v11
	v_or_b32_e32 v0, s0, v51
	v_lshlrev_b32_e32 v0, 12, v0
	v_lshl_add_u64 v[18:19], v[12:13], 0, v[0:1]
	flat_store_dwordx4 v[18:19], v[14:17]
	ds_read_b32 v0, v49 offset:96
	ds_read_b32 v11, v49 offset:356
	s_waitcnt lgkmcnt(0)
	v_cvt_pk_bf16_f32 v14, v0, v11
	ds_read_b32 v0, v49 offset:616
	ds_read_b32 v11, v49 offset:876
	s_waitcnt lgkmcnt(0)
	v_cvt_pk_bf16_f32 v15, v0, v11
	ds_read_b32 v0, v49 offset:1136
	ds_read_b32 v11, v49 offset:1396
	s_waitcnt lgkmcnt(0)
	v_cvt_pk_bf16_f32 v16, v0, v11
	ds_read_b32 v0, v49 offset:1656
	ds_read_b32 v11, v49 offset:1916
	s_waitcnt lgkmcnt(0)
	v_cvt_pk_bf16_f32 v17, v0, v11
	v_or_b32_e32 v0, s0, v52
	v_lshlrev_b32_e32 v0, 12, v0
	v_lshl_add_u64 v[18:19], v[12:13], 0, v[0:1]
	flat_store_dwordx4 v[18:19], v[14:17]
	ds_read_b32 v0, v49 offset:128
	ds_read_b32 v11, v49 offset:388
	s_waitcnt lgkmcnt(0)
	v_cvt_pk_bf16_f32 v14, v0, v11
	ds_read_b32 v0, v49 offset:648
	ds_read_b32 v11, v49 offset:908
	s_waitcnt lgkmcnt(0)
	v_cvt_pk_bf16_f32 v15, v0, v11
	ds_read_b32 v0, v49 offset:1168
	ds_read_b32 v11, v49 offset:1428
	s_waitcnt lgkmcnt(0)
	v_cvt_pk_bf16_f32 v16, v0, v11
	ds_read_b32 v0, v49 offset:1688
	ds_read_b32 v11, v49 offset:1948
	s_waitcnt lgkmcnt(0)
	v_cvt_pk_bf16_f32 v17, v0, v11
	v_or_b32_e32 v0, s0, v53
	v_lshlrev_b32_e32 v0, 12, v0
	v_lshl_add_u64 v[18:19], v[12:13], 0, v[0:1]
	flat_store_dwordx4 v[18:19], v[14:17]
	ds_read_b32 v0, v49 offset:160
	ds_read_b32 v11, v49 offset:420
	s_waitcnt lgkmcnt(0)
	v_cvt_pk_bf16_f32 v14, v0, v11
	ds_read_b32 v0, v49 offset:680
	ds_read_b32 v11, v49 offset:940
	s_waitcnt lgkmcnt(0)
	v_cvt_pk_bf16_f32 v15, v0, v11
	ds_read_b32 v0, v49 offset:1200
	ds_read_b32 v11, v49 offset:1460
	s_waitcnt lgkmcnt(0)
	v_cvt_pk_bf16_f32 v16, v0, v11
	ds_read_b32 v0, v49 offset:1720
	ds_read_b32 v11, v49 offset:1980
	s_waitcnt lgkmcnt(0)
	v_cvt_pk_bf16_f32 v17, v0, v11
	v_or_b32_e32 v0, s0, v54
	v_lshlrev_b32_e32 v0, 12, v0
	v_lshl_add_u64 v[18:19], v[12:13], 0, v[0:1]
	flat_store_dwordx4 v[18:19], v[14:17]
	ds_read_b32 v0, v49 offset:192
	ds_read_b32 v11, v49 offset:452
	s_waitcnt lgkmcnt(0)
	v_cvt_pk_bf16_f32 v14, v0, v11
	ds_read_b32 v0, v49 offset:712
	ds_read_b32 v11, v49 offset:972
	s_waitcnt lgkmcnt(0)
	v_cvt_pk_bf16_f32 v15, v0, v11
	ds_read_b32 v0, v49 offset:1232
	ds_read_b32 v11, v49 offset:1492
	s_waitcnt lgkmcnt(0)
	v_cvt_pk_bf16_f32 v16, v0, v11
	ds_read_b32 v0, v49 offset:1752
	ds_read_b32 v11, v49 offset:2012
	s_waitcnt lgkmcnt(0)
	v_cvt_pk_bf16_f32 v17, v0, v11
	v_or_b32_e32 v0, s0, v55
	v_lshlrev_b32_e32 v0, 12, v0
	v_lshl_add_u64 v[18:19], v[12:13], 0, v[0:1]
	flat_store_dwordx4 v[18:19], v[14:17]
	ds_read_b32 v0, v49 offset:224
	ds_read_b32 v11, v49 offset:484
	s_waitcnt lgkmcnt(0)
	v_cvt_pk_bf16_f32 v14, v0, v11
	ds_read_b32 v0, v49 offset:744
	ds_read_b32 v11, v49 offset:1004
	s_waitcnt lgkmcnt(0)
	v_cvt_pk_bf16_f32 v15, v0, v11
	ds_read_b32 v0, v49 offset:1264
	ds_read_b32 v11, v49 offset:1524
	s_waitcnt lgkmcnt(0)
	v_cvt_pk_bf16_f32 v16, v0, v11
	ds_read_b32 v0, v49 offset:1784
	ds_read_b32 v11, v49 offset:2044
	s_waitcnt lgkmcnt(0)
	v_cvt_pk_bf16_f32 v17, v0, v11
	v_or_b32_e32 v0, s0, v56
	v_lshlrev_b32_e32 v0, 12, v0
	v_lshl_add_u64 v[12:13], v[12:13], 0, v[0:1]
	flat_store_dwordx4 v[12:13], v[14:17]
	s_waitcnt lgkmcnt(0)
